# hand-scheduled deltanet scan (batched LDS reads), batched FF1 epilogue loads, three branch GEMMs fused in the accumulators (gate-ratio rescale between them, no f32 scratch round trip)
# speedup vs baseline: 1.0448x; 1.0448x over previous
.LBB0_652:
	s_andn2_b64 vcc, exec, s[0:1]
	s_cbranch_vccnz .LBB0_704
	v_and_b32_e32 v14, 63, v206
	v_lshrrev_b32_e32 v15, 6, v206
	v_and_b32_e32 v64, 15, v14
	v_readfirstlane_b32 s11, v15
	v_lshrrev_b32_e32 v65, 4, v14
	v_lshlrev_b32_e32 v66, 2, v206
	ds_write_b32 v66, v0
	ds_write_b32 v66, v0 offset:2048
	ds_write_b32 v66, v0 offset:4096
	ds_write_b32 v66, v0 offset:6144
	ds_write_b32 v66, v0 offset:8192
	s_and_b32 s12, s11, 3
	s_and_b32 s13, s72, 7
	s_lshr_b32 s14, s72, 5
	s_bfe_u32 s15, s72, 0x20003
	s_lshl_b32 s16, s14, 3
	s_add_u32 s16, s16, s13
	s_lshl_b32 s17, s16, 21
	s_mov_b32 s18, 0x13800000
	s_cmp_lt_u32 s11, 4
	s_cselect_b32 s18, 0x11800000, s18
	s_add_u32 s18, s18, s17
	s_lshl_b32 s19, s12, 12
	s_add_u32 s18, s18, s19
	s_add_u32 s0, s70, s18
	s_addc_u32 s1, s71, 0
	s_lshl_b32 s19, s11, 11
	s_add_u32 s18, s17, s19
	s_add_u32 s18, s18, 0x15800000
	s_add_u32 s4, s70, s18
	s_addc_u32 s5, s71, 0
	s_lshl_b32 s18, s16, 9
	s_add_u32 s18, s18, 0x11500000
	s_add_u32 s6, s70, s18
	s_addc_u32 s7, s71, 0
	s_lshl_b32 s18, s15, 12
	s_lshl_b32 s19, s12, 9
	s_add_u32 s18, s18, s19
	s_add_u32 s18, s18, s17
	s_add_u32 s18, s18, 0x17800000
	s_lshl_b32 s19, s16, 20
	s_lshl_b32 s20, s12, 11
	s_add_u32 s19, s19, s20
	s_add_u32 s19, s19, 0x19800000
	s_cmp_lt_u32 s11, 4
	s_cselect_b32 s18, s18, s19
	s_add_u32 s2, s70, s18
	s_addc_u32 s3, s71, 0
	s_lshl_b32 s18, s14, 24
	s_lshl_b32 s19, s12, 15
	s_add_u32 s18, s18, s19
	s_lshl_b32 s19, s13, 8
	s_add_u32 s18, s18, s19
	s_lshl_b32 s19, s15, 6
	s_add_u32 s18, s18, s19
	s_add_u32 s18, s18, 0xb400000
	s_add_u32 s8, s70, s18
	s_addc_u32 s9, s71, 0
	v_lshlrev_b32_e32 v1, 4, v14
	v_mov_b32_e32 v3, 0
	v_mul_u32_u24_e32 v8, 0x110, v64
	v_mul_u32_u24_e32 v9, 0x90, v64
	v_lshl_add_u32 v11, v65, 3, v8
	v_lshl_add_u32 v10, v65, 3, v9
	v_lshl_add_u32 v8, v65, 4, v8
	v_lshl_add_u32 v9, v65, 4, v9
	s_lshl_b32 s18, s11, 5
	v_add_u32_e32 v11, s18, v11
	s_lshl_b32 s18, s12, 5
	v_add_u32_e32 v10, s18, v10
	v_lshlrev_b32_e32 v12, 13, v65
	v_lshl_add_u32 v12, v64, 1, v12
	v_add_u32_e32 v13, 0x1000, v12
	v_mov_b32_e32 v16, 0
	v_mov_b32_e32 v17, 0
	v_mov_b32_e32 v18, 0
	v_mov_b32_e32 v19, 0
	v_mov_b32_e32 v20, 0
	v_mov_b32_e32 v21, 0
	v_mov_b32_e32 v22, 0
	v_mov_b32_e32 v23, 0
	s_cmp_lt_u32 s11, 4
	s_waitcnt lgkmcnt(0)
	s_barrier
	s_cbranch_scc0 .Lscan_O_path
	v_lshlrev_b32_e32 v2, 3, v14
	global_load_dwordx4 v[72:75], v1, s[0:1]
	global_load_dwordx4 v[76:79], v1, s[0:1] offset:1024
	global_load_dwordx4 v[80:83], v1, s[0:1] offset:2048
	global_load_dwordx4 v[84:87], v1, s[0:1] offset:3072
	global_load_dwordx2 v[88:89], v2, s[2:3]
	global_load_dwordx2 v[90:91], v2, s[2:3] offset:2048
	global_load_dwordx4 v[96:99], v1, s[4:5]
	global_load_dwordx4 v[100:103], v1, s[4:5] offset:1024
	global_load_dword v184, v3, s[6:7]
	v_add_u32_e32 v1, 0x4000, v1
	v_add_u32_e32 v2, 0x4000, v2
	v_add_u32_e32 v3, 4, v3
	global_load_dwordx4 v[104:107], v1, s[0:1]
	global_load_dwordx4 v[108:111], v1, s[0:1] offset:1024
	global_load_dwordx4 v[112:115], v1, s[0:1] offset:2048
	global_load_dwordx4 v[116:119], v1, s[0:1] offset:3072
	global_load_dwordx2 v[120:121], v2, s[2:3]
	global_load_dwordx2 v[122:123], v2, s[2:3] offset:2048
	global_load_dwordx4 v[128:131], v1, s[4:5]
	global_load_dwordx4 v[132:135], v1, s[4:5] offset:1024
	global_load_dword v185, v3, s[6:7]
	v_add_u32_e32 v1, 0x4000, v1
	v_add_u32_e32 v2, 0x4000, v2
	v_add_u32_e32 v3, 4, v3
	global_load_dwordx4 v[136:139], v1, s[0:1]
	global_load_dwordx4 v[140:143], v1, s[0:1] offset:1024
	global_load_dwordx4 v[144:147], v1, s[0:1] offset:2048
	global_load_dwordx4 v[148:151], v1, s[0:1] offset:3072
	global_load_dwordx2 v[188:189], v2, s[2:3]
	global_load_dwordx2 v[190:191], v2, s[2:3] offset:2048
	global_load_dwordx4 v[196:199], v1, s[4:5]
	global_load_dwordx4 v[200:203], v1, s[4:5] offset:1024
	global_load_dword v186, v3, s[6:7]
	v_add_u32_e32 v1, 0x4000, v1
	v_add_u32_e32 v2, 0x4000, v2
	v_add_u32_e32 v3, 4, v3
	s_waitcnt vmcnt(0)
	s_movk_i32 s10, 32
.Lscan_V_loop:
	s_waitcnt vmcnt(23)
	ds_read_b128 v[32:35], v8 offset:0
	ds_read_b128 v[36:39], v8 offset:4352
	ds_read_b128 v[40:43], v8 offset:64
	ds_read_b128 v[44:47], v8 offset:4416
	ds_read_b128 v[48:51], v8 offset:128
	ds_read_b128 v[52:55], v8 offset:4480
	ds_read_b128 v[56:59], v8 offset:192
	ds_read_b128 v[60:63], v8 offset:4544
	global_load_dwordx4 v[216:219], v1, s[0:1]
	global_load_dwordx4 v[220:223], v1, s[0:1] offset:1024
	global_load_dwordx4 v[224:227], v1, s[0:1] offset:2048
	global_load_dwordx4 v[228:231], v1, s[0:1] offset:3072
	global_load_dwordx2 v[232:233], v2, s[2:3]
	global_load_dwordx2 v[234:235], v2, s[2:3] offset:2048
	global_load_dwordx4 v[240:243], v1, s[4:5]
	global_load_dwordx4 v[244:247], v1, s[4:5] offset:1024
	global_load_dword v187, v3, s[6:7]
	v_add_u32_e32 v1, 0x4000, v1
	v_add_u32_e32 v2, 0x4000, v2
	v_add_u32_e32 v3, 4, v3
	s_waitcnt vmcnt(27)
	v_mul_f32_e32 v16, v184, v16
	v_mul_f32_e32 v17, v184, v17
	v_mul_f32_e32 v18, v184, v18
	v_mul_f32_e32 v19, v184, v19
	v_mul_f32_e32 v20, v184, v20
	v_mul_f32_e32 v21, v184, v21
	v_mul_f32_e32 v22, v184, v22
	v_mul_f32_e32 v23, v184, v23
	v_lshlrev_b32_e32 v64, 16, v88
	v_and_b32_e32 v65, 0xffff0000, v88
	v_lshlrev_b32_e32 v66, 16, v89
	v_and_b32_e32 v67, 0xffff0000, v89
	v_lshlrev_b32_e32 v68, 16, v90
	v_and_b32_e32 v69, 0xffff0000, v90
	v_lshlrev_b32_e32 v70, 16, v91
	v_and_b32_e32 v71, 0xffff0000, v91
	s_waitcnt lgkmcnt(6)
	v_mfma_f32_16x16x32_bf16 v[24:27], v[72:75], v[32:35], 0
	v_mfma_f32_16x16x32_bf16 v[28:31], v[72:75], v[36:39], 0
	s_waitcnt lgkmcnt(4)
	v_mfma_f32_16x16x32_bf16 v[24:27], v[76:79], v[40:43], v[24:27]
	v_mfma_f32_16x16x32_bf16 v[28:31], v[76:79], v[44:47], v[28:31]
	s_waitcnt lgkmcnt(2)
	v_mfma_f32_16x16x32_bf16 v[24:27], v[80:83], v[48:51], v[24:27]
	v_mfma_f32_16x16x32_bf16 v[28:31], v[80:83], v[52:55], v[28:31]
	s_waitcnt lgkmcnt(0)
	v_mfma_f32_16x16x32_bf16 v[24:27], v[84:87], v[56:59], v[24:27]
	v_mfma_f32_16x16x32_bf16 v[28:31], v[84:87], v[60:63], v[28:31]
	s_nop 7
	v_sub_f32_e32 v64, v64, v24
	v_sub_f32_e32 v65, v65, v25
	v_sub_f32_e32 v66, v66, v26
	v_sub_f32_e32 v67, v67, v27
	v_sub_f32_e32 v68, v68, v28
	v_sub_f32_e32 v69, v69, v29
	v_sub_f32_e32 v70, v70, v30
	v_sub_f32_e32 v71, v71, v31
	v_cvt_pk_bf16_f32 v64, v64, v65
	v_cvt_pk_bf16_f32 v65, v66, v67
	v_cvt_pk_bf16_f32 v68, v68, v69
	v_cvt_pk_bf16_f32 v69, v70, v71
	ds_write_b64 v10, v[64:65] offset:17408
	ds_write_b64 v10, v[68:69] offset:19712
	s_waitcnt lgkmcnt(0)
	s_barrier
	ds_read_b128 v[32:35], v9 offset:17408
	ds_read_b128 v[36:39], v9 offset:19712
	ds_read_b128 v[40:43], v9 offset:17472
	ds_read_b128 v[44:47], v9 offset:19776
	s_waitcnt lgkmcnt(2)
	v_mfma_f32_16x16x32_bf16 v[16:19], v[96:99], v[32:35], v[16:19]
	v_mfma_f32_16x16x32_bf16 v[20:23], v[96:99], v[36:39], v[20:23]
	s_waitcnt lgkmcnt(0)
	v_mfma_f32_16x16x32_bf16 v[16:19], v[100:103], v[40:43], v[16:19]
	v_mfma_f32_16x16x32_bf16 v[20:23], v[100:103], v[44:47], v[20:23]
	s_nop 7
	v_cvt_pk_bf16_f32 v64, v16, v17
	v_cvt_pk_bf16_f32 v65, v18, v19
	v_cvt_pk_bf16_f32 v66, v20, v21
	v_cvt_pk_bf16_f32 v67, v22, v23
	ds_write_b64 v11, v[64:65] offset:8704
	ds_write_b64 v11, v[66:67] offset:13056
	s_waitcnt lgkmcnt(0)
	s_barrier
	s_waitcnt vmcnt(23)
	ds_read_b128 v[32:35], v8 offset:8704
	ds_read_b128 v[36:39], v8 offset:13056
	ds_read_b128 v[40:43], v8 offset:8768
	ds_read_b128 v[44:47], v8 offset:13120
	ds_read_b128 v[48:51], v8 offset:8832
	ds_read_b128 v[52:55], v8 offset:13184
	ds_read_b128 v[56:59], v8 offset:8896
	ds_read_b128 v[60:63], v8 offset:13248
	global_load_dwordx4 v[72:75], v1, s[0:1]
	global_load_dwordx4 v[76:79], v1, s[0:1] offset:1024
	global_load_dwordx4 v[80:83], v1, s[0:1] offset:2048
	global_load_dwordx4 v[84:87], v1, s[0:1] offset:3072
	global_load_dwordx2 v[88:89], v2, s[2:3]
	global_load_dwordx2 v[90:91], v2, s[2:3] offset:2048
	global_load_dwordx4 v[96:99], v1, s[4:5]
	global_load_dwordx4 v[100:103], v1, s[4:5] offset:1024
	global_load_dword v184, v3, s[6:7]
	v_add_u32_e32 v1, 0x4000, v1
	v_add_u32_e32 v2, 0x4000, v2
	v_add_u32_e32 v3, 4, v3
	s_waitcnt vmcnt(27)
	v_mul_f32_e32 v16, v185, v16
	v_mul_f32_e32 v17, v185, v17
	v_mul_f32_e32 v18, v185, v18
	v_mul_f32_e32 v19, v185, v19
	v_mul_f32_e32 v20, v185, v20
	v_mul_f32_e32 v21, v185, v21
	v_mul_f32_e32 v22, v185, v22
	v_mul_f32_e32 v23, v185, v23
	v_lshlrev_b32_e32 v64, 16, v120
	v_and_b32_e32 v65, 0xffff0000, v120
	v_lshlrev_b32_e32 v66, 16, v121
	v_and_b32_e32 v67, 0xffff0000, v121
	v_lshlrev_b32_e32 v68, 16, v122
	v_and_b32_e32 v69, 0xffff0000, v122
	v_lshlrev_b32_e32 v70, 16, v123
	v_and_b32_e32 v71, 0xffff0000, v123
	s_waitcnt lgkmcnt(6)
	v_mfma_f32_16x16x32_bf16 v[24:27], v[104:107], v[32:35], 0
	v_mfma_f32_16x16x32_bf16 v[28:31], v[104:107], v[36:39], 0
	s_waitcnt lgkmcnt(4)
	v_mfma_f32_16x16x32_bf16 v[24:27], v[108:111], v[40:43], v[24:27]
	v_mfma_f32_16x16x32_bf16 v[28:31], v[108:111], v[44:47], v[28:31]
	s_waitcnt lgkmcnt(2)
	v_mfma_f32_16x16x32_bf16 v[24:27], v[112:115], v[48:51], v[24:27]
	v_mfma_f32_16x16x32_bf16 v[28:31], v[112:115], v[52:55], v[28:31]
	s_waitcnt lgkmcnt(0)
	v_mfma_f32_16x16x32_bf16 v[24:27], v[116:119], v[56:59], v[24:27]
	v_mfma_f32_16x16x32_bf16 v[28:31], v[116:119], v[60:63], v[28:31]
	s_nop 7
	v_sub_f32_e32 v64, v64, v24
	v_sub_f32_e32 v65, v65, v25
	v_sub_f32_e32 v66, v66, v26
	v_sub_f32_e32 v67, v67, v27
	v_sub_f32_e32 v68, v68, v28
	v_sub_f32_e32 v69, v69, v29
	v_sub_f32_e32 v70, v70, v30
	v_sub_f32_e32 v71, v71, v31
	v_cvt_pk_bf16_f32 v64, v64, v65
	v_cvt_pk_bf16_f32 v65, v66, v67
	v_cvt_pk_bf16_f32 v68, v68, v69
	v_cvt_pk_bf16_f32 v69, v70, v71
	ds_write_b64 v10, v[64:65] offset:17408
	ds_write_b64 v10, v[68:69] offset:19712
	s_waitcnt lgkmcnt(0)
	s_barrier
	ds_read_b128 v[32:35], v9 offset:17408
	ds_read_b128 v[36:39], v9 offset:19712
	ds_read_b128 v[40:43], v9 offset:17472
	ds_read_b128 v[44:47], v9 offset:19776
	s_waitcnt lgkmcnt(2)
	v_mfma_f32_16x16x32_bf16 v[16:19], v[128:131], v[32:35], v[16:19]
	v_mfma_f32_16x16x32_bf16 v[20:23], v[128:131], v[36:39], v[20:23]
	s_waitcnt lgkmcnt(0)
	v_mfma_f32_16x16x32_bf16 v[16:19], v[132:135], v[40:43], v[16:19]
	v_mfma_f32_16x16x32_bf16 v[20:23], v[132:135], v[44:47], v[20:23]
	s_nop 7
	v_cvt_pk_bf16_f32 v64, v16, v17
	v_cvt_pk_bf16_f32 v65, v18, v19
	v_cvt_pk_bf16_f32 v66, v20, v21
	v_cvt_pk_bf16_f32 v67, v22, v23
	ds_write_b64 v11, v[64:65] offset:0
	ds_write_b64 v11, v[66:67] offset:4352
	s_waitcnt lgkmcnt(0)
	s_barrier
	s_waitcnt vmcnt(23)
	ds_read_b128 v[32:35], v8 offset:0
	ds_read_b128 v[36:39], v8 offset:4352
	ds_read_b128 v[40:43], v8 offset:64
	ds_read_b128 v[44:47], v8 offset:4416
	ds_read_b128 v[48:51], v8 offset:128
	ds_read_b128 v[52:55], v8 offset:4480
	ds_read_b128 v[56:59], v8 offset:192
	ds_read_b128 v[60:63], v8 offset:4544
	global_load_dwordx4 v[104:107], v1, s[0:1]
	global_load_dwordx4 v[108:111], v1, s[0:1] offset:1024
	global_load_dwordx4 v[112:115], v1, s[0:1] offset:2048
	global_load_dwordx4 v[116:119], v1, s[0:1] offset:3072
	global_load_dwordx2 v[120:121], v2, s[2:3]
	global_load_dwordx2 v[122:123], v2, s[2:3] offset:2048
	global_load_dwordx4 v[128:131], v1, s[4:5]
	global_load_dwordx4 v[132:135], v1, s[4:5] offset:1024
	global_load_dword v185, v3, s[6:7]
	v_add_u32_e32 v1, 0x4000, v1
	v_add_u32_e32 v2, 0x4000, v2
	v_add_u32_e32 v3, 4, v3
	s_waitcnt vmcnt(27)
	v_mul_f32_e32 v16, v186, v16
	v_mul_f32_e32 v17, v186, v17
	v_mul_f32_e32 v18, v186, v18
	v_mul_f32_e32 v19, v186, v19
	v_mul_f32_e32 v20, v186, v20
	v_mul_f32_e32 v21, v186, v21
	v_mul_f32_e32 v22, v186, v22
	v_mul_f32_e32 v23, v186, v23
	v_lshlrev_b32_e32 v64, 16, v188
	v_and_b32_e32 v65, 0xffff0000, v188
	v_lshlrev_b32_e32 v66, 16, v189
	v_and_b32_e32 v67, 0xffff0000, v189
	v_lshlrev_b32_e32 v68, 16, v190
	v_and_b32_e32 v69, 0xffff0000, v190
	v_lshlrev_b32_e32 v70, 16, v191
	v_and_b32_e32 v71, 0xffff0000, v191
	s_waitcnt lgkmcnt(6)
	v_mfma_f32_16x16x32_bf16 v[24:27], v[136:139], v[32:35], 0
	v_mfma_f32_16x16x32_bf16 v[28:31], v[136:139], v[36:39], 0
	s_waitcnt lgkmcnt(4)
	v_mfma_f32_16x16x32_bf16 v[24:27], v[140:143], v[40:43], v[24:27]
	v_mfma_f32_16x16x32_bf16 v[28:31], v[140:143], v[44:47], v[28:31]
	s_waitcnt lgkmcnt(2)
	v_mfma_f32_16x16x32_bf16 v[24:27], v[144:147], v[48:51], v[24:27]
	v_mfma_f32_16x16x32_bf16 v[28:31], v[144:147], v[52:55], v[28:31]
	s_waitcnt lgkmcnt(0)
	v_mfma_f32_16x16x32_bf16 v[24:27], v[148:151], v[56:59], v[24:27]
	v_mfma_f32_16x16x32_bf16 v[28:31], v[148:151], v[60:63], v[28:31]
	s_nop 7
	v_sub_f32_e32 v64, v64, v24
	v_sub_f32_e32 v65, v65, v25
	v_sub_f32_e32 v66, v66, v26
	v_sub_f32_e32 v67, v67, v27
	v_sub_f32_e32 v68, v68, v28
	v_sub_f32_e32 v69, v69, v29
	v_sub_f32_e32 v70, v70, v30
	v_sub_f32_e32 v71, v71, v31
	v_cvt_pk_bf16_f32 v64, v64, v65
	v_cvt_pk_bf16_f32 v65, v66, v67
	v_cvt_pk_bf16_f32 v68, v68, v69
	v_cvt_pk_bf16_f32 v69, v70, v71
	ds_write_b64 v10, v[64:65] offset:17408
	ds_write_b64 v10, v[68:69] offset:19712
	s_waitcnt lgkmcnt(0)
	s_barrier
	ds_read_b128 v[32:35], v9 offset:17408
	ds_read_b128 v[36:39], v9 offset:19712
	ds_read_b128 v[40:43], v9 offset:17472
	ds_read_b128 v[44:47], v9 offset:19776
	s_waitcnt lgkmcnt(2)
	v_mfma_f32_16x16x32_bf16 v[16:19], v[196:199], v[32:35], v[16:19]
	v_mfma_f32_16x16x32_bf16 v[20:23], v[196:199], v[36:39], v[20:23]
	s_waitcnt lgkmcnt(0)
	v_mfma_f32_16x16x32_bf16 v[16:19], v[200:203], v[40:43], v[16:19]
	v_mfma_f32_16x16x32_bf16 v[20:23], v[200:203], v[44:47], v[20:23]
	s_nop 7
	v_cvt_pk_bf16_f32 v64, v16, v17
	v_cvt_pk_bf16_f32 v65, v18, v19
	v_cvt_pk_bf16_f32 v66, v20, v21
	v_cvt_pk_bf16_f32 v67, v22, v23
	ds_write_b64 v11, v[64:65] offset:8704
	ds_write_b64 v11, v[66:67] offset:13056
	s_waitcnt lgkmcnt(0)
	s_barrier
	s_waitcnt vmcnt(23)
	ds_read_b128 v[32:35], v8 offset:8704
	ds_read_b128 v[36:39], v8 offset:13056
	ds_read_b128 v[40:43], v8 offset:8768
	ds_read_b128 v[44:47], v8 offset:13120
	ds_read_b128 v[48:51], v8 offset:8832
	ds_read_b128 v[52:55], v8 offset:13184
	ds_read_b128 v[56:59], v8 offset:8896
	ds_read_b128 v[60:63], v8 offset:13248
	global_load_dwordx4 v[136:139], v1, s[0:1]
	global_load_dwordx4 v[140:143], v1, s[0:1] offset:1024
	global_load_dwordx4 v[144:147], v1, s[0:1] offset:2048
	global_load_dwordx4 v[148:151], v1, s[0:1] offset:3072
	global_load_dwordx2 v[188:189], v2, s[2:3]
	global_load_dwordx2 v[190:191], v2, s[2:3] offset:2048
	global_load_dwordx4 v[196:199], v1, s[4:5]
	global_load_dwordx4 v[200:203], v1, s[4:5] offset:1024
	global_load_dword v186, v3, s[6:7]
	v_add_u32_e32 v1, 0x4000, v1
	v_add_u32_e32 v2, 0x4000, v2
	v_add_u32_e32 v3, 4, v3
	s_waitcnt vmcnt(27)
	v_mul_f32_e32 v16, v187, v16
	v_mul_f32_e32 v17, v187, v17
	v_mul_f32_e32 v18, v187, v18
	v_mul_f32_e32 v19, v187, v19
	v_mul_f32_e32 v20, v187, v20
	v_mul_f32_e32 v21, v187, v21
	v_mul_f32_e32 v22, v187, v22
	v_mul_f32_e32 v23, v187, v23
	v_lshlrev_b32_e32 v64, 16, v232
	v_and_b32_e32 v65, 0xffff0000, v232
	v_lshlrev_b32_e32 v66, 16, v233
	v_and_b32_e32 v67, 0xffff0000, v233
	v_lshlrev_b32_e32 v68, 16, v234
	v_and_b32_e32 v69, 0xffff0000, v234
	v_lshlrev_b32_e32 v70, 16, v235
	v_and_b32_e32 v71, 0xffff0000, v235
	s_waitcnt lgkmcnt(6)
	v_mfma_f32_16x16x32_bf16 v[24:27], v[216:219], v[32:35], 0
	v_mfma_f32_16x16x32_bf16 v[28:31], v[216:219], v[36:39], 0
	s_waitcnt lgkmcnt(4)
	v_mfma_f32_16x16x32_bf16 v[24:27], v[220:223], v[40:43], v[24:27]
	v_mfma_f32_16x16x32_bf16 v[28:31], v[220:223], v[44:47], v[28:31]
	s_waitcnt lgkmcnt(2)
	v_mfma_f32_16x16x32_bf16 v[24:27], v[224:227], v[48:51], v[24:27]
	v_mfma_f32_16x16x32_bf16 v[28:31], v[224:227], v[52:55], v[28:31]
	s_waitcnt lgkmcnt(0)
	v_mfma_f32_16x16x32_bf16 v[24:27], v[228:231], v[56:59], v[24:27]
	v_mfma_f32_16x16x32_bf16 v[28:31], v[228:231], v[60:63], v[28:31]
	s_nop 7
	v_sub_f32_e32 v64, v64, v24
	v_sub_f32_e32 v65, v65, v25
	v_sub_f32_e32 v66, v66, v26
	v_sub_f32_e32 v67, v67, v27
	v_sub_f32_e32 v68, v68, v28
	v_sub_f32_e32 v69, v69, v29
	v_sub_f32_e32 v70, v70, v30
	v_sub_f32_e32 v71, v71, v31
	v_cvt_pk_bf16_f32 v64, v64, v65
	v_cvt_pk_bf16_f32 v65, v66, v67
	v_cvt_pk_bf16_f32 v68, v68, v69
	v_cvt_pk_bf16_f32 v69, v70, v71
	ds_write_b64 v10, v[64:65] offset:17408
	ds_write_b64 v10, v[68:69] offset:19712
	s_waitcnt lgkmcnt(0)
	s_barrier
	ds_read_b128 v[32:35], v9 offset:17408
	ds_read_b128 v[36:39], v9 offset:19712
	ds_read_b128 v[40:43], v9 offset:17472
	ds_read_b128 v[44:47], v9 offset:19776
	s_waitcnt lgkmcnt(2)
	v_mfma_f32_16x16x32_bf16 v[16:19], v[240:243], v[32:35], v[16:19]
	v_mfma_f32_16x16x32_bf16 v[20:23], v[240:243], v[36:39], v[20:23]
	s_waitcnt lgkmcnt(0)
	v_mfma_f32_16x16x32_bf16 v[16:19], v[244:247], v[40:43], v[16:19]
	v_mfma_f32_16x16x32_bf16 v[20:23], v[244:247], v[44:47], v[20:23]
	s_nop 7
	v_cvt_pk_bf16_f32 v64, v16, v17
	v_cvt_pk_bf16_f32 v65, v18, v19
	v_cvt_pk_bf16_f32 v66, v20, v21
	v_cvt_pk_bf16_f32 v67, v22, v23
	ds_write_b64 v11, v[64:65] offset:0
	ds_write_b64 v11, v[66:67] offset:4352
	s_waitcnt lgkmcnt(0)
	s_barrier
	s_sub_u32 s10, s10, 1
	s_cmp_lg_u32 s10, 0
	s_cbranch_scc1 .Lscan_V_loop
	s_branch .Lscan_done
.Lscan_O_path:
	v_lshlrev_b32_e32 v2, 4, v14
	global_load_dwordx4 v[72:75], v1, s[0:1]
	global_load_dwordx4 v[76:79], v1, s[0:1] offset:1024
	global_load_dwordx4 v[80:83], v1, s[0:1] offset:2048
	global_load_dwordx4 v[84:87], v1, s[0:1] offset:3072
	global_load_dwordx4 v[88:91], v2, s[2:3]
	global_load_dwordx4 v[92:95], v2, s[2:3] offset:1024
	global_load_dwordx4 v[96:99], v1, s[4:5]
	global_load_dwordx4 v[100:103], v1, s[4:5] offset:1024
	global_load_dword v184, v3, s[6:7]
	v_add_u32_e32 v1, 0x4000, v1
	v_add_u32_e32 v2, 0x2000, v2
	v_add_u32_e32 v3, 4, v3
	global_load_dwordx4 v[104:107], v1, s[0:1]
	global_load_dwordx4 v[108:111], v1, s[0:1] offset:1024
	global_load_dwordx4 v[112:115], v1, s[0:1] offset:2048
	global_load_dwordx4 v[116:119], v1, s[0:1] offset:3072
	global_load_dwordx4 v[120:123], v2, s[2:3]
	global_load_dwordx4 v[124:127], v2, s[2:3] offset:1024
	global_load_dwordx4 v[128:131], v1, s[4:5]
	global_load_dwordx4 v[132:135], v1, s[4:5] offset:1024
	global_load_dword v185, v3, s[6:7]
	v_add_u32_e32 v1, 0x4000, v1
	v_add_u32_e32 v2, 0x2000, v2
	v_add_u32_e32 v3, 4, v3
	global_load_dwordx4 v[136:139], v1, s[0:1]
	global_load_dwordx4 v[140:143], v1, s[0:1] offset:1024
	global_load_dwordx4 v[144:147], v1, s[0:1] offset:2048
	global_load_dwordx4 v[148:151], v1, s[0:1] offset:3072
	global_load_dwordx4 v[188:191], v2, s[2:3]
	global_load_dwordx4 v[192:195], v2, s[2:3] offset:1024
	global_load_dwordx4 v[196:199], v1, s[4:5]
	global_load_dwordx4 v[200:203], v1, s[4:5] offset:1024
	global_load_dword v186, v3, s[6:7]
	v_add_u32_e32 v1, 0x4000, v1
	v_add_u32_e32 v2, 0x2000, v2
	v_add_u32_e32 v3, 4, v3
	s_waitcnt vmcnt(0)
	s_movk_i32 s10, 32
.Lscan_O_loop:
	s_waitcnt vmcnt(47)
	ds_read_b128 v[32:35], v8 offset:0
	ds_read_b128 v[36:39], v8 offset:4352
	ds_read_b128 v[40:43], v8 offset:64
	ds_read_b128 v[44:47], v8 offset:4416
	ds_read_b128 v[48:51], v8 offset:128
	ds_read_b128 v[52:55], v8 offset:4480
	ds_read_b128 v[56:59], v8 offset:192
	ds_read_b128 v[60:63], v8 offset:4544
	global_load_dwordx4 v[216:219], v1, s[0:1]
	global_load_dwordx4 v[220:223], v1, s[0:1] offset:1024
	global_load_dwordx4 v[224:227], v1, s[0:1] offset:2048
	global_load_dwordx4 v[228:231], v1, s[0:1] offset:3072
	global_load_dwordx4 v[232:235], v2, s[2:3]
	global_load_dwordx4 v[236:239], v2, s[2:3] offset:1024
	global_load_dwordx4 v[240:243], v1, s[4:5]
	global_load_dwordx4 v[244:247], v1, s[4:5] offset:1024
	global_load_dword v187, v3, s[6:7]
	v_add_u32_e32 v1, 0x4000, v1
	v_add_u32_e32 v2, 0x2000, v2
	v_add_u32_e32 v3, 4, v3
	s_waitcnt vmcnt(51)
	v_mul_f32_e32 v16, v184, v16
	v_mul_f32_e32 v17, v184, v17
	v_mul_f32_e32 v18, v184, v18
	v_mul_f32_e32 v19, v184, v19
	v_mul_f32_e32 v20, v184, v20
	v_mul_f32_e32 v21, v184, v21
	v_mul_f32_e32 v22, v184, v22
	v_mul_f32_e32 v23, v184, v23
	s_waitcnt lgkmcnt(6)
	v_mfma_f32_16x16x32_bf16 v[24:27], v[72:75], v[32:35], 0
	v_mfma_f32_16x16x32_bf16 v[28:31], v[72:75], v[36:39], 0
	s_waitcnt lgkmcnt(4)
	v_mfma_f32_16x16x32_bf16 v[24:27], v[76:79], v[40:43], v[24:27]
	v_mfma_f32_16x16x32_bf16 v[28:31], v[76:79], v[44:47], v[28:31]
	s_waitcnt lgkmcnt(2)
	v_mfma_f32_16x16x32_bf16 v[24:27], v[80:83], v[48:51], v[24:27]
	v_mfma_f32_16x16x32_bf16 v[28:31], v[80:83], v[52:55], v[28:31]
	s_waitcnt lgkmcnt(0)
	v_mfma_f32_16x16x32_bf16 v[24:27], v[84:87], v[56:59], v[24:27]
	v_mfma_f32_16x16x32_bf16 v[28:31], v[84:87], v[60:63], v[28:31]
	s_waitcnt lgkmcnt(0)
	s_barrier
	ds_read_b128 v[32:35], v9 offset:17408
	ds_read_b128 v[36:39], v9 offset:19712
	ds_read_b128 v[40:43], v9 offset:17472
	ds_read_b128 v[44:47], v9 offset:19776
	s_waitcnt lgkmcnt(2)
	v_mfma_f32_16x16x32_bf16 v[16:19], v[96:99], v[32:35], v[16:19]
	v_mfma_f32_16x16x32_bf16 v[20:23], v[96:99], v[36:39], v[20:23]
	v_mfma_f32_16x16x32_bf16 v[24:27], v[88:91], v[32:35], v[24:27]
	v_mfma_f32_16x16x32_bf16 v[28:31], v[88:91], v[36:39], v[28:31]
	s_waitcnt lgkmcnt(0)
	v_mfma_f32_16x16x32_bf16 v[16:19], v[100:103], v[40:43], v[16:19]
	v_mfma_f32_16x16x32_bf16 v[20:23], v[100:103], v[44:47], v[20:23]
	v_mfma_f32_16x16x32_bf16 v[24:27], v[92:95], v[40:43], v[24:27]
	v_mfma_f32_16x16x32_bf16 v[28:31], v[92:95], v[44:47], v[28:31]
	s_nop 5
	v_cvt_pk_bf16_f32 v64, v16, v17
	v_cvt_pk_bf16_f32 v65, v18, v19
	v_cvt_pk_bf16_f32 v66, v20, v21
	v_cvt_pk_bf16_f32 v67, v22, v23
	ds_write_b64 v11, v[64:65] offset:8704
	ds_write_b64 v11, v[66:67] offset:13056
	v_cvt_pk_bf16_f32 v68, v24, v25
	v_cvt_pk_bf16_f32 v69, v26, v27
	v_cvt_pk_bf16_f32 v70, v28, v29
	v_cvt_pk_bf16_f32 v71, v30, v31
	global_store_short v12, v68, s[8:9]
	global_store_short_d16_hi v12, v68, s[8:9] offset:2048
	global_store_short v13, v69, s[8:9]
	global_store_short_d16_hi v13, v69, s[8:9] offset:2048
	global_store_short v12, v70, s[8:9] offset:32
	global_store_short_d16_hi v12, v70, s[8:9] offset:2080
	global_store_short v13, v71, s[8:9] offset:32
	global_store_short_d16_hi v13, v71, s[8:9] offset:2080
	v_add_u32_e32 v12, 0x20000, v12
	v_add_u32_e32 v13, 0x20000, v13
	s_waitcnt lgkmcnt(0)
	s_barrier
	s_waitcnt vmcnt(47)
	ds_read_b128 v[32:35], v8 offset:8704
	ds_read_b128 v[36:39], v8 offset:13056
	ds_read_b128 v[40:43], v8 offset:8768
	ds_read_b128 v[44:47], v8 offset:13120
	ds_read_b128 v[48:51], v8 offset:8832
	ds_read_b128 v[52:55], v8 offset:13184
	ds_read_b128 v[56:59], v8 offset:8896
	ds_read_b128 v[60:63], v8 offset:13248
	global_load_dwordx4 v[72:75], v1, s[0:1]
	global_load_dwordx4 v[76:79], v1, s[0:1] offset:1024
	global_load_dwordx4 v[80:83], v1, s[0:1] offset:2048
	global_load_dwordx4 v[84:87], v1, s[0:1] offset:3072
	global_load_dwordx4 v[88:91], v2, s[2:3]
	global_load_dwordx4 v[92:95], v2, s[2:3] offset:1024
	global_load_dwordx4 v[96:99], v1, s[4:5]
	global_load_dwordx4 v[100:103], v1, s[4:5] offset:1024
	global_load_dword v184, v3, s[6:7]
	v_add_u32_e32 v1, 0x4000, v1
	v_add_u32_e32 v2, 0x2000, v2
	v_add_u32_e32 v3, 4, v3
	s_waitcnt vmcnt(51)
	v_mul_f32_e32 v16, v185, v16
	v_mul_f32_e32 v17, v185, v17
	v_mul_f32_e32 v18, v185, v18
	v_mul_f32_e32 v19, v185, v19
	v_mul_f32_e32 v20, v185, v20
	v_mul_f32_e32 v21, v185, v21
	v_mul_f32_e32 v22, v185, v22
	v_mul_f32_e32 v23, v185, v23
	s_waitcnt lgkmcnt(6)
	v_mfma_f32_16x16x32_bf16 v[24:27], v[104:107], v[32:35], 0
	v_mfma_f32_16x16x32_bf16 v[28:31], v[104:107], v[36:39], 0
	s_waitcnt lgkmcnt(4)
	v_mfma_f32_16x16x32_bf16 v[24:27], v[108:111], v[40:43], v[24:27]
	v_mfma_f32_16x16x32_bf16 v[28:31], v[108:111], v[44:47], v[28:31]
	s_waitcnt lgkmcnt(2)
	v_mfma_f32_16x16x32_bf16 v[24:27], v[112:115], v[48:51], v[24:27]
	v_mfma_f32_16x16x32_bf16 v[28:31], v[112:115], v[52:55], v[28:31]
	s_waitcnt lgkmcnt(0)
	v_mfma_f32_16x16x32_bf16 v[24:27], v[116:119], v[56:59], v[24:27]
	v_mfma_f32_16x16x32_bf16 v[28:31], v[116:119], v[60:63], v[28:31]
	s_waitcnt lgkmcnt(0)
	s_barrier
	ds_read_b128 v[32:35], v9 offset:17408
	ds_read_b128 v[36:39], v9 offset:19712
	ds_read_b128 v[40:43], v9 offset:17472
	ds_read_b128 v[44:47], v9 offset:19776
	s_waitcnt lgkmcnt(2)
	v_mfma_f32_16x16x32_bf16 v[16:19], v[128:131], v[32:35], v[16:19]
	v_mfma_f32_16x16x32_bf16 v[20:23], v[128:131], v[36:39], v[20:23]
	v_mfma_f32_16x16x32_bf16 v[24:27], v[120:123], v[32:35], v[24:27]
	v_mfma_f32_16x16x32_bf16 v[28:31], v[120:123], v[36:39], v[28:31]
	s_waitcnt lgkmcnt(0)
	v_mfma_f32_16x16x32_bf16 v[16:19], v[132:135], v[40:43], v[16:19]
	v_mfma_f32_16x16x32_bf16 v[20:23], v[132:135], v[44:47], v[20:23]
	v_mfma_f32_16x16x32_bf16 v[24:27], v[124:127], v[40:43], v[24:27]
	v_mfma_f32_16x16x32_bf16 v[28:31], v[124:127], v[44:47], v[28:31]
	s_nop 5
	v_cvt_pk_bf16_f32 v64, v16, v17
	v_cvt_pk_bf16_f32 v65, v18, v19
	v_cvt_pk_bf16_f32 v66, v20, v21
	v_cvt_pk_bf16_f32 v67, v22, v23
	ds_write_b64 v11, v[64:65] offset:0
	ds_write_b64 v11, v[66:67] offset:4352
	v_cvt_pk_bf16_f32 v68, v24, v25
	v_cvt_pk_bf16_f32 v69, v26, v27
	v_cvt_pk_bf16_f32 v70, v28, v29
	v_cvt_pk_bf16_f32 v71, v30, v31
	global_store_short v12, v68, s[8:9]
	global_store_short_d16_hi v12, v68, s[8:9] offset:2048
	global_store_short v13, v69, s[8:9]
	global_store_short_d16_hi v13, v69, s[8:9] offset:2048
	global_store_short v12, v70, s[8:9] offset:32
	global_store_short_d16_hi v12, v70, s[8:9] offset:2080
	global_store_short v13, v71, s[8:9] offset:32
	global_store_short_d16_hi v13, v71, s[8:9] offset:2080
	v_add_u32_e32 v12, 0x20000, v12
	v_add_u32_e32 v13, 0x20000, v13
	s_waitcnt lgkmcnt(0)
	s_barrier
	s_waitcnt vmcnt(47)
	ds_read_b128 v[32:35], v8 offset:0
	ds_read_b128 v[36:39], v8 offset:4352
	ds_read_b128 v[40:43], v8 offset:64
	ds_read_b128 v[44:47], v8 offset:4416
	ds_read_b128 v[48:51], v8 offset:128
	ds_read_b128 v[52:55], v8 offset:4480
	ds_read_b128 v[56:59], v8 offset:192
	ds_read_b128 v[60:63], v8 offset:4544
	global_load_dwordx4 v[104:107], v1, s[0:1]
	global_load_dwordx4 v[108:111], v1, s[0:1] offset:1024
	global_load_dwordx4 v[112:115], v1, s[0:1] offset:2048
	global_load_dwordx4 v[116:119], v1, s[0:1] offset:3072
	global_load_dwordx4 v[120:123], v2, s[2:3]
	global_load_dwordx4 v[124:127], v2, s[2:3] offset:1024
	global_load_dwordx4 v[128:131], v1, s[4:5]
	global_load_dwordx4 v[132:135], v1, s[4:5] offset:1024
	global_load_dword v185, v3, s[6:7]
	v_add_u32_e32 v1, 0x4000, v1
	v_add_u32_e32 v2, 0x2000, v2
	v_add_u32_e32 v3, 4, v3
	s_waitcnt vmcnt(51)
	v_mul_f32_e32 v16, v186, v16
	v_mul_f32_e32 v17, v186, v17
	v_mul_f32_e32 v18, v186, v18
	v_mul_f32_e32 v19, v186, v19
	v_mul_f32_e32 v20, v186, v20
	v_mul_f32_e32 v21, v186, v21
	v_mul_f32_e32 v22, v186, v22
	v_mul_f32_e32 v23, v186, v23
	s_waitcnt lgkmcnt(6)
	v_mfma_f32_16x16x32_bf16 v[24:27], v[136:139], v[32:35], 0
	v_mfma_f32_16x16x32_bf16 v[28:31], v[136:139], v[36:39], 0
	s_waitcnt lgkmcnt(4)
	v_mfma_f32_16x16x32_bf16 v[24:27], v[140:143], v[40:43], v[24:27]
	v_mfma_f32_16x16x32_bf16 v[28:31], v[140:143], v[44:47], v[28:31]
	s_waitcnt lgkmcnt(2)
	v_mfma_f32_16x16x32_bf16 v[24:27], v[144:147], v[48:51], v[24:27]
	v_mfma_f32_16x16x32_bf16 v[28:31], v[144:147], v[52:55], v[28:31]
	s_waitcnt lgkmcnt(0)
	v_mfma_f32_16x16x32_bf16 v[24:27], v[148:151], v[56:59], v[24:27]
	v_mfma_f32_16x16x32_bf16 v[28:31], v[148:151], v[60:63], v[28:31]
	s_waitcnt lgkmcnt(0)
	s_barrier
	ds_read_b128 v[32:35], v9 offset:17408
	ds_read_b128 v[36:39], v9 offset:19712
	ds_read_b128 v[40:43], v9 offset:17472
	ds_read_b128 v[44:47], v9 offset:19776
	s_waitcnt lgkmcnt(2)
	v_mfma_f32_16x16x32_bf16 v[16:19], v[196:199], v[32:35], v[16:19]
	v_mfma_f32_16x16x32_bf16 v[20:23], v[196:199], v[36:39], v[20:23]
	v_mfma_f32_16x16x32_bf16 v[24:27], v[188:191], v[32:35], v[24:27]
	v_mfma_f32_16x16x32_bf16 v[28:31], v[188:191], v[36:39], v[28:31]
	s_waitcnt lgkmcnt(0)
	v_mfma_f32_16x16x32_bf16 v[16:19], v[200:203], v[40:43], v[16:19]
	v_mfma_f32_16x16x32_bf16 v[20:23], v[200:203], v[44:47], v[20:23]
	v_mfma_f32_16x16x32_bf16 v[24:27], v[192:195], v[40:43], v[24:27]
	v_mfma_f32_16x16x32_bf16 v[28:31], v[192:195], v[44:47], v[28:31]
	s_nop 5
	v_cvt_pk_bf16_f32 v64, v16, v17
	v_cvt_pk_bf16_f32 v65, v18, v19
	v_cvt_pk_bf16_f32 v66, v20, v21
	v_cvt_pk_bf16_f32 v67, v22, v23
	ds_write_b64 v11, v[64:65] offset:8704
	ds_write_b64 v11, v[66:67] offset:13056
	v_cvt_pk_bf16_f32 v68, v24, v25
	v_cvt_pk_bf16_f32 v69, v26, v27
	v_cvt_pk_bf16_f32 v70, v28, v29
	v_cvt_pk_bf16_f32 v71, v30, v31
	global_store_short v12, v68, s[8:9]
	global_store_short_d16_hi v12, v68, s[8:9] offset:2048
	global_store_short v13, v69, s[8:9]
	global_store_short_d16_hi v13, v69, s[8:9] offset:2048
	global_store_short v12, v70, s[8:9] offset:32
	global_store_short_d16_hi v12, v70, s[8:9] offset:2080
	global_store_short v13, v71, s[8:9] offset:32
	global_store_short_d16_hi v13, v71, s[8:9] offset:2080
	v_add_u32_e32 v12, 0x20000, v12
	v_add_u32_e32 v13, 0x20000, v13
	s_waitcnt lgkmcnt(0)
	s_barrier
	s_waitcnt vmcnt(47)
	ds_read_b128 v[32:35], v8 offset:8704
	ds_read_b128 v[36:39], v8 offset:13056
	ds_read_b128 v[40:43], v8 offset:8768
	ds_read_b128 v[44:47], v8 offset:13120
	ds_read_b128 v[48:51], v8 offset:8832
	ds_read_b128 v[52:55], v8 offset:13184
	ds_read_b128 v[56:59], v8 offset:8896
	ds_read_b128 v[60:63], v8 offset:13248
	global_load_dwordx4 v[136:139], v1, s[0:1]
	global_load_dwordx4 v[140:143], v1, s[0:1] offset:1024
	global_load_dwordx4 v[144:147], v1, s[0:1] offset:2048
	global_load_dwordx4 v[148:151], v1, s[0:1] offset:3072
	global_load_dwordx4 v[188:191], v2, s[2:3]
	global_load_dwordx4 v[192:195], v2, s[2:3] offset:1024
	global_load_dwordx4 v[196:199], v1, s[4:5]
	global_load_dwordx4 v[200:203], v1, s[4:5] offset:1024
	global_load_dword v186, v3, s[6:7]
	v_add_u32_e32 v1, 0x4000, v1
	v_add_u32_e32 v2, 0x2000, v2
	v_add_u32_e32 v3, 4, v3
	s_waitcnt vmcnt(51)
	v_mul_f32_e32 v16, v187, v16
	v_mul_f32_e32 v17, v187, v17
	v_mul_f32_e32 v18, v187, v18
	v_mul_f32_e32 v19, v187, v19
	v_mul_f32_e32 v20, v187, v20
	v_mul_f32_e32 v21, v187, v21
	v_mul_f32_e32 v22, v187, v22
	v_mul_f32_e32 v23, v187, v23
	s_waitcnt lgkmcnt(6)
	v_mfma_f32_16x16x32_bf16 v[24:27], v[216:219], v[32:35], 0
	v_mfma_f32_16x16x32_bf16 v[28:31], v[216:219], v[36:39], 0
	s_waitcnt lgkmcnt(4)
	v_mfma_f32_16x16x32_bf16 v[24:27], v[220:223], v[40:43], v[24:27]
	v_mfma_f32_16x16x32_bf16 v[28:31], v[220:223], v[44:47], v[28:31]
	s_waitcnt lgkmcnt(2)
	v_mfma_f32_16x16x32_bf16 v[24:27], v[224:227], v[48:51], v[24:27]
	v_mfma_f32_16x16x32_bf16 v[28:31], v[224:227], v[52:55], v[28:31]
	s_waitcnt lgkmcnt(0)
	v_mfma_f32_16x16x32_bf16 v[24:27], v[228:231], v[56:59], v[24:27]
	v_mfma_f32_16x16x32_bf16 v[28:31], v[228:231], v[60:63], v[28:31]
	s_waitcnt lgkmcnt(0)
	s_barrier
	ds_read_b128 v[32:35], v9 offset:17408
	ds_read_b128 v[36:39], v9 offset:19712
	ds_read_b128 v[40:43], v9 offset:17472
	ds_read_b128 v[44:47], v9 offset:19776
	s_waitcnt lgkmcnt(2)
	v_mfma_f32_16x16x32_bf16 v[16:19], v[240:243], v[32:35], v[16:19]
	v_mfma_f32_16x16x32_bf16 v[20:23], v[240:243], v[36:39], v[20:23]
	v_mfma_f32_16x16x32_bf16 v[24:27], v[232:235], v[32:35], v[24:27]
	v_mfma_f32_16x16x32_bf16 v[28:31], v[232:235], v[36:39], v[28:31]
	s_waitcnt lgkmcnt(0)
	v_mfma_f32_16x16x32_bf16 v[16:19], v[244:247], v[40:43], v[16:19]
	v_mfma_f32_16x16x32_bf16 v[20:23], v[244:247], v[44:47], v[20:23]
	v_mfma_f32_16x16x32_bf16 v[24:27], v[236:239], v[40:43], v[24:27]
	v_mfma_f32_16x16x32_bf16 v[28:31], v[236:239], v[44:47], v[28:31]
	s_nop 5
	v_cvt_pk_bf16_f32 v64, v16, v17
	v_cvt_pk_bf16_f32 v65, v18, v19
	v_cvt_pk_bf16_f32 v66, v20, v21
	v_cvt_pk_bf16_f32 v67, v22, v23
	ds_write_b64 v11, v[64:65] offset:0
	ds_write_b64 v11, v[66:67] offset:4352
	v_cvt_pk_bf16_f32 v68, v24, v25
	v_cvt_pk_bf16_f32 v69, v26, v27
	v_cvt_pk_bf16_f32 v70, v28, v29
	v_cvt_pk_bf16_f32 v71, v30, v31
	global_store_short v12, v68, s[8:9]
	global_store_short_d16_hi v12, v68, s[8:9] offset:2048
	global_store_short v13, v69, s[8:9]
	global_store_short_d16_hi v13, v69, s[8:9] offset:2048
	global_store_short v12, v70, s[8:9] offset:32
	global_store_short_d16_hi v12, v70, s[8:9] offset:2080
	global_store_short v13, v71, s[8:9] offset:32
	global_store_short_d16_hi v13, v71, s[8:9] offset:2080
	v_add_u32_e32 v12, 0x20000, v12
	v_add_u32_e32 v13, 0x20000, v13
	s_waitcnt lgkmcnt(0)
	s_barrier
	s_sub_u32 s10, s10, 1
	s_cmp_lg_u32 s10, 0
	s_cbranch_scc1 .Lscan_O_loop
.Lscan_done:
.LBB0_704:
	s_waitcnt vmcnt(0)
	s_waitcnt lgkmcnt(0)
	s_barrier
	s_mov_b64 s[0:1], exec
	v_readlane_b32 s2, v248, 18
	v_readlane_b32 s3, v248, 19
	s_and_b64 s[2:3], s[0:1], s[2:3]
	s_mov_b64 exec, s[2:3]
	s_cbranch_execz .LBB0_756
	v_readlane_b32 s2, v251, 2
	s_waitcnt vmcnt(0) expcnt(0) lgkmcnt(0)
	s_nop 0
	v_mov_b32_e32 v1, s2
	ds_read_b32 v3, v1
	v_readlane_b32 s2, v251, 3
	s_waitcnt lgkmcnt(0)
	v_cmp_ne_u32_e32 vcc, 0, v3
	v_mov_b32_e32 v1, s2
	ds_read_b32 v2, v1
	s_cbranch_vccnz .LBB0_720
	s_mov_b32 s8, 1
	s_branch .LBB0_708

.LBB0_846:
	v_and_b32_e32 v160, 63, v206
	v_lshrrev_b32_e32 v161, 6, v206
	v_and_b32_e32 v162, 15, v160
	v_readfirstlane_b32 s16, v161
	v_lshrrev_b32_e32 v163, 4, v160
	s_nop 3
	s_and_b32 s17, s16, 3
	s_lshl_b32 s17, s17, 5
	s_lshl_b32 s9, s33, 8
	s_add_i32 s17, s17, s9
	v_lshl_add_u32 v164, v163, 3, s17
	s_lshr_b32 s17, s16, 2
	s_lshl_b32 s17, s17, 6
	s_lshl_b32 s9, s37, 8
	s_add_i32 s9, s9, s17
	v_add_u32_e32 v165, s9, v162
	v_lshlrev_b32_e32 v146, 11, v165
	v_lshl_add_u32 v146, v164, 1, v146
	s_add_u32 s46, s70, 0x6c00000
	s_addc_u32 s47, s71, 0
	s_add_u32 s48, s70, 0x8c00000
	s_addc_u32 s49, s71, 0
	v_mov_b32_e32 v147, 0x21800000
	v_mov_b32_e32 v172, v146
	v_add_u32_e32 v173, 0x8000, v146
	v_add_u32_e32 v174, 0x10000, v146
	v_add_u32_e32 v175, 0x18000, v146
	v_add_u32_e32 v176, 0x40000, v146
	v_add_u32_e32 v177, 0x48000, v146
	v_add_u32_e32 v178, 0x50000, v146
	v_add_u32_e32 v179, 0x58000, v146
	global_load_dwordx4 v[192:195], v172, s[46:47]
	global_load_dwordx4 v[196:199], v172, s[48:49]
	global_load_dwordx4 v[200:203], v172, s[46:47] offset:256
	global_load_dwordx4 v[216:219], v172, s[48:49] offset:256
	global_load_dwordx4 v[220:223], v173, s[46:47]
	global_load_dwordx4 v[224:227], v173, s[48:49]
	global_load_dwordx4 v[228:231], v173, s[46:47] offset:256
	global_load_dwordx4 v[232:235], v173, s[48:49] offset:256
	global_load_dwordx4 v[236:239], v174, s[46:47]
	global_load_dwordx4 v[240:243], v174, s[48:49]
	s_waitcnt vmcnt(8)
	v_lshlrev_b32_e32 v160, 16, v192
	v_and_b32_e32 v161, 0xffff0000, v192
	v_lshlrev_b32_e32 v162, 16, v193
	v_and_b32_e32 v163, 0xffff0000, v193
	v_lshlrev_b32_e32 v164, 16, v194
	v_and_b32_e32 v165, 0xffff0000, v194
	v_lshlrev_b32_e32 v180, 16, v195
	v_and_b32_e32 v181, 0xffff0000, v195
	v_lshlrev_b32_e32 v183, 16, v196
	v_and_b32_e32 v184, 0xffff0000, v196
	v_lshlrev_b32_e32 v185, 16, v197
	v_and_b32_e32 v186, 0xffff0000, v197
	v_lshlrev_b32_e32 v187, 16, v198
	v_and_b32_e32 v188, 0xffff0000, v198
	v_lshlrev_b32_e32 v189, 16, v199
	v_and_b32_e32 v190, 0xffff0000, v199
	global_load_dwordx4 v[192:195], v174, s[46:47] offset:256
	global_load_dwordx4 v[196:199], v174, s[48:49] offset:256
	v_max_f32_e32 v183, v183, v147
	v_max_f32_e32 v184, v184, v147
	v_max_f32_e32 v185, v185, v147
	v_max_f32_e32 v186, v186, v147
	v_max_f32_e32 v187, v187, v147
	v_max_f32_e32 v188, v188, v147
	v_max_f32_e32 v189, v189, v147
	v_max_f32_e32 v190, v190, v147
	v_rcp_f32_e32 v183, v183
	v_rcp_f32_e32 v184, v184
	v_rcp_f32_e32 v185, v185
	v_rcp_f32_e32 v186, v186
	v_rcp_f32_e32 v187, v187
	v_rcp_f32_e32 v188, v188
	v_rcp_f32_e32 v189, v189
	v_rcp_f32_e32 v190, v190
	v_mul_f32_e32 v160, v160, v183
	v_mul_f32_e32 v161, v161, v184
	v_mul_f32_e32 v162, v162, v185
	v_mul_f32_e32 v163, v163, v186
	v_mul_f32_e32 v164, v164, v187
	v_mul_f32_e32 v165, v165, v188
	v_mul_f32_e32 v180, v180, v189
	v_mul_f32_e32 v181, v181, v190
	v_mul_f32_e32 v132, v132, v160
	v_mul_f32_e32 v133, v133, v161
	v_mul_f32_e32 v134, v134, v162
	v_mul_f32_e32 v135, v135, v163
	v_mul_f32_e32 v128, v128, v164
	v_mul_f32_e32 v129, v129, v165
	v_mul_f32_e32 v130, v130, v180
	v_mul_f32_e32 v131, v131, v181
	s_waitcnt vmcnt(8)
	v_lshlrev_b32_e32 v160, 16, v200
	v_and_b32_e32 v161, 0xffff0000, v200
	v_lshlrev_b32_e32 v162, 16, v201
	v_and_b32_e32 v163, 0xffff0000, v201
	v_lshlrev_b32_e32 v164, 16, v202
	v_and_b32_e32 v165, 0xffff0000, v202
	v_lshlrev_b32_e32 v180, 16, v203
	v_and_b32_e32 v181, 0xffff0000, v203
	v_lshlrev_b32_e32 v183, 16, v216
	v_and_b32_e32 v184, 0xffff0000, v216
	v_lshlrev_b32_e32 v185, 16, v217
	v_and_b32_e32 v186, 0xffff0000, v217
	v_lshlrev_b32_e32 v187, 16, v218
	v_and_b32_e32 v188, 0xffff0000, v218
	v_lshlrev_b32_e32 v189, 16, v219
	v_and_b32_e32 v190, 0xffff0000, v219
	global_load_dwordx4 v[200:203], v175, s[46:47]
	global_load_dwordx4 v[216:219], v175, s[48:49]
	v_max_f32_e32 v183, v183, v147
	v_max_f32_e32 v184, v184, v147
	v_max_f32_e32 v185, v185, v147
	v_max_f32_e32 v186, v186, v147
	v_max_f32_e32 v187, v187, v147
	v_max_f32_e32 v188, v188, v147
	v_max_f32_e32 v189, v189, v147
	v_max_f32_e32 v190, v190, v147
	v_rcp_f32_e32 v183, v183
	v_rcp_f32_e32 v184, v184
	v_rcp_f32_e32 v185, v185
	v_rcp_f32_e32 v186, v186
	v_rcp_f32_e32 v187, v187
	v_rcp_f32_e32 v188, v188
	v_rcp_f32_e32 v189, v189
	v_rcp_f32_e32 v190, v190
	v_mul_f32_e32 v160, v160, v183
	v_mul_f32_e32 v161, v161, v184
	v_mul_f32_e32 v162, v162, v185
	v_mul_f32_e32 v163, v163, v186
	v_mul_f32_e32 v164, v164, v187
	v_mul_f32_e32 v165, v165, v188
	v_mul_f32_e32 v180, v180, v189
	v_mul_f32_e32 v181, v181, v190
	v_mul_f32_e32 v124, v124, v160
	v_mul_f32_e32 v125, v125, v161
	v_mul_f32_e32 v126, v126, v162
	v_mul_f32_e32 v127, v127, v163
	v_mul_f32_e32 v120, v120, v164
	v_mul_f32_e32 v121, v121, v165
	v_mul_f32_e32 v122, v122, v180
	v_mul_f32_e32 v123, v123, v181
	s_waitcnt vmcnt(8)
	v_lshlrev_b32_e32 v160, 16, v220
	v_and_b32_e32 v161, 0xffff0000, v220
	v_lshlrev_b32_e32 v162, 16, v221
	v_and_b32_e32 v163, 0xffff0000, v221
	v_lshlrev_b32_e32 v164, 16, v222
	v_and_b32_e32 v165, 0xffff0000, v222
	v_lshlrev_b32_e32 v180, 16, v223
	v_and_b32_e32 v181, 0xffff0000, v223
	v_lshlrev_b32_e32 v183, 16, v224
	v_and_b32_e32 v184, 0xffff0000, v224
	v_lshlrev_b32_e32 v185, 16, v225
	v_and_b32_e32 v186, 0xffff0000, v225
	v_lshlrev_b32_e32 v187, 16, v226
	v_and_b32_e32 v188, 0xffff0000, v226
	v_lshlrev_b32_e32 v189, 16, v227
	v_and_b32_e32 v190, 0xffff0000, v227
	global_load_dwordx4 v[220:223], v175, s[46:47] offset:256
	global_load_dwordx4 v[224:227], v175, s[48:49] offset:256
	v_max_f32_e32 v183, v183, v147
	v_max_f32_e32 v184, v184, v147
	v_max_f32_e32 v185, v185, v147
	v_max_f32_e32 v186, v186, v147
	v_max_f32_e32 v187, v187, v147
	v_max_f32_e32 v188, v188, v147
	v_max_f32_e32 v189, v189, v147
	v_max_f32_e32 v190, v190, v147
	v_rcp_f32_e32 v183, v183
	v_rcp_f32_e32 v184, v184
	v_rcp_f32_e32 v185, v185
	v_rcp_f32_e32 v186, v186
	v_rcp_f32_e32 v187, v187
	v_rcp_f32_e32 v188, v188
	v_rcp_f32_e32 v189, v189
	v_rcp_f32_e32 v190, v190
	v_mul_f32_e32 v160, v160, v183
	v_mul_f32_e32 v161, v161, v184
	v_mul_f32_e32 v162, v162, v185
	v_mul_f32_e32 v163, v163, v186
	v_mul_f32_e32 v164, v164, v187
	v_mul_f32_e32 v165, v165, v188
	v_mul_f32_e32 v180, v180, v189
	v_mul_f32_e32 v181, v181, v190
	v_mul_f32_e32 v116, v116, v160
	v_mul_f32_e32 v117, v117, v161
	v_mul_f32_e32 v118, v118, v162
	v_mul_f32_e32 v119, v119, v163
	v_mul_f32_e32 v112, v112, v164
	v_mul_f32_e32 v113, v113, v165
	v_mul_f32_e32 v114, v114, v180
	v_mul_f32_e32 v115, v115, v181
	s_waitcnt vmcnt(8)
	v_lshlrev_b32_e32 v160, 16, v228
	v_and_b32_e32 v161, 0xffff0000, v228
	v_lshlrev_b32_e32 v162, 16, v229
	v_and_b32_e32 v163, 0xffff0000, v229
	v_lshlrev_b32_e32 v164, 16, v230
	v_and_b32_e32 v165, 0xffff0000, v230
	v_lshlrev_b32_e32 v180, 16, v231
	v_and_b32_e32 v181, 0xffff0000, v231
	v_lshlrev_b32_e32 v183, 16, v232
	v_and_b32_e32 v184, 0xffff0000, v232
	v_lshlrev_b32_e32 v185, 16, v233
	v_and_b32_e32 v186, 0xffff0000, v233
	v_lshlrev_b32_e32 v187, 16, v234
	v_and_b32_e32 v188, 0xffff0000, v234
	v_lshlrev_b32_e32 v189, 16, v235
	v_and_b32_e32 v190, 0xffff0000, v235
	global_load_dwordx4 v[228:231], v176, s[46:47]
	global_load_dwordx4 v[232:235], v176, s[48:49]
	v_max_f32_e32 v183, v183, v147
	v_max_f32_e32 v184, v184, v147
	v_max_f32_e32 v185, v185, v147
	v_max_f32_e32 v186, v186, v147
	v_max_f32_e32 v187, v187, v147
	v_max_f32_e32 v188, v188, v147
	v_max_f32_e32 v189, v189, v147
	v_max_f32_e32 v190, v190, v147
	v_rcp_f32_e32 v183, v183
	v_rcp_f32_e32 v184, v184
	v_rcp_f32_e32 v185, v185
	v_rcp_f32_e32 v186, v186
	v_rcp_f32_e32 v187, v187
	v_rcp_f32_e32 v188, v188
	v_rcp_f32_e32 v189, v189
	v_rcp_f32_e32 v190, v190
	v_mul_f32_e32 v160, v160, v183
	v_mul_f32_e32 v161, v161, v184
	v_mul_f32_e32 v162, v162, v185
	v_mul_f32_e32 v163, v163, v186
	v_mul_f32_e32 v164, v164, v187
	v_mul_f32_e32 v165, v165, v188
	v_mul_f32_e32 v180, v180, v189
	v_mul_f32_e32 v181, v181, v190
	v_mul_f32_e32 v108, v108, v160
	v_mul_f32_e32 v109, v109, v161
	v_mul_f32_e32 v110, v110, v162
	v_mul_f32_e32 v111, v111, v163
	v_mul_f32_e32 v104, v104, v164
	v_mul_f32_e32 v105, v105, v165
	v_mul_f32_e32 v106, v106, v180
	v_mul_f32_e32 v107, v107, v181
	s_waitcnt vmcnt(8)
	v_lshlrev_b32_e32 v160, 16, v236
	v_and_b32_e32 v161, 0xffff0000, v236
	v_lshlrev_b32_e32 v162, 16, v237
	v_and_b32_e32 v163, 0xffff0000, v237
	v_lshlrev_b32_e32 v164, 16, v238
	v_and_b32_e32 v165, 0xffff0000, v238
	v_lshlrev_b32_e32 v180, 16, v239
	v_and_b32_e32 v181, 0xffff0000, v239
	v_lshlrev_b32_e32 v183, 16, v240
	v_and_b32_e32 v184, 0xffff0000, v240
	v_lshlrev_b32_e32 v185, 16, v241
	v_and_b32_e32 v186, 0xffff0000, v241
	v_lshlrev_b32_e32 v187, 16, v242
	v_and_b32_e32 v188, 0xffff0000, v242
	v_lshlrev_b32_e32 v189, 16, v243
	v_and_b32_e32 v190, 0xffff0000, v243
	global_load_dwordx4 v[236:239], v176, s[46:47] offset:256
	global_load_dwordx4 v[240:243], v176, s[48:49] offset:256
	v_max_f32_e32 v183, v183, v147
	v_max_f32_e32 v184, v184, v147
	v_max_f32_e32 v185, v185, v147
	v_max_f32_e32 v186, v186, v147
	v_max_f32_e32 v187, v187, v147
	v_max_f32_e32 v188, v188, v147
	v_max_f32_e32 v189, v189, v147
	v_max_f32_e32 v190, v190, v147
	v_rcp_f32_e32 v183, v183
	v_rcp_f32_e32 v184, v184
	v_rcp_f32_e32 v185, v185
	v_rcp_f32_e32 v186, v186
	v_rcp_f32_e32 v187, v187
	v_rcp_f32_e32 v188, v188
	v_rcp_f32_e32 v189, v189
	v_rcp_f32_e32 v190, v190
	v_mul_f32_e32 v160, v160, v183
	v_mul_f32_e32 v161, v161, v184
	v_mul_f32_e32 v162, v162, v185
	v_mul_f32_e32 v163, v163, v186
	v_mul_f32_e32 v164, v164, v187
	v_mul_f32_e32 v165, v165, v188
	v_mul_f32_e32 v180, v180, v189
	v_mul_f32_e32 v181, v181, v190
	v_mul_f32_e32 v100, v100, v160
	v_mul_f32_e32 v101, v101, v161
	v_mul_f32_e32 v102, v102, v162
	v_mul_f32_e32 v103, v103, v163
	v_mul_f32_e32 v96, v96, v164
	v_mul_f32_e32 v97, v97, v165
	v_mul_f32_e32 v98, v98, v180
	v_mul_f32_e32 v99, v99, v181
	s_waitcnt vmcnt(8)
	v_lshlrev_b32_e32 v160, 16, v192
	v_and_b32_e32 v161, 0xffff0000, v192
	v_lshlrev_b32_e32 v162, 16, v193
	v_and_b32_e32 v163, 0xffff0000, v193
	v_lshlrev_b32_e32 v164, 16, v194
	v_and_b32_e32 v165, 0xffff0000, v194
	v_lshlrev_b32_e32 v180, 16, v195
	v_and_b32_e32 v181, 0xffff0000, v195
	v_lshlrev_b32_e32 v183, 16, v196
	v_and_b32_e32 v184, 0xffff0000, v196
	v_lshlrev_b32_e32 v185, 16, v197
	v_and_b32_e32 v186, 0xffff0000, v197
	v_lshlrev_b32_e32 v187, 16, v198
	v_and_b32_e32 v188, 0xffff0000, v198
	v_lshlrev_b32_e32 v189, 16, v199
	v_and_b32_e32 v190, 0xffff0000, v199
	global_load_dwordx4 v[192:195], v177, s[46:47]
	global_load_dwordx4 v[196:199], v177, s[48:49]
	v_max_f32_e32 v183, v183, v147
	v_max_f32_e32 v184, v184, v147
	v_max_f32_e32 v185, v185, v147
	v_max_f32_e32 v186, v186, v147
	v_max_f32_e32 v187, v187, v147
	v_max_f32_e32 v188, v188, v147
	v_max_f32_e32 v189, v189, v147
	v_max_f32_e32 v190, v190, v147
	v_rcp_f32_e32 v183, v183
	v_rcp_f32_e32 v184, v184
	v_rcp_f32_e32 v185, v185
	v_rcp_f32_e32 v186, v186
	v_rcp_f32_e32 v187, v187
	v_rcp_f32_e32 v188, v188
	v_rcp_f32_e32 v189, v189
	v_rcp_f32_e32 v190, v190
	v_mul_f32_e32 v160, v160, v183
	v_mul_f32_e32 v161, v161, v184
	v_mul_f32_e32 v162, v162, v185
	v_mul_f32_e32 v163, v163, v186
	v_mul_f32_e32 v164, v164, v187
	v_mul_f32_e32 v165, v165, v188
	v_mul_f32_e32 v180, v180, v189
	v_mul_f32_e32 v181, v181, v190
	v_mul_f32_e32 v92, v92, v160
	v_mul_f32_e32 v93, v93, v161
	v_mul_f32_e32 v94, v94, v162
	v_mul_f32_e32 v95, v95, v163
	v_mul_f32_e32 v88, v88, v164
	v_mul_f32_e32 v89, v89, v165
	v_mul_f32_e32 v90, v90, v180
	v_mul_f32_e32 v91, v91, v181
	s_waitcnt vmcnt(8)
	v_lshlrev_b32_e32 v160, 16, v200
	v_and_b32_e32 v161, 0xffff0000, v200
	v_lshlrev_b32_e32 v162, 16, v201
	v_and_b32_e32 v163, 0xffff0000, v201
	v_lshlrev_b32_e32 v164, 16, v202
	v_and_b32_e32 v165, 0xffff0000, v202
	v_lshlrev_b32_e32 v180, 16, v203
	v_and_b32_e32 v181, 0xffff0000, v203
	v_lshlrev_b32_e32 v183, 16, v216
	v_and_b32_e32 v184, 0xffff0000, v216
	v_lshlrev_b32_e32 v185, 16, v217
	v_and_b32_e32 v186, 0xffff0000, v217
	v_lshlrev_b32_e32 v187, 16, v218
	v_and_b32_e32 v188, 0xffff0000, v218
	v_lshlrev_b32_e32 v189, 16, v219
	v_and_b32_e32 v190, 0xffff0000, v219
	global_load_dwordx4 v[200:203], v177, s[46:47] offset:256
	global_load_dwordx4 v[216:219], v177, s[48:49] offset:256
	v_max_f32_e32 v183, v183, v147
	v_max_f32_e32 v184, v184, v147
	v_max_f32_e32 v185, v185, v147
	v_max_f32_e32 v186, v186, v147
	v_max_f32_e32 v187, v187, v147
	v_max_f32_e32 v188, v188, v147
	v_max_f32_e32 v189, v189, v147
	v_max_f32_e32 v190, v190, v147
	v_rcp_f32_e32 v183, v183
	v_rcp_f32_e32 v184, v184
	v_rcp_f32_e32 v185, v185
	v_rcp_f32_e32 v186, v186
	v_rcp_f32_e32 v187, v187
	v_rcp_f32_e32 v188, v188
	v_rcp_f32_e32 v189, v189
	v_rcp_f32_e32 v190, v190
	v_mul_f32_e32 v160, v160, v183
	v_mul_f32_e32 v161, v161, v184
	v_mul_f32_e32 v162, v162, v185
	v_mul_f32_e32 v163, v163, v186
	v_mul_f32_e32 v164, v164, v187
	v_mul_f32_e32 v165, v165, v188
	v_mul_f32_e32 v180, v180, v189
	v_mul_f32_e32 v181, v181, v190
	v_mul_f32_e32 v84, v84, v160
	v_mul_f32_e32 v85, v85, v161
	v_mul_f32_e32 v86, v86, v162
	v_mul_f32_e32 v87, v87, v163
	v_mul_f32_e32 v80, v80, v164
	v_mul_f32_e32 v81, v81, v165
	v_mul_f32_e32 v82, v82, v180
	v_mul_f32_e32 v83, v83, v181
	s_waitcnt vmcnt(8)
	v_lshlrev_b32_e32 v160, 16, v220
	v_and_b32_e32 v161, 0xffff0000, v220
	v_lshlrev_b32_e32 v162, 16, v221
	v_and_b32_e32 v163, 0xffff0000, v221
	v_lshlrev_b32_e32 v164, 16, v222
	v_and_b32_e32 v165, 0xffff0000, v222
	v_lshlrev_b32_e32 v180, 16, v223
	v_and_b32_e32 v181, 0xffff0000, v223
	v_lshlrev_b32_e32 v183, 16, v224
	v_and_b32_e32 v184, 0xffff0000, v224
	v_lshlrev_b32_e32 v185, 16, v225
	v_and_b32_e32 v186, 0xffff0000, v225
	v_lshlrev_b32_e32 v187, 16, v226
	v_and_b32_e32 v188, 0xffff0000, v226
	v_lshlrev_b32_e32 v189, 16, v227
	v_and_b32_e32 v190, 0xffff0000, v227
	global_load_dwordx4 v[220:223], v178, s[46:47]
	global_load_dwordx4 v[224:227], v178, s[48:49]
	v_max_f32_e32 v183, v183, v147
	v_max_f32_e32 v184, v184, v147
	v_max_f32_e32 v185, v185, v147
	v_max_f32_e32 v186, v186, v147
	v_max_f32_e32 v187, v187, v147
	v_max_f32_e32 v188, v188, v147
	v_max_f32_e32 v189, v189, v147
	v_max_f32_e32 v190, v190, v147
	v_rcp_f32_e32 v183, v183
	v_rcp_f32_e32 v184, v184
	v_rcp_f32_e32 v185, v185
	v_rcp_f32_e32 v186, v186
	v_rcp_f32_e32 v187, v187
	v_rcp_f32_e32 v188, v188
	v_rcp_f32_e32 v189, v189
	v_rcp_f32_e32 v190, v190
	v_mul_f32_e32 v160, v160, v183
	v_mul_f32_e32 v161, v161, v184
	v_mul_f32_e32 v162, v162, v185
	v_mul_f32_e32 v163, v163, v186
	v_mul_f32_e32 v164, v164, v187
	v_mul_f32_e32 v165, v165, v188
	v_mul_f32_e32 v180, v180, v189
	v_mul_f32_e32 v181, v181, v190
	v_mul_f32_e32 v76, v76, v160
	v_mul_f32_e32 v77, v77, v161
	v_mul_f32_e32 v78, v78, v162
	v_mul_f32_e32 v79, v79, v163
	v_mul_f32_e32 v72, v72, v164
	v_mul_f32_e32 v73, v73, v165
	v_mul_f32_e32 v74, v74, v180
	v_mul_f32_e32 v75, v75, v181
	s_waitcnt vmcnt(8)
	v_lshlrev_b32_e32 v160, 16, v228
	v_and_b32_e32 v161, 0xffff0000, v228
	v_lshlrev_b32_e32 v162, 16, v229
	v_and_b32_e32 v163, 0xffff0000, v229
	v_lshlrev_b32_e32 v164, 16, v230
	v_and_b32_e32 v165, 0xffff0000, v230
	v_lshlrev_b32_e32 v180, 16, v231
	v_and_b32_e32 v181, 0xffff0000, v231
	v_lshlrev_b32_e32 v183, 16, v232
	v_and_b32_e32 v184, 0xffff0000, v232
	v_lshlrev_b32_e32 v185, 16, v233
	v_and_b32_e32 v186, 0xffff0000, v233
	v_lshlrev_b32_e32 v187, 16, v234
	v_and_b32_e32 v188, 0xffff0000, v234
	v_lshlrev_b32_e32 v189, 16, v235
	v_and_b32_e32 v190, 0xffff0000, v235
	global_load_dwordx4 v[228:231], v178, s[46:47] offset:256
	global_load_dwordx4 v[232:235], v178, s[48:49] offset:256
	v_max_f32_e32 v183, v183, v147
	v_max_f32_e32 v184, v184, v147
	v_max_f32_e32 v185, v185, v147
	v_max_f32_e32 v186, v186, v147
	v_max_f32_e32 v187, v187, v147
	v_max_f32_e32 v188, v188, v147
	v_max_f32_e32 v189, v189, v147
	v_max_f32_e32 v190, v190, v147
	v_rcp_f32_e32 v183, v183
	v_rcp_f32_e32 v184, v184
	v_rcp_f32_e32 v185, v185
	v_rcp_f32_e32 v186, v186
	v_rcp_f32_e32 v187, v187
	v_rcp_f32_e32 v188, v188
	v_rcp_f32_e32 v189, v189
	v_rcp_f32_e32 v190, v190
	v_mul_f32_e32 v160, v160, v183
	v_mul_f32_e32 v161, v161, v184
	v_mul_f32_e32 v162, v162, v185
	v_mul_f32_e32 v163, v163, v186
	v_mul_f32_e32 v164, v164, v187
	v_mul_f32_e32 v165, v165, v188
	v_mul_f32_e32 v180, v180, v189
	v_mul_f32_e32 v181, v181, v190
	v_mul_f32_e32 v68, v68, v160
	v_mul_f32_e32 v69, v69, v161
	v_mul_f32_e32 v70, v70, v162
	v_mul_f32_e32 v71, v71, v163
	v_mul_f32_e32 v64, v64, v164
	v_mul_f32_e32 v65, v65, v165
	v_mul_f32_e32 v66, v66, v180
	v_mul_f32_e32 v67, v67, v181
	s_waitcnt vmcnt(8)
	v_lshlrev_b32_e32 v160, 16, v236
	v_and_b32_e32 v161, 0xffff0000, v236
	v_lshlrev_b32_e32 v162, 16, v237
	v_and_b32_e32 v163, 0xffff0000, v237
	v_lshlrev_b32_e32 v164, 16, v238
	v_and_b32_e32 v165, 0xffff0000, v238
	v_lshlrev_b32_e32 v180, 16, v239
	v_and_b32_e32 v181, 0xffff0000, v239
	v_lshlrev_b32_e32 v183, 16, v240
	v_and_b32_e32 v184, 0xffff0000, v240
	v_lshlrev_b32_e32 v185, 16, v241
	v_and_b32_e32 v186, 0xffff0000, v241
	v_lshlrev_b32_e32 v187, 16, v242
	v_and_b32_e32 v188, 0xffff0000, v242
	v_lshlrev_b32_e32 v189, 16, v243
	v_and_b32_e32 v190, 0xffff0000, v243
	global_load_dwordx4 v[236:239], v179, s[46:47]
	global_load_dwordx4 v[240:243], v179, s[48:49]
	v_max_f32_e32 v183, v183, v147
	v_max_f32_e32 v184, v184, v147
	v_max_f32_e32 v185, v185, v147
	v_max_f32_e32 v186, v186, v147
	v_max_f32_e32 v187, v187, v147
	v_max_f32_e32 v188, v188, v147
	v_max_f32_e32 v189, v189, v147
	v_max_f32_e32 v190, v190, v147
	v_rcp_f32_e32 v183, v183
	v_rcp_f32_e32 v184, v184
	v_rcp_f32_e32 v185, v185
	v_rcp_f32_e32 v186, v186
	v_rcp_f32_e32 v187, v187
	v_rcp_f32_e32 v188, v188
	v_rcp_f32_e32 v189, v189
	v_rcp_f32_e32 v190, v190
	v_mul_f32_e32 v160, v160, v183
	v_mul_f32_e32 v161, v161, v184
	v_mul_f32_e32 v162, v162, v185
	v_mul_f32_e32 v163, v163, v186
	v_mul_f32_e32 v164, v164, v187
	v_mul_f32_e32 v165, v165, v188
	v_mul_f32_e32 v180, v180, v189
	v_mul_f32_e32 v181, v181, v190
	v_mul_f32_e32 v60, v60, v160
	v_mul_f32_e32 v61, v61, v161
	v_mul_f32_e32 v62, v62, v162
	v_mul_f32_e32 v63, v63, v163
	v_mul_f32_e32 v56, v56, v164
	v_mul_f32_e32 v57, v57, v165
	v_mul_f32_e32 v58, v58, v180
	v_mul_f32_e32 v59, v59, v181
	s_waitcnt vmcnt(8)
	v_lshlrev_b32_e32 v160, 16, v192
	v_and_b32_e32 v161, 0xffff0000, v192
	v_lshlrev_b32_e32 v162, 16, v193
	v_and_b32_e32 v163, 0xffff0000, v193
	v_lshlrev_b32_e32 v164, 16, v194
	v_and_b32_e32 v165, 0xffff0000, v194
	v_lshlrev_b32_e32 v180, 16, v195
	v_and_b32_e32 v181, 0xffff0000, v195
	v_lshlrev_b32_e32 v183, 16, v196
	v_and_b32_e32 v184, 0xffff0000, v196
	v_lshlrev_b32_e32 v185, 16, v197
	v_and_b32_e32 v186, 0xffff0000, v197
	v_lshlrev_b32_e32 v187, 16, v198
	v_and_b32_e32 v188, 0xffff0000, v198
	v_lshlrev_b32_e32 v189, 16, v199
	v_and_b32_e32 v190, 0xffff0000, v199
	global_load_dwordx4 v[192:195], v179, s[46:47] offset:256
	global_load_dwordx4 v[196:199], v179, s[48:49] offset:256
	v_max_f32_e32 v183, v183, v147
	v_max_f32_e32 v184, v184, v147
	v_max_f32_e32 v185, v185, v147
	v_max_f32_e32 v186, v186, v147
	v_max_f32_e32 v187, v187, v147
	v_max_f32_e32 v188, v188, v147
	v_max_f32_e32 v189, v189, v147
	v_max_f32_e32 v190, v190, v147
	v_rcp_f32_e32 v183, v183
	v_rcp_f32_e32 v184, v184
	v_rcp_f32_e32 v185, v185
	v_rcp_f32_e32 v186, v186
	v_rcp_f32_e32 v187, v187
	v_rcp_f32_e32 v188, v188
	v_rcp_f32_e32 v189, v189
	v_rcp_f32_e32 v190, v190
	v_mul_f32_e32 v160, v160, v183
	v_mul_f32_e32 v161, v161, v184
	v_mul_f32_e32 v162, v162, v185
	v_mul_f32_e32 v163, v163, v186
	v_mul_f32_e32 v164, v164, v187
	v_mul_f32_e32 v165, v165, v188
	v_mul_f32_e32 v180, v180, v189
	v_mul_f32_e32 v181, v181, v190
	v_mul_f32_e32 v52, v52, v160
	v_mul_f32_e32 v53, v53, v161
	v_mul_f32_e32 v54, v54, v162
	v_mul_f32_e32 v55, v55, v163
	v_mul_f32_e32 v48, v48, v164
	v_mul_f32_e32 v49, v49, v165
	v_mul_f32_e32 v50, v50, v180
	v_mul_f32_e32 v51, v51, v181
	s_waitcnt vmcnt(8)
	v_lshlrev_b32_e32 v160, 16, v200
	v_and_b32_e32 v161, 0xffff0000, v200
	v_lshlrev_b32_e32 v162, 16, v201
	v_and_b32_e32 v163, 0xffff0000, v201
	v_lshlrev_b32_e32 v164, 16, v202
	v_and_b32_e32 v165, 0xffff0000, v202
	v_lshlrev_b32_e32 v180, 16, v203
	v_and_b32_e32 v181, 0xffff0000, v203
	v_lshlrev_b32_e32 v183, 16, v216
	v_and_b32_e32 v184, 0xffff0000, v216
	v_lshlrev_b32_e32 v185, 16, v217
	v_and_b32_e32 v186, 0xffff0000, v217
	v_lshlrev_b32_e32 v187, 16, v218
	v_and_b32_e32 v188, 0xffff0000, v218
	v_lshlrev_b32_e32 v189, 16, v219
	v_and_b32_e32 v190, 0xffff0000, v219
	v_max_f32_e32 v183, v183, v147
	v_max_f32_e32 v184, v184, v147
	v_max_f32_e32 v185, v185, v147
	v_max_f32_e32 v186, v186, v147
	v_max_f32_e32 v187, v187, v147
	v_max_f32_e32 v188, v188, v147
	v_max_f32_e32 v189, v189, v147
	v_max_f32_e32 v190, v190, v147
	v_rcp_f32_e32 v183, v183
	v_rcp_f32_e32 v184, v184
	v_rcp_f32_e32 v185, v185
	v_rcp_f32_e32 v186, v186
	v_rcp_f32_e32 v187, v187
	v_rcp_f32_e32 v188, v188
	v_rcp_f32_e32 v189, v189
	v_rcp_f32_e32 v190, v190
	v_mul_f32_e32 v160, v160, v183
	v_mul_f32_e32 v161, v161, v184
	v_mul_f32_e32 v162, v162, v185
	v_mul_f32_e32 v163, v163, v186
	v_mul_f32_e32 v164, v164, v187
	v_mul_f32_e32 v165, v165, v188
	v_mul_f32_e32 v180, v180, v189
	v_mul_f32_e32 v181, v181, v190
	v_mul_f32_e32 v44, v44, v160
	v_mul_f32_e32 v45, v45, v161
	v_mul_f32_e32 v46, v46, v162
	v_mul_f32_e32 v47, v47, v163
	v_mul_f32_e32 v40, v40, v164
	v_mul_f32_e32 v41, v41, v165
	v_mul_f32_e32 v42, v42, v180
	v_mul_f32_e32 v43, v43, v181
	s_waitcnt vmcnt(6)
	v_lshlrev_b32_e32 v160, 16, v220
	v_and_b32_e32 v161, 0xffff0000, v220
	v_lshlrev_b32_e32 v162, 16, v221
	v_and_b32_e32 v163, 0xffff0000, v221
	v_lshlrev_b32_e32 v164, 16, v222
	v_and_b32_e32 v165, 0xffff0000, v222
	v_lshlrev_b32_e32 v180, 16, v223
	v_and_b32_e32 v181, 0xffff0000, v223
	v_lshlrev_b32_e32 v183, 16, v224
	v_and_b32_e32 v184, 0xffff0000, v224
	v_lshlrev_b32_e32 v185, 16, v225
	v_and_b32_e32 v186, 0xffff0000, v225
	v_lshlrev_b32_e32 v187, 16, v226
	v_and_b32_e32 v188, 0xffff0000, v226
	v_lshlrev_b32_e32 v189, 16, v227
	v_and_b32_e32 v190, 0xffff0000, v227
	v_max_f32_e32 v183, v183, v147
	v_max_f32_e32 v184, v184, v147
	v_max_f32_e32 v185, v185, v147
	v_max_f32_e32 v186, v186, v147
	v_max_f32_e32 v187, v187, v147
	v_max_f32_e32 v188, v188, v147
	v_max_f32_e32 v189, v189, v147
	v_max_f32_e32 v190, v190, v147
	v_rcp_f32_e32 v183, v183
	v_rcp_f32_e32 v184, v184
	v_rcp_f32_e32 v185, v185
	v_rcp_f32_e32 v186, v186
	v_rcp_f32_e32 v187, v187
	v_rcp_f32_e32 v188, v188
	v_rcp_f32_e32 v189, v189
	v_rcp_f32_e32 v190, v190
	v_mul_f32_e32 v160, v160, v183
	v_mul_f32_e32 v161, v161, v184
	v_mul_f32_e32 v162, v162, v185
	v_mul_f32_e32 v163, v163, v186
	v_mul_f32_e32 v164, v164, v187
	v_mul_f32_e32 v165, v165, v188
	v_mul_f32_e32 v180, v180, v189
	v_mul_f32_e32 v181, v181, v190
	v_mul_f32_e32 v36, v36, v160
	v_mul_f32_e32 v37, v37, v161
	v_mul_f32_e32 v38, v38, v162
	v_mul_f32_e32 v39, v39, v163
	v_mul_f32_e32 v32, v32, v164
	v_mul_f32_e32 v33, v33, v165
	v_mul_f32_e32 v34, v34, v180
	v_mul_f32_e32 v35, v35, v181
	s_waitcnt vmcnt(4)
	v_lshlrev_b32_e32 v160, 16, v228
	v_and_b32_e32 v161, 0xffff0000, v228
	v_lshlrev_b32_e32 v162, 16, v229
	v_and_b32_e32 v163, 0xffff0000, v229
	v_lshlrev_b32_e32 v164, 16, v230
	v_and_b32_e32 v165, 0xffff0000, v230
	v_lshlrev_b32_e32 v180, 16, v231
	v_and_b32_e32 v181, 0xffff0000, v231
	v_lshlrev_b32_e32 v183, 16, v232
	v_and_b32_e32 v184, 0xffff0000, v232
	v_lshlrev_b32_e32 v185, 16, v233
	v_and_b32_e32 v186, 0xffff0000, v233
	v_lshlrev_b32_e32 v187, 16, v234
	v_and_b32_e32 v188, 0xffff0000, v234
	v_lshlrev_b32_e32 v189, 16, v235
	v_and_b32_e32 v190, 0xffff0000, v235
	v_max_f32_e32 v183, v183, v147
	v_max_f32_e32 v184, v184, v147
	v_max_f32_e32 v185, v185, v147
	v_max_f32_e32 v186, v186, v147
	v_max_f32_e32 v187, v187, v147
	v_max_f32_e32 v188, v188, v147
	v_max_f32_e32 v189, v189, v147
	v_max_f32_e32 v190, v190, v147
	v_rcp_f32_e32 v183, v183
	v_rcp_f32_e32 v184, v184
	v_rcp_f32_e32 v185, v185
	v_rcp_f32_e32 v186, v186
	v_rcp_f32_e32 v187, v187
	v_rcp_f32_e32 v188, v188
	v_rcp_f32_e32 v189, v189
	v_rcp_f32_e32 v190, v190
	v_mul_f32_e32 v160, v160, v183
	v_mul_f32_e32 v161, v161, v184
	v_mul_f32_e32 v162, v162, v185
	v_mul_f32_e32 v163, v163, v186
	v_mul_f32_e32 v164, v164, v187
	v_mul_f32_e32 v165, v165, v188
	v_mul_f32_e32 v180, v180, v189
	v_mul_f32_e32 v181, v181, v190
	v_mul_f32_e32 v28, v28, v160
	v_mul_f32_e32 v29, v29, v161
	v_mul_f32_e32 v30, v30, v162
	v_mul_f32_e32 v31, v31, v163
	v_mul_f32_e32 v24, v24, v164
	v_mul_f32_e32 v25, v25, v165
	v_mul_f32_e32 v26, v26, v180
	v_mul_f32_e32 v27, v27, v181
	s_waitcnt vmcnt(2)
	v_lshlrev_b32_e32 v160, 16, v236
	v_and_b32_e32 v161, 0xffff0000, v236
	v_lshlrev_b32_e32 v162, 16, v237
	v_and_b32_e32 v163, 0xffff0000, v237
	v_lshlrev_b32_e32 v164, 16, v238
	v_and_b32_e32 v165, 0xffff0000, v238
	v_lshlrev_b32_e32 v180, 16, v239
	v_and_b32_e32 v181, 0xffff0000, v239
	v_lshlrev_b32_e32 v183, 16, v240
	v_and_b32_e32 v184, 0xffff0000, v240
	v_lshlrev_b32_e32 v185, 16, v241
	v_and_b32_e32 v186, 0xffff0000, v241
	v_lshlrev_b32_e32 v187, 16, v242
	v_and_b32_e32 v188, 0xffff0000, v242
	v_lshlrev_b32_e32 v189, 16, v243
	v_and_b32_e32 v190, 0xffff0000, v243
	v_max_f32_e32 v183, v183, v147
	v_max_f32_e32 v184, v184, v147
	v_max_f32_e32 v185, v185, v147
	v_max_f32_e32 v186, v186, v147
	v_max_f32_e32 v187, v187, v147
	v_max_f32_e32 v188, v188, v147
	v_max_f32_e32 v189, v189, v147
	v_max_f32_e32 v190, v190, v147
	v_rcp_f32_e32 v183, v183
	v_rcp_f32_e32 v184, v184
	v_rcp_f32_e32 v185, v185
	v_rcp_f32_e32 v186, v186
	v_rcp_f32_e32 v187, v187
	v_rcp_f32_e32 v188, v188
	v_rcp_f32_e32 v189, v189
	v_rcp_f32_e32 v190, v190
	v_mul_f32_e32 v160, v160, v183
	v_mul_f32_e32 v161, v161, v184
	v_mul_f32_e32 v162, v162, v185
	v_mul_f32_e32 v163, v163, v186
	v_mul_f32_e32 v164, v164, v187
	v_mul_f32_e32 v165, v165, v188
	v_mul_f32_e32 v180, v180, v189
	v_mul_f32_e32 v181, v181, v190
	v_mul_f32_e32 v20, v20, v160
	v_mul_f32_e32 v21, v21, v161
	v_mul_f32_e32 v22, v22, v162
	v_mul_f32_e32 v23, v23, v163
	v_mul_f32_e32 v16, v16, v164
	v_mul_f32_e32 v17, v17, v165
	v_mul_f32_e32 v18, v18, v180
	v_mul_f32_e32 v19, v19, v181
	s_waitcnt vmcnt(0)
	v_lshlrev_b32_e32 v160, 16, v192
	v_and_b32_e32 v161, 0xffff0000, v192
	v_lshlrev_b32_e32 v162, 16, v193
	v_and_b32_e32 v163, 0xffff0000, v193
	v_lshlrev_b32_e32 v164, 16, v194
	v_and_b32_e32 v165, 0xffff0000, v194
	v_lshlrev_b32_e32 v180, 16, v195
	v_and_b32_e32 v181, 0xffff0000, v195
	v_lshlrev_b32_e32 v183, 16, v196
	v_and_b32_e32 v184, 0xffff0000, v196
	v_lshlrev_b32_e32 v185, 16, v197
	v_and_b32_e32 v186, 0xffff0000, v197
	v_lshlrev_b32_e32 v187, 16, v198
	v_and_b32_e32 v188, 0xffff0000, v198
	v_lshlrev_b32_e32 v189, 16, v199
	v_and_b32_e32 v190, 0xffff0000, v199
	v_max_f32_e32 v183, v183, v147
	v_max_f32_e32 v184, v184, v147
	v_max_f32_e32 v185, v185, v147
	v_max_f32_e32 v186, v186, v147
	v_max_f32_e32 v187, v187, v147
	v_max_f32_e32 v188, v188, v147
	v_max_f32_e32 v189, v189, v147
	v_max_f32_e32 v190, v190, v147
	v_rcp_f32_e32 v183, v183
	v_rcp_f32_e32 v184, v184
	v_rcp_f32_e32 v185, v185
	v_rcp_f32_e32 v186, v186
	v_rcp_f32_e32 v187, v187
	v_rcp_f32_e32 v188, v188
	v_rcp_f32_e32 v189, v189
	v_rcp_f32_e32 v190, v190
	v_mul_f32_e32 v160, v160, v183
	v_mul_f32_e32 v161, v161, v184
	v_mul_f32_e32 v162, v162, v185
	v_mul_f32_e32 v163, v163, v186
	v_mul_f32_e32 v164, v164, v187
	v_mul_f32_e32 v165, v165, v188
	v_mul_f32_e32 v180, v180, v189
	v_mul_f32_e32 v181, v181, v190
	v_mul_f32_e32 v12, v12, v160
	v_mul_f32_e32 v13, v13, v161
	v_mul_f32_e32 v14, v14, v162
	v_mul_f32_e32 v15, v15, v163
	v_mul_f32_e32 v8, v8, v164
	v_mul_f32_e32 v9, v9, v165
	v_mul_f32_e32 v10, v10, v180
	v_mul_f32_e32 v11, v11, v181
	v_mov_b32_e32 v214, v8
	v_mov_b32_e32 v215, v9
	v_mov_b32_e32 v216, v10
	v_mov_b32_e32 v217, v11
	v_mov_b32_e32 v218, v12
	v_mov_b32_e32 v219, v13
	v_mov_b32_e32 v220, v14
	v_mov_b32_e32 v221, v15
	v_mov_b32_e32 v222, v16
	v_mov_b32_e32 v223, v17
	v_mov_b32_e32 v224, v18
	v_mov_b32_e32 v225, v19
	v_mov_b32_e32 v226, v20
	v_mov_b32_e32 v227, v21
	v_mov_b32_e32 v228, v22
	v_mov_b32_e32 v229, v23
	v_mov_b32_e32 v230, v24
	v_mov_b32_e32 v231, v25
	v_mov_b32_e32 v232, v26
	s_mov_b64 s[48:49], 0x4000
	s_mov_b64 s[46:47], 0x8000
	s_mov_b32 s9, 0x58000
	s_mov_b64 s[16:17], -1
	s_andn2_b64 vcc, exec, s[42:43]
	s_cbranch_vccnz .LBB0_835
	s_andn2_b64 vcc, exec, s[0:1]
	s_cbranch_vccnz .LBB0_834
	s_barrier
	s_branch .LBB0_834

.LBB0_862:
	s_ashr_i32 s11, s10, 31
	s_lshl_b64 s[12:13], s[10:11], 18
	s_add_u32 s12, s22, s12
	s_addc_u32 s13, s23, s13
	s_and_b64 s[14:15], s[44:45], exec
	s_cselect_b32 s11, s13, s19
	s_cselect_b32 s38, s12, s18
	s_ashr_i32 s9, s8, 31
	s_lshl_b64 s[14:15], s[8:9], 18
	s_add_u32 s14, s24, s14
	s_addc_u32 s15, s25, s15
	s_and_b64 s[20:21], s[44:45], exec
	s_cselect_b32 s9, s15, s17
	s_cselect_b32 s39, s14, s16
	s_add_u32 s40, s16, 0x100
	s_addc_u32 s41, s17, 0
	s_add_u32 s16, s18, 0x20080
	s_addc_u32 s17, s19, 0
	s_mov_b32 s46, -2
	v_mov_b32_e32 v8, v214
	v_mov_b32_e32 v9, v215
	v_mov_b32_e32 v10, v216
	v_mov_b32_e32 v11, v217
	v_mov_b32_e32 v12, v218
	v_mov_b32_e32 v13, v219
	v_mov_b32_e32 v14, v220
	v_mov_b32_e32 v15, v221
	v_mov_b32_e32 v16, v222
	v_mov_b32_e32 v17, v223
	v_mov_b32_e32 v18, v224
	v_mov_b32_e32 v19, v225
	v_mov_b32_e32 v20, v226
	v_mov_b32_e32 v21, v227
	v_mov_b32_e32 v22, v228
	v_mov_b32_e32 v23, v229
	v_mov_b32_e32 v24, v230
	v_mov_b32_e32 v25, v231
	v_mov_b32_e32 v26, v232

.LBB0_866:
	v_and_b32_e32 v160, 63, v206
	v_lshrrev_b32_e32 v161, 6, v206
	v_and_b32_e32 v162, 15, v160
	v_readfirstlane_b32 s16, v161
	v_lshrrev_b32_e32 v163, 4, v160
	s_nop 3
	s_and_b32 s17, s16, 3
	s_lshl_b32 s17, s17, 5
	s_lshl_b32 s9, s33, 8
	s_add_i32 s17, s17, s9
	v_lshl_add_u32 v164, v163, 3, s17
	s_lshr_b32 s17, s16, 2
	s_lshl_b32 s17, s17, 6
	s_lshl_b32 s9, s37, 8
	s_add_i32 s9, s9, s17
	v_add_u32_e32 v165, s9, v162
	v_lshlrev_b32_e32 v146, 11, v165
	v_lshl_add_u32 v146, v164, 1, v146
	s_add_u32 s46, s70, 0x8c00000
	s_addc_u32 s47, s71, 0
	s_add_u32 s48, s70, 0x17800000
	s_addc_u32 s49, s71, 0
	v_mov_b32_e32 v147, 0x21800000
	v_mov_b32_e32 v172, v146
	v_add_u32_e32 v173, 0x8000, v146
	v_add_u32_e32 v174, 0x10000, v146
	v_add_u32_e32 v175, 0x18000, v146
	v_add_u32_e32 v176, 0x40000, v146
	v_add_u32_e32 v177, 0x48000, v146
	v_add_u32_e32 v178, 0x50000, v146
	v_add_u32_e32 v179, 0x58000, v146
	global_load_dwordx4 v[192:195], v172, s[46:47]
	global_load_dwordx4 v[196:199], v172, s[48:49]
	global_load_dwordx4 v[200:203], v172, s[46:47] offset:256
	global_load_dwordx4 v[216:219], v172, s[48:49] offset:256
	global_load_dwordx4 v[220:223], v173, s[46:47]
	global_load_dwordx4 v[224:227], v173, s[48:49]
	global_load_dwordx4 v[228:231], v173, s[46:47] offset:256
	global_load_dwordx4 v[232:235], v173, s[48:49] offset:256
	global_load_dwordx4 v[236:239], v174, s[46:47]
	global_load_dwordx4 v[240:243], v174, s[48:49]
	s_waitcnt vmcnt(8)
	v_lshlrev_b32_e32 v160, 16, v192
	v_and_b32_e32 v161, 0xffff0000, v192
	v_lshlrev_b32_e32 v162, 16, v193
	v_and_b32_e32 v163, 0xffff0000, v193
	v_lshlrev_b32_e32 v164, 16, v194
	v_and_b32_e32 v165, 0xffff0000, v194
	v_lshlrev_b32_e32 v180, 16, v195
	v_and_b32_e32 v181, 0xffff0000, v195
	v_lshlrev_b32_e32 v183, 16, v196
	v_and_b32_e32 v184, 0xffff0000, v196
	v_lshlrev_b32_e32 v185, 16, v197
	v_and_b32_e32 v186, 0xffff0000, v197
	v_lshlrev_b32_e32 v187, 16, v198
	v_and_b32_e32 v188, 0xffff0000, v198
	v_lshlrev_b32_e32 v189, 16, v199
	v_and_b32_e32 v190, 0xffff0000, v199
	global_load_dwordx4 v[192:195], v174, s[46:47] offset:256
	global_load_dwordx4 v[196:199], v174, s[48:49] offset:256
	v_max_f32_e32 v160, v160, v147
	v_max_f32_e32 v161, v161, v147
	v_max_f32_e32 v162, v162, v147
	v_max_f32_e32 v163, v163, v147
	v_max_f32_e32 v164, v164, v147
	v_max_f32_e32 v165, v165, v147
	v_max_f32_e32 v180, v180, v147
	v_max_f32_e32 v181, v181, v147
	v_max_f32_e32 v183, v183, v147
	v_max_f32_e32 v184, v184, v147
	v_max_f32_e32 v185, v185, v147
	v_max_f32_e32 v186, v186, v147
	v_max_f32_e32 v187, v187, v147
	v_max_f32_e32 v188, v188, v147
	v_max_f32_e32 v189, v189, v147
	v_max_f32_e32 v190, v190, v147
	v_rcp_f32_e32 v183, v183
	v_rcp_f32_e32 v184, v184
	v_rcp_f32_e32 v185, v185
	v_rcp_f32_e32 v186, v186
	v_rcp_f32_e32 v187, v187
	v_rcp_f32_e32 v188, v188
	v_rcp_f32_e32 v189, v189
	v_rcp_f32_e32 v190, v190
	v_mul_f32_e32 v160, v160, v183
	v_mul_f32_e32 v161, v161, v184
	v_mul_f32_e32 v162, v162, v185
	v_mul_f32_e32 v163, v163, v186
	v_mul_f32_e32 v164, v164, v187
	v_mul_f32_e32 v165, v165, v188
	v_mul_f32_e32 v180, v180, v189
	v_mul_f32_e32 v181, v181, v190
	v_mul_f32_e32 v132, v132, v160
	v_mul_f32_e32 v133, v133, v161
	v_mul_f32_e32 v134, v134, v162
	v_mul_f32_e32 v135, v135, v163
	v_mul_f32_e32 v128, v128, v164
	v_mul_f32_e32 v129, v129, v165
	v_mul_f32_e32 v130, v130, v180
	v_mul_f32_e32 v131, v131, v181
	s_waitcnt vmcnt(8)
	v_lshlrev_b32_e32 v160, 16, v200
	v_and_b32_e32 v161, 0xffff0000, v200
	v_lshlrev_b32_e32 v162, 16, v201
	v_and_b32_e32 v163, 0xffff0000, v201
	v_lshlrev_b32_e32 v164, 16, v202
	v_and_b32_e32 v165, 0xffff0000, v202
	v_lshlrev_b32_e32 v180, 16, v203
	v_and_b32_e32 v181, 0xffff0000, v203
	v_lshlrev_b32_e32 v183, 16, v216
	v_and_b32_e32 v184, 0xffff0000, v216
	v_lshlrev_b32_e32 v185, 16, v217
	v_and_b32_e32 v186, 0xffff0000, v217
	v_lshlrev_b32_e32 v187, 16, v218
	v_and_b32_e32 v188, 0xffff0000, v218
	v_lshlrev_b32_e32 v189, 16, v219
	v_and_b32_e32 v190, 0xffff0000, v219
	global_load_dwordx4 v[200:203], v175, s[46:47]
	global_load_dwordx4 v[216:219], v175, s[48:49]
	v_max_f32_e32 v160, v160, v147
	v_max_f32_e32 v161, v161, v147
	v_max_f32_e32 v162, v162, v147
	v_max_f32_e32 v163, v163, v147
	v_max_f32_e32 v164, v164, v147
	v_max_f32_e32 v165, v165, v147
	v_max_f32_e32 v180, v180, v147
	v_max_f32_e32 v181, v181, v147
	v_max_f32_e32 v183, v183, v147
	v_max_f32_e32 v184, v184, v147
	v_max_f32_e32 v185, v185, v147
	v_max_f32_e32 v186, v186, v147
	v_max_f32_e32 v187, v187, v147
	v_max_f32_e32 v188, v188, v147
	v_max_f32_e32 v189, v189, v147
	v_max_f32_e32 v190, v190, v147
	v_rcp_f32_e32 v183, v183
	v_rcp_f32_e32 v184, v184
	v_rcp_f32_e32 v185, v185
	v_rcp_f32_e32 v186, v186
	v_rcp_f32_e32 v187, v187
	v_rcp_f32_e32 v188, v188
	v_rcp_f32_e32 v189, v189
	v_rcp_f32_e32 v190, v190
	v_mul_f32_e32 v160, v160, v183
	v_mul_f32_e32 v161, v161, v184
	v_mul_f32_e32 v162, v162, v185
	v_mul_f32_e32 v163, v163, v186
	v_mul_f32_e32 v164, v164, v187
	v_mul_f32_e32 v165, v165, v188
	v_mul_f32_e32 v180, v180, v189
	v_mul_f32_e32 v181, v181, v190
	v_mul_f32_e32 v124, v124, v160
	v_mul_f32_e32 v125, v125, v161
	v_mul_f32_e32 v126, v126, v162
	v_mul_f32_e32 v127, v127, v163
	v_mul_f32_e32 v120, v120, v164
	v_mul_f32_e32 v121, v121, v165
	v_mul_f32_e32 v122, v122, v180
	v_mul_f32_e32 v123, v123, v181
	s_waitcnt vmcnt(8)
	v_lshlrev_b32_e32 v160, 16, v220
	v_and_b32_e32 v161, 0xffff0000, v220
	v_lshlrev_b32_e32 v162, 16, v221
	v_and_b32_e32 v163, 0xffff0000, v221
	v_lshlrev_b32_e32 v164, 16, v222
	v_and_b32_e32 v165, 0xffff0000, v222
	v_lshlrev_b32_e32 v180, 16, v223
	v_and_b32_e32 v181, 0xffff0000, v223
	v_lshlrev_b32_e32 v183, 16, v224
	v_and_b32_e32 v184, 0xffff0000, v224
	v_lshlrev_b32_e32 v185, 16, v225
	v_and_b32_e32 v186, 0xffff0000, v225
	v_lshlrev_b32_e32 v187, 16, v226
	v_and_b32_e32 v188, 0xffff0000, v226
	v_lshlrev_b32_e32 v189, 16, v227
	v_and_b32_e32 v190, 0xffff0000, v227
	global_load_dwordx4 v[220:223], v175, s[46:47] offset:256
	global_load_dwordx4 v[224:227], v175, s[48:49] offset:256
	v_max_f32_e32 v160, v160, v147
	v_max_f32_e32 v161, v161, v147
	v_max_f32_e32 v162, v162, v147
	v_max_f32_e32 v163, v163, v147
	v_max_f32_e32 v164, v164, v147
	v_max_f32_e32 v165, v165, v147
	v_max_f32_e32 v180, v180, v147
	v_max_f32_e32 v181, v181, v147
	v_max_f32_e32 v183, v183, v147
	v_max_f32_e32 v184, v184, v147
	v_max_f32_e32 v185, v185, v147
	v_max_f32_e32 v186, v186, v147
	v_max_f32_e32 v187, v187, v147
	v_max_f32_e32 v188, v188, v147
	v_max_f32_e32 v189, v189, v147
	v_max_f32_e32 v190, v190, v147
	v_rcp_f32_e32 v183, v183
	v_rcp_f32_e32 v184, v184
	v_rcp_f32_e32 v185, v185
	v_rcp_f32_e32 v186, v186
	v_rcp_f32_e32 v187, v187
	v_rcp_f32_e32 v188, v188
	v_rcp_f32_e32 v189, v189
	v_rcp_f32_e32 v190, v190
	v_mul_f32_e32 v160, v160, v183
	v_mul_f32_e32 v161, v161, v184
	v_mul_f32_e32 v162, v162, v185
	v_mul_f32_e32 v163, v163, v186
	v_mul_f32_e32 v164, v164, v187
	v_mul_f32_e32 v165, v165, v188
	v_mul_f32_e32 v180, v180, v189
	v_mul_f32_e32 v181, v181, v190
	v_mul_f32_e32 v116, v116, v160
	v_mul_f32_e32 v117, v117, v161
	v_mul_f32_e32 v118, v118, v162
	v_mul_f32_e32 v119, v119, v163
	v_mul_f32_e32 v112, v112, v164
	v_mul_f32_e32 v113, v113, v165
	v_mul_f32_e32 v114, v114, v180
	v_mul_f32_e32 v115, v115, v181
	s_waitcnt vmcnt(8)
	v_lshlrev_b32_e32 v160, 16, v228
	v_and_b32_e32 v161, 0xffff0000, v228
	v_lshlrev_b32_e32 v162, 16, v229
	v_and_b32_e32 v163, 0xffff0000, v229
	v_lshlrev_b32_e32 v164, 16, v230
	v_and_b32_e32 v165, 0xffff0000, v230
	v_lshlrev_b32_e32 v180, 16, v231
	v_and_b32_e32 v181, 0xffff0000, v231
	v_lshlrev_b32_e32 v183, 16, v232
	v_and_b32_e32 v184, 0xffff0000, v232
	v_lshlrev_b32_e32 v185, 16, v233
	v_and_b32_e32 v186, 0xffff0000, v233
	v_lshlrev_b32_e32 v187, 16, v234
	v_and_b32_e32 v188, 0xffff0000, v234
	v_lshlrev_b32_e32 v189, 16, v235
	v_and_b32_e32 v190, 0xffff0000, v235
	global_load_dwordx4 v[228:231], v176, s[46:47]
	global_load_dwordx4 v[232:235], v176, s[48:49]
	v_max_f32_e32 v160, v160, v147
	v_max_f32_e32 v161, v161, v147
	v_max_f32_e32 v162, v162, v147
	v_max_f32_e32 v163, v163, v147
	v_max_f32_e32 v164, v164, v147
	v_max_f32_e32 v165, v165, v147
	v_max_f32_e32 v180, v180, v147
	v_max_f32_e32 v181, v181, v147
	v_max_f32_e32 v183, v183, v147
	v_max_f32_e32 v184, v184, v147
	v_max_f32_e32 v185, v185, v147
	v_max_f32_e32 v186, v186, v147
	v_max_f32_e32 v187, v187, v147
	v_max_f32_e32 v188, v188, v147
	v_max_f32_e32 v189, v189, v147
	v_max_f32_e32 v190, v190, v147
	v_rcp_f32_e32 v183, v183
	v_rcp_f32_e32 v184, v184
	v_rcp_f32_e32 v185, v185
	v_rcp_f32_e32 v186, v186
	v_rcp_f32_e32 v187, v187
	v_rcp_f32_e32 v188, v188
	v_rcp_f32_e32 v189, v189
	v_rcp_f32_e32 v190, v190
	v_mul_f32_e32 v160, v160, v183
	v_mul_f32_e32 v161, v161, v184
	v_mul_f32_e32 v162, v162, v185
	v_mul_f32_e32 v163, v163, v186
	v_mul_f32_e32 v164, v164, v187
	v_mul_f32_e32 v165, v165, v188
	v_mul_f32_e32 v180, v180, v189
	v_mul_f32_e32 v181, v181, v190
	v_mul_f32_e32 v108, v108, v160
	v_mul_f32_e32 v109, v109, v161
	v_mul_f32_e32 v110, v110, v162
	v_mul_f32_e32 v111, v111, v163
	v_mul_f32_e32 v104, v104, v164
	v_mul_f32_e32 v105, v105, v165
	v_mul_f32_e32 v106, v106, v180
	v_mul_f32_e32 v107, v107, v181
	s_waitcnt vmcnt(8)
	v_lshlrev_b32_e32 v160, 16, v236
	v_and_b32_e32 v161, 0xffff0000, v236
	v_lshlrev_b32_e32 v162, 16, v237
	v_and_b32_e32 v163, 0xffff0000, v237
	v_lshlrev_b32_e32 v164, 16, v238
	v_and_b32_e32 v165, 0xffff0000, v238
	v_lshlrev_b32_e32 v180, 16, v239
	v_and_b32_e32 v181, 0xffff0000, v239
	v_lshlrev_b32_e32 v183, 16, v240
	v_and_b32_e32 v184, 0xffff0000, v240
	v_lshlrev_b32_e32 v185, 16, v241
	v_and_b32_e32 v186, 0xffff0000, v241
	v_lshlrev_b32_e32 v187, 16, v242
	v_and_b32_e32 v188, 0xffff0000, v242
	v_lshlrev_b32_e32 v189, 16, v243
	v_and_b32_e32 v190, 0xffff0000, v243
	global_load_dwordx4 v[236:239], v176, s[46:47] offset:256
	global_load_dwordx4 v[240:243], v176, s[48:49] offset:256
	v_max_f32_e32 v160, v160, v147
	v_max_f32_e32 v161, v161, v147
	v_max_f32_e32 v162, v162, v147
	v_max_f32_e32 v163, v163, v147
	v_max_f32_e32 v164, v164, v147
	v_max_f32_e32 v165, v165, v147
	v_max_f32_e32 v180, v180, v147
	v_max_f32_e32 v181, v181, v147
	v_max_f32_e32 v183, v183, v147
	v_max_f32_e32 v184, v184, v147
	v_max_f32_e32 v185, v185, v147
	v_max_f32_e32 v186, v186, v147
	v_max_f32_e32 v187, v187, v147
	v_max_f32_e32 v188, v188, v147
	v_max_f32_e32 v189, v189, v147
	v_max_f32_e32 v190, v190, v147
	v_rcp_f32_e32 v183, v183
	v_rcp_f32_e32 v184, v184
	v_rcp_f32_e32 v185, v185
	v_rcp_f32_e32 v186, v186
	v_rcp_f32_e32 v187, v187
	v_rcp_f32_e32 v188, v188
	v_rcp_f32_e32 v189, v189
	v_rcp_f32_e32 v190, v190
	v_mul_f32_e32 v160, v160, v183
	v_mul_f32_e32 v161, v161, v184
	v_mul_f32_e32 v162, v162, v185
	v_mul_f32_e32 v163, v163, v186
	v_mul_f32_e32 v164, v164, v187
	v_mul_f32_e32 v165, v165, v188
	v_mul_f32_e32 v180, v180, v189
	v_mul_f32_e32 v181, v181, v190
	v_mul_f32_e32 v100, v100, v160
	v_mul_f32_e32 v101, v101, v161
	v_mul_f32_e32 v102, v102, v162
	v_mul_f32_e32 v103, v103, v163
	v_mul_f32_e32 v96, v96, v164
	v_mul_f32_e32 v97, v97, v165
	v_mul_f32_e32 v98, v98, v180
	v_mul_f32_e32 v99, v99, v181
	s_waitcnt vmcnt(8)
	v_lshlrev_b32_e32 v160, 16, v192
	v_and_b32_e32 v161, 0xffff0000, v192
	v_lshlrev_b32_e32 v162, 16, v193
	v_and_b32_e32 v163, 0xffff0000, v193
	v_lshlrev_b32_e32 v164, 16, v194
	v_and_b32_e32 v165, 0xffff0000, v194
	v_lshlrev_b32_e32 v180, 16, v195
	v_and_b32_e32 v181, 0xffff0000, v195
	v_lshlrev_b32_e32 v183, 16, v196
	v_and_b32_e32 v184, 0xffff0000, v196
	v_lshlrev_b32_e32 v185, 16, v197
	v_and_b32_e32 v186, 0xffff0000, v197
	v_lshlrev_b32_e32 v187, 16, v198
	v_and_b32_e32 v188, 0xffff0000, v198
	v_lshlrev_b32_e32 v189, 16, v199
	v_and_b32_e32 v190, 0xffff0000, v199
	global_load_dwordx4 v[192:195], v177, s[46:47]
	global_load_dwordx4 v[196:199], v177, s[48:49]
	v_max_f32_e32 v160, v160, v147
	v_max_f32_e32 v161, v161, v147
	v_max_f32_e32 v162, v162, v147
	v_max_f32_e32 v163, v163, v147
	v_max_f32_e32 v164, v164, v147
	v_max_f32_e32 v165, v165, v147
	v_max_f32_e32 v180, v180, v147
	v_max_f32_e32 v181, v181, v147
	v_max_f32_e32 v183, v183, v147
	v_max_f32_e32 v184, v184, v147
	v_max_f32_e32 v185, v185, v147
	v_max_f32_e32 v186, v186, v147
	v_max_f32_e32 v187, v187, v147
	v_max_f32_e32 v188, v188, v147
	v_max_f32_e32 v189, v189, v147
	v_max_f32_e32 v190, v190, v147
	v_rcp_f32_e32 v183, v183
	v_rcp_f32_e32 v184, v184
	v_rcp_f32_e32 v185, v185
	v_rcp_f32_e32 v186, v186
	v_rcp_f32_e32 v187, v187
	v_rcp_f32_e32 v188, v188
	v_rcp_f32_e32 v189, v189
	v_rcp_f32_e32 v190, v190
	v_mul_f32_e32 v160, v160, v183
	v_mul_f32_e32 v161, v161, v184
	v_mul_f32_e32 v162, v162, v185
	v_mul_f32_e32 v163, v163, v186
	v_mul_f32_e32 v164, v164, v187
	v_mul_f32_e32 v165, v165, v188
	v_mul_f32_e32 v180, v180, v189
	v_mul_f32_e32 v181, v181, v190
	v_mul_f32_e32 v92, v92, v160
	v_mul_f32_e32 v93, v93, v161
	v_mul_f32_e32 v94, v94, v162
	v_mul_f32_e32 v95, v95, v163
	v_mul_f32_e32 v88, v88, v164
	v_mul_f32_e32 v89, v89, v165
	v_mul_f32_e32 v90, v90, v180
	v_mul_f32_e32 v91, v91, v181
	s_waitcnt vmcnt(8)
	v_lshlrev_b32_e32 v160, 16, v200
	v_and_b32_e32 v161, 0xffff0000, v200
	v_lshlrev_b32_e32 v162, 16, v201
	v_and_b32_e32 v163, 0xffff0000, v201
	v_lshlrev_b32_e32 v164, 16, v202
	v_and_b32_e32 v165, 0xffff0000, v202
	v_lshlrev_b32_e32 v180, 16, v203
	v_and_b32_e32 v181, 0xffff0000, v203
	v_lshlrev_b32_e32 v183, 16, v216
	v_and_b32_e32 v184, 0xffff0000, v216
	v_lshlrev_b32_e32 v185, 16, v217
	v_and_b32_e32 v186, 0xffff0000, v217
	v_lshlrev_b32_e32 v187, 16, v218
	v_and_b32_e32 v188, 0xffff0000, v218
	v_lshlrev_b32_e32 v189, 16, v219
	v_and_b32_e32 v190, 0xffff0000, v219
	global_load_dwordx4 v[200:203], v177, s[46:47] offset:256
	global_load_dwordx4 v[216:219], v177, s[48:49] offset:256
	v_max_f32_e32 v160, v160, v147
	v_max_f32_e32 v161, v161, v147
	v_max_f32_e32 v162, v162, v147
	v_max_f32_e32 v163, v163, v147
	v_max_f32_e32 v164, v164, v147
	v_max_f32_e32 v165, v165, v147
	v_max_f32_e32 v180, v180, v147
	v_max_f32_e32 v181, v181, v147
	v_max_f32_e32 v183, v183, v147
	v_max_f32_e32 v184, v184, v147
	v_max_f32_e32 v185, v185, v147
	v_max_f32_e32 v186, v186, v147
	v_max_f32_e32 v187, v187, v147
	v_max_f32_e32 v188, v188, v147
	v_max_f32_e32 v189, v189, v147
	v_max_f32_e32 v190, v190, v147
	v_rcp_f32_e32 v183, v183
	v_rcp_f32_e32 v184, v184
	v_rcp_f32_e32 v185, v185
	v_rcp_f32_e32 v186, v186
	v_rcp_f32_e32 v187, v187
	v_rcp_f32_e32 v188, v188
	v_rcp_f32_e32 v189, v189
	v_rcp_f32_e32 v190, v190
	v_mul_f32_e32 v160, v160, v183
	v_mul_f32_e32 v161, v161, v184
	v_mul_f32_e32 v162, v162, v185
	v_mul_f32_e32 v163, v163, v186
	v_mul_f32_e32 v164, v164, v187
	v_mul_f32_e32 v165, v165, v188
	v_mul_f32_e32 v180, v180, v189
	v_mul_f32_e32 v181, v181, v190
	v_mul_f32_e32 v84, v84, v160
	v_mul_f32_e32 v85, v85, v161
	v_mul_f32_e32 v86, v86, v162
	v_mul_f32_e32 v87, v87, v163
	v_mul_f32_e32 v80, v80, v164
	v_mul_f32_e32 v81, v81, v165
	v_mul_f32_e32 v82, v82, v180
	v_mul_f32_e32 v83, v83, v181
	s_waitcnt vmcnt(8)
	v_lshlrev_b32_e32 v160, 16, v220
	v_and_b32_e32 v161, 0xffff0000, v220
	v_lshlrev_b32_e32 v162, 16, v221
	v_and_b32_e32 v163, 0xffff0000, v221
	v_lshlrev_b32_e32 v164, 16, v222
	v_and_b32_e32 v165, 0xffff0000, v222
	v_lshlrev_b32_e32 v180, 16, v223
	v_and_b32_e32 v181, 0xffff0000, v223
	v_lshlrev_b32_e32 v183, 16, v224
	v_and_b32_e32 v184, 0xffff0000, v224
	v_lshlrev_b32_e32 v185, 16, v225
	v_and_b32_e32 v186, 0xffff0000, v225
	v_lshlrev_b32_e32 v187, 16, v226
	v_and_b32_e32 v188, 0xffff0000, v226
	v_lshlrev_b32_e32 v189, 16, v227
	v_and_b32_e32 v190, 0xffff0000, v227
	global_load_dwordx4 v[220:223], v178, s[46:47]
	global_load_dwordx4 v[224:227], v178, s[48:49]
	v_max_f32_e32 v160, v160, v147
	v_max_f32_e32 v161, v161, v147
	v_max_f32_e32 v162, v162, v147
	v_max_f32_e32 v163, v163, v147
	v_max_f32_e32 v164, v164, v147
	v_max_f32_e32 v165, v165, v147
	v_max_f32_e32 v180, v180, v147
	v_max_f32_e32 v181, v181, v147
	v_max_f32_e32 v183, v183, v147
	v_max_f32_e32 v184, v184, v147
	v_max_f32_e32 v185, v185, v147
	v_max_f32_e32 v186, v186, v147
	v_max_f32_e32 v187, v187, v147
	v_max_f32_e32 v188, v188, v147
	v_max_f32_e32 v189, v189, v147
	v_max_f32_e32 v190, v190, v147
	v_rcp_f32_e32 v183, v183
	v_rcp_f32_e32 v184, v184
	v_rcp_f32_e32 v185, v185
	v_rcp_f32_e32 v186, v186
	v_rcp_f32_e32 v187, v187
	v_rcp_f32_e32 v188, v188
	v_rcp_f32_e32 v189, v189
	v_rcp_f32_e32 v190, v190
	v_mul_f32_e32 v160, v160, v183
	v_mul_f32_e32 v161, v161, v184
	v_mul_f32_e32 v162, v162, v185
	v_mul_f32_e32 v163, v163, v186
	v_mul_f32_e32 v164, v164, v187
	v_mul_f32_e32 v165, v165, v188
	v_mul_f32_e32 v180, v180, v189
	v_mul_f32_e32 v181, v181, v190
	v_mul_f32_e32 v76, v76, v160
	v_mul_f32_e32 v77, v77, v161
	v_mul_f32_e32 v78, v78, v162
	v_mul_f32_e32 v79, v79, v163
	v_mul_f32_e32 v72, v72, v164
	v_mul_f32_e32 v73, v73, v165
	v_mul_f32_e32 v74, v74, v180
	v_mul_f32_e32 v75, v75, v181
	s_waitcnt vmcnt(8)
	v_lshlrev_b32_e32 v160, 16, v228
	v_and_b32_e32 v161, 0xffff0000, v228
	v_lshlrev_b32_e32 v162, 16, v229
	v_and_b32_e32 v163, 0xffff0000, v229
	v_lshlrev_b32_e32 v164, 16, v230
	v_and_b32_e32 v165, 0xffff0000, v230
	v_lshlrev_b32_e32 v180, 16, v231
	v_and_b32_e32 v181, 0xffff0000, v231
	v_lshlrev_b32_e32 v183, 16, v232
	v_and_b32_e32 v184, 0xffff0000, v232
	v_lshlrev_b32_e32 v185, 16, v233
	v_and_b32_e32 v186, 0xffff0000, v233
	v_lshlrev_b32_e32 v187, 16, v234
	v_and_b32_e32 v188, 0xffff0000, v234
	v_lshlrev_b32_e32 v189, 16, v235
	v_and_b32_e32 v190, 0xffff0000, v235
	global_load_dwordx4 v[228:231], v178, s[46:47] offset:256
	global_load_dwordx4 v[232:235], v178, s[48:49] offset:256
	v_max_f32_e32 v160, v160, v147
	v_max_f32_e32 v161, v161, v147
	v_max_f32_e32 v162, v162, v147
	v_max_f32_e32 v163, v163, v147
	v_max_f32_e32 v164, v164, v147
	v_max_f32_e32 v165, v165, v147
	v_max_f32_e32 v180, v180, v147
	v_max_f32_e32 v181, v181, v147
	v_max_f32_e32 v183, v183, v147
	v_max_f32_e32 v184, v184, v147
	v_max_f32_e32 v185, v185, v147
	v_max_f32_e32 v186, v186, v147
	v_max_f32_e32 v187, v187, v147
	v_max_f32_e32 v188, v188, v147
	v_max_f32_e32 v189, v189, v147
	v_max_f32_e32 v190, v190, v147
	v_rcp_f32_e32 v183, v183
	v_rcp_f32_e32 v184, v184
	v_rcp_f32_e32 v185, v185
	v_rcp_f32_e32 v186, v186
	v_rcp_f32_e32 v187, v187
	v_rcp_f32_e32 v188, v188
	v_rcp_f32_e32 v189, v189
	v_rcp_f32_e32 v190, v190
	v_mul_f32_e32 v160, v160, v183
	v_mul_f32_e32 v161, v161, v184
	v_mul_f32_e32 v162, v162, v185
	v_mul_f32_e32 v163, v163, v186
	v_mul_f32_e32 v164, v164, v187
	v_mul_f32_e32 v165, v165, v188
	v_mul_f32_e32 v180, v180, v189
	v_mul_f32_e32 v181, v181, v190
	v_mul_f32_e32 v68, v68, v160
	v_mul_f32_e32 v69, v69, v161
	v_mul_f32_e32 v70, v70, v162
	v_mul_f32_e32 v71, v71, v163
	v_mul_f32_e32 v64, v64, v164
	v_mul_f32_e32 v65, v65, v165
	v_mul_f32_e32 v66, v66, v180
	v_mul_f32_e32 v67, v67, v181
	s_waitcnt vmcnt(8)
	v_lshlrev_b32_e32 v160, 16, v236
	v_and_b32_e32 v161, 0xffff0000, v236
	v_lshlrev_b32_e32 v162, 16, v237
	v_and_b32_e32 v163, 0xffff0000, v237
	v_lshlrev_b32_e32 v164, 16, v238
	v_and_b32_e32 v165, 0xffff0000, v238
	v_lshlrev_b32_e32 v180, 16, v239
	v_and_b32_e32 v181, 0xffff0000, v239
	v_lshlrev_b32_e32 v183, 16, v240
	v_and_b32_e32 v184, 0xffff0000, v240
	v_lshlrev_b32_e32 v185, 16, v241
	v_and_b32_e32 v186, 0xffff0000, v241
	v_lshlrev_b32_e32 v187, 16, v242
	v_and_b32_e32 v188, 0xffff0000, v242
	v_lshlrev_b32_e32 v189, 16, v243
	v_and_b32_e32 v190, 0xffff0000, v243
	global_load_dwordx4 v[236:239], v179, s[46:47]
	global_load_dwordx4 v[240:243], v179, s[48:49]
	v_max_f32_e32 v160, v160, v147
	v_max_f32_e32 v161, v161, v147
	v_max_f32_e32 v162, v162, v147
	v_max_f32_e32 v163, v163, v147
	v_max_f32_e32 v164, v164, v147
	v_max_f32_e32 v165, v165, v147
	v_max_f32_e32 v180, v180, v147
	v_max_f32_e32 v181, v181, v147
	v_max_f32_e32 v183, v183, v147
	v_max_f32_e32 v184, v184, v147
	v_max_f32_e32 v185, v185, v147
	v_max_f32_e32 v186, v186, v147
	v_max_f32_e32 v187, v187, v147
	v_max_f32_e32 v188, v188, v147
	v_max_f32_e32 v189, v189, v147
	v_max_f32_e32 v190, v190, v147
	v_rcp_f32_e32 v183, v183
	v_rcp_f32_e32 v184, v184
	v_rcp_f32_e32 v185, v185
	v_rcp_f32_e32 v186, v186
	v_rcp_f32_e32 v187, v187
	v_rcp_f32_e32 v188, v188
	v_rcp_f32_e32 v189, v189
	v_rcp_f32_e32 v190, v190
	v_mul_f32_e32 v160, v160, v183
	v_mul_f32_e32 v161, v161, v184
	v_mul_f32_e32 v162, v162, v185
	v_mul_f32_e32 v163, v163, v186
	v_mul_f32_e32 v164, v164, v187
	v_mul_f32_e32 v165, v165, v188
	v_mul_f32_e32 v180, v180, v189
	v_mul_f32_e32 v181, v181, v190
	v_mul_f32_e32 v60, v60, v160
	v_mul_f32_e32 v61, v61, v161
	v_mul_f32_e32 v62, v62, v162
	v_mul_f32_e32 v63, v63, v163
	v_mul_f32_e32 v56, v56, v164
	v_mul_f32_e32 v57, v57, v165
	v_mul_f32_e32 v58, v58, v180
	v_mul_f32_e32 v59, v59, v181
	s_waitcnt vmcnt(8)
	v_lshlrev_b32_e32 v160, 16, v192
	v_and_b32_e32 v161, 0xffff0000, v192
	v_lshlrev_b32_e32 v162, 16, v193
	v_and_b32_e32 v163, 0xffff0000, v193
	v_lshlrev_b32_e32 v164, 16, v194
	v_and_b32_e32 v165, 0xffff0000, v194
	v_lshlrev_b32_e32 v180, 16, v195
	v_and_b32_e32 v181, 0xffff0000, v195
	v_lshlrev_b32_e32 v183, 16, v196
	v_and_b32_e32 v184, 0xffff0000, v196
	v_lshlrev_b32_e32 v185, 16, v197
	v_and_b32_e32 v186, 0xffff0000, v197
	v_lshlrev_b32_e32 v187, 16, v198
	v_and_b32_e32 v188, 0xffff0000, v198
	v_lshlrev_b32_e32 v189, 16, v199
	v_and_b32_e32 v190, 0xffff0000, v199
	global_load_dwordx4 v[192:195], v179, s[46:47] offset:256
	global_load_dwordx4 v[196:199], v179, s[48:49] offset:256
	v_max_f32_e32 v160, v160, v147
	v_max_f32_e32 v161, v161, v147
	v_max_f32_e32 v162, v162, v147
	v_max_f32_e32 v163, v163, v147
	v_max_f32_e32 v164, v164, v147
	v_max_f32_e32 v165, v165, v147
	v_max_f32_e32 v180, v180, v147
	v_max_f32_e32 v181, v181, v147
	v_max_f32_e32 v183, v183, v147
	v_max_f32_e32 v184, v184, v147
	v_max_f32_e32 v185, v185, v147
	v_max_f32_e32 v186, v186, v147
	v_max_f32_e32 v187, v187, v147
	v_max_f32_e32 v188, v188, v147
	v_max_f32_e32 v189, v189, v147
	v_max_f32_e32 v190, v190, v147
	v_rcp_f32_e32 v183, v183
	v_rcp_f32_e32 v184, v184
	v_rcp_f32_e32 v185, v185
	v_rcp_f32_e32 v186, v186
	v_rcp_f32_e32 v187, v187
	v_rcp_f32_e32 v188, v188
	v_rcp_f32_e32 v189, v189
	v_rcp_f32_e32 v190, v190
	v_mul_f32_e32 v160, v160, v183
	v_mul_f32_e32 v161, v161, v184
	v_mul_f32_e32 v162, v162, v185
	v_mul_f32_e32 v163, v163, v186
	v_mul_f32_e32 v164, v164, v187
	v_mul_f32_e32 v165, v165, v188
	v_mul_f32_e32 v180, v180, v189
	v_mul_f32_e32 v181, v181, v190
	v_mul_f32_e32 v52, v52, v160
	v_mul_f32_e32 v53, v53, v161
	v_mul_f32_e32 v54, v54, v162
	v_mul_f32_e32 v55, v55, v163
	v_mul_f32_e32 v48, v48, v164
	v_mul_f32_e32 v49, v49, v165
	v_mul_f32_e32 v50, v50, v180
	v_mul_f32_e32 v51, v51, v181
	s_waitcnt vmcnt(8)
	v_lshlrev_b32_e32 v160, 16, v200
	v_and_b32_e32 v161, 0xffff0000, v200
	v_lshlrev_b32_e32 v162, 16, v201
	v_and_b32_e32 v163, 0xffff0000, v201
	v_lshlrev_b32_e32 v164, 16, v202
	v_and_b32_e32 v165, 0xffff0000, v202
	v_lshlrev_b32_e32 v180, 16, v203
	v_and_b32_e32 v181, 0xffff0000, v203
	v_lshlrev_b32_e32 v183, 16, v216
	v_and_b32_e32 v184, 0xffff0000, v216
	v_lshlrev_b32_e32 v185, 16, v217
	v_and_b32_e32 v186, 0xffff0000, v217
	v_lshlrev_b32_e32 v187, 16, v218
	v_and_b32_e32 v188, 0xffff0000, v218
	v_lshlrev_b32_e32 v189, 16, v219
	v_and_b32_e32 v190, 0xffff0000, v219
	v_max_f32_e32 v160, v160, v147
	v_max_f32_e32 v161, v161, v147
	v_max_f32_e32 v162, v162, v147
	v_max_f32_e32 v163, v163, v147
	v_max_f32_e32 v164, v164, v147
	v_max_f32_e32 v165, v165, v147
	v_max_f32_e32 v180, v180, v147
	v_max_f32_e32 v181, v181, v147
	v_max_f32_e32 v183, v183, v147
	v_max_f32_e32 v184, v184, v147
	v_max_f32_e32 v185, v185, v147
	v_max_f32_e32 v186, v186, v147
	v_max_f32_e32 v187, v187, v147
	v_max_f32_e32 v188, v188, v147
	v_max_f32_e32 v189, v189, v147
	v_max_f32_e32 v190, v190, v147
	v_rcp_f32_e32 v183, v183
	v_rcp_f32_e32 v184, v184
	v_rcp_f32_e32 v185, v185
	v_rcp_f32_e32 v186, v186
	v_rcp_f32_e32 v187, v187
	v_rcp_f32_e32 v188, v188
	v_rcp_f32_e32 v189, v189
	v_rcp_f32_e32 v190, v190
	v_mul_f32_e32 v160, v160, v183
	v_mul_f32_e32 v161, v161, v184
	v_mul_f32_e32 v162, v162, v185
	v_mul_f32_e32 v163, v163, v186
	v_mul_f32_e32 v164, v164, v187
	v_mul_f32_e32 v165, v165, v188
	v_mul_f32_e32 v180, v180, v189
	v_mul_f32_e32 v181, v181, v190
	v_mul_f32_e32 v44, v44, v160
	v_mul_f32_e32 v45, v45, v161
	v_mul_f32_e32 v46, v46, v162
	v_mul_f32_e32 v47, v47, v163
	v_mul_f32_e32 v40, v40, v164
	v_mul_f32_e32 v41, v41, v165
	v_mul_f32_e32 v42, v42, v180
	v_mul_f32_e32 v43, v43, v181
	s_waitcnt vmcnt(6)
	v_lshlrev_b32_e32 v160, 16, v220
	v_and_b32_e32 v161, 0xffff0000, v220
	v_lshlrev_b32_e32 v162, 16, v221
	v_and_b32_e32 v163, 0xffff0000, v221
	v_lshlrev_b32_e32 v164, 16, v222
	v_and_b32_e32 v165, 0xffff0000, v222
	v_lshlrev_b32_e32 v180, 16, v223
	v_and_b32_e32 v181, 0xffff0000, v223
	v_lshlrev_b32_e32 v183, 16, v224
	v_and_b32_e32 v184, 0xffff0000, v224
	v_lshlrev_b32_e32 v185, 16, v225
	v_and_b32_e32 v186, 0xffff0000, v225
	v_lshlrev_b32_e32 v187, 16, v226
	v_and_b32_e32 v188, 0xffff0000, v226
	v_lshlrev_b32_e32 v189, 16, v227
	v_and_b32_e32 v190, 0xffff0000, v227
	v_max_f32_e32 v160, v160, v147
	v_max_f32_e32 v161, v161, v147
	v_max_f32_e32 v162, v162, v147
	v_max_f32_e32 v163, v163, v147
	v_max_f32_e32 v164, v164, v147
	v_max_f32_e32 v165, v165, v147
	v_max_f32_e32 v180, v180, v147
	v_max_f32_e32 v181, v181, v147
	v_max_f32_e32 v183, v183, v147
	v_max_f32_e32 v184, v184, v147
	v_max_f32_e32 v185, v185, v147
	v_max_f32_e32 v186, v186, v147
	v_max_f32_e32 v187, v187, v147
	v_max_f32_e32 v188, v188, v147
	v_max_f32_e32 v189, v189, v147
	v_max_f32_e32 v190, v190, v147
	v_rcp_f32_e32 v183, v183
	v_rcp_f32_e32 v184, v184
	v_rcp_f32_e32 v185, v185
	v_rcp_f32_e32 v186, v186
	v_rcp_f32_e32 v187, v187
	v_rcp_f32_e32 v188, v188
	v_rcp_f32_e32 v189, v189
	v_rcp_f32_e32 v190, v190
	v_mul_f32_e32 v160, v160, v183
	v_mul_f32_e32 v161, v161, v184
	v_mul_f32_e32 v162, v162, v185
	v_mul_f32_e32 v163, v163, v186
	v_mul_f32_e32 v164, v164, v187
	v_mul_f32_e32 v165, v165, v188
	v_mul_f32_e32 v180, v180, v189
	v_mul_f32_e32 v181, v181, v190
	v_mul_f32_e32 v36, v36, v160
	v_mul_f32_e32 v37, v37, v161
	v_mul_f32_e32 v38, v38, v162
	v_mul_f32_e32 v39, v39, v163
	v_mul_f32_e32 v32, v32, v164
	v_mul_f32_e32 v33, v33, v165
	v_mul_f32_e32 v34, v34, v180
	v_mul_f32_e32 v35, v35, v181
	s_waitcnt vmcnt(4)
	v_lshlrev_b32_e32 v160, 16, v228
	v_and_b32_e32 v161, 0xffff0000, v228
	v_lshlrev_b32_e32 v162, 16, v229
	v_and_b32_e32 v163, 0xffff0000, v229
	v_lshlrev_b32_e32 v164, 16, v230
	v_and_b32_e32 v165, 0xffff0000, v230
	v_lshlrev_b32_e32 v180, 16, v231
	v_and_b32_e32 v181, 0xffff0000, v231
	v_lshlrev_b32_e32 v183, 16, v232
	v_and_b32_e32 v184, 0xffff0000, v232
	v_lshlrev_b32_e32 v185, 16, v233
	v_and_b32_e32 v186, 0xffff0000, v233
	v_lshlrev_b32_e32 v187, 16, v234
	v_and_b32_e32 v188, 0xffff0000, v234
	v_lshlrev_b32_e32 v189, 16, v235
	v_and_b32_e32 v190, 0xffff0000, v235
	v_max_f32_e32 v160, v160, v147
	v_max_f32_e32 v161, v161, v147
	v_max_f32_e32 v162, v162, v147
	v_max_f32_e32 v163, v163, v147
	v_max_f32_e32 v164, v164, v147
	v_max_f32_e32 v165, v165, v147
	v_max_f32_e32 v180, v180, v147
	v_max_f32_e32 v181, v181, v147
	v_max_f32_e32 v183, v183, v147
	v_max_f32_e32 v184, v184, v147
	v_max_f32_e32 v185, v185, v147
	v_max_f32_e32 v186, v186, v147
	v_max_f32_e32 v187, v187, v147
	v_max_f32_e32 v188, v188, v147
	v_max_f32_e32 v189, v189, v147
	v_max_f32_e32 v190, v190, v147
	v_rcp_f32_e32 v183, v183
	v_rcp_f32_e32 v184, v184
	v_rcp_f32_e32 v185, v185
	v_rcp_f32_e32 v186, v186
	v_rcp_f32_e32 v187, v187
	v_rcp_f32_e32 v188, v188
	v_rcp_f32_e32 v189, v189
	v_rcp_f32_e32 v190, v190
	v_mul_f32_e32 v160, v160, v183
	v_mul_f32_e32 v161, v161, v184
	v_mul_f32_e32 v162, v162, v185
	v_mul_f32_e32 v163, v163, v186
	v_mul_f32_e32 v164, v164, v187
	v_mul_f32_e32 v165, v165, v188
	v_mul_f32_e32 v180, v180, v189
	v_mul_f32_e32 v181, v181, v190
	v_mul_f32_e32 v28, v28, v160
	v_mul_f32_e32 v29, v29, v161
	v_mul_f32_e32 v30, v30, v162
	v_mul_f32_e32 v31, v31, v163
	v_mul_f32_e32 v24, v24, v164
	v_mul_f32_e32 v25, v25, v165
	v_mul_f32_e32 v26, v26, v180
	v_mul_f32_e32 v27, v27, v181
	s_waitcnt vmcnt(2)
	v_lshlrev_b32_e32 v160, 16, v236
	v_and_b32_e32 v161, 0xffff0000, v236
	v_lshlrev_b32_e32 v162, 16, v237
	v_and_b32_e32 v163, 0xffff0000, v237
	v_lshlrev_b32_e32 v164, 16, v238
	v_and_b32_e32 v165, 0xffff0000, v238
	v_lshlrev_b32_e32 v180, 16, v239
	v_and_b32_e32 v181, 0xffff0000, v239
	v_lshlrev_b32_e32 v183, 16, v240
	v_and_b32_e32 v184, 0xffff0000, v240
	v_lshlrev_b32_e32 v185, 16, v241
	v_and_b32_e32 v186, 0xffff0000, v241
	v_lshlrev_b32_e32 v187, 16, v242
	v_and_b32_e32 v188, 0xffff0000, v242
	v_lshlrev_b32_e32 v189, 16, v243
	v_and_b32_e32 v190, 0xffff0000, v243
	v_max_f32_e32 v160, v160, v147
	v_max_f32_e32 v161, v161, v147
	v_max_f32_e32 v162, v162, v147
	v_max_f32_e32 v163, v163, v147
	v_max_f32_e32 v164, v164, v147
	v_max_f32_e32 v165, v165, v147
	v_max_f32_e32 v180, v180, v147
	v_max_f32_e32 v181, v181, v147
	v_max_f32_e32 v183, v183, v147
	v_max_f32_e32 v184, v184, v147
	v_max_f32_e32 v185, v185, v147
	v_max_f32_e32 v186, v186, v147
	v_max_f32_e32 v187, v187, v147
	v_max_f32_e32 v188, v188, v147
	v_max_f32_e32 v189, v189, v147
	v_max_f32_e32 v190, v190, v147
	v_rcp_f32_e32 v183, v183
	v_rcp_f32_e32 v184, v184
	v_rcp_f32_e32 v185, v185
	v_rcp_f32_e32 v186, v186
	v_rcp_f32_e32 v187, v187
	v_rcp_f32_e32 v188, v188
	v_rcp_f32_e32 v189, v189
	v_rcp_f32_e32 v190, v190
	v_mul_f32_e32 v160, v160, v183
	v_mul_f32_e32 v161, v161, v184
	v_mul_f32_e32 v162, v162, v185
	v_mul_f32_e32 v163, v163, v186
	v_mul_f32_e32 v164, v164, v187
	v_mul_f32_e32 v165, v165, v188
	v_mul_f32_e32 v180, v180, v189
	v_mul_f32_e32 v181, v181, v190
	v_mul_f32_e32 v20, v20, v160
	v_mul_f32_e32 v21, v21, v161
	v_mul_f32_e32 v22, v22, v162
	v_mul_f32_e32 v23, v23, v163
	v_mul_f32_e32 v16, v16, v164
	v_mul_f32_e32 v17, v17, v165
	v_mul_f32_e32 v18, v18, v180
	v_mul_f32_e32 v19, v19, v181
	s_waitcnt vmcnt(0)
	v_lshlrev_b32_e32 v160, 16, v192
	v_and_b32_e32 v161, 0xffff0000, v192
	v_lshlrev_b32_e32 v162, 16, v193
	v_and_b32_e32 v163, 0xffff0000, v193
	v_lshlrev_b32_e32 v164, 16, v194
	v_and_b32_e32 v165, 0xffff0000, v194
	v_lshlrev_b32_e32 v180, 16, v195
	v_and_b32_e32 v181, 0xffff0000, v195
	v_lshlrev_b32_e32 v183, 16, v196
	v_and_b32_e32 v184, 0xffff0000, v196
	v_lshlrev_b32_e32 v185, 16, v197
	v_and_b32_e32 v186, 0xffff0000, v197
	v_lshlrev_b32_e32 v187, 16, v198
	v_and_b32_e32 v188, 0xffff0000, v198
	v_lshlrev_b32_e32 v189, 16, v199
	v_and_b32_e32 v190, 0xffff0000, v199
	v_max_f32_e32 v160, v160, v147
	v_max_f32_e32 v161, v161, v147
	v_max_f32_e32 v162, v162, v147
	v_max_f32_e32 v163, v163, v147
	v_max_f32_e32 v164, v164, v147
	v_max_f32_e32 v165, v165, v147
	v_max_f32_e32 v180, v180, v147
	v_max_f32_e32 v181, v181, v147
	v_max_f32_e32 v183, v183, v147
	v_max_f32_e32 v184, v184, v147
	v_max_f32_e32 v185, v185, v147
	v_max_f32_e32 v186, v186, v147
	v_max_f32_e32 v187, v187, v147
	v_max_f32_e32 v188, v188, v147
	v_max_f32_e32 v189, v189, v147
	v_max_f32_e32 v190, v190, v147
	v_rcp_f32_e32 v183, v183
	v_rcp_f32_e32 v184, v184
	v_rcp_f32_e32 v185, v185
	v_rcp_f32_e32 v186, v186
	v_rcp_f32_e32 v187, v187
	v_rcp_f32_e32 v188, v188
	v_rcp_f32_e32 v189, v189
	v_rcp_f32_e32 v190, v190
	v_mul_f32_e32 v160, v160, v183
	v_mul_f32_e32 v161, v161, v184
	v_mul_f32_e32 v162, v162, v185
	v_mul_f32_e32 v163, v163, v186
	v_mul_f32_e32 v164, v164, v187
	v_mul_f32_e32 v165, v165, v188
	v_mul_f32_e32 v180, v180, v189
	v_mul_f32_e32 v181, v181, v190
	v_mul_f32_e32 v12, v12, v160
	v_mul_f32_e32 v13, v13, v161
	v_mul_f32_e32 v14, v14, v162
	v_mul_f32_e32 v15, v15, v163
	v_mul_f32_e32 v8, v8, v164
	v_mul_f32_e32 v9, v9, v165
	v_mul_f32_e32 v10, v10, v180
	v_mul_f32_e32 v11, v11, v181
	v_mov_b32_e32 v214, v8
	v_mov_b32_e32 v215, v9
	v_mov_b32_e32 v216, v10
	v_mov_b32_e32 v217, v11
	v_mov_b32_e32 v218, v12
	v_mov_b32_e32 v219, v13
	v_mov_b32_e32 v220, v14
	v_mov_b32_e32 v221, v15
	v_mov_b32_e32 v222, v16
	v_mov_b32_e32 v223, v17
	v_mov_b32_e32 v224, v18
	v_mov_b32_e32 v225, v19
	v_mov_b32_e32 v226, v20
	v_mov_b32_e32 v227, v21
	v_mov_b32_e32 v228, v22
	v_mov_b32_e32 v229, v23
	v_mov_b32_e32 v230, v24
	v_mov_b32_e32 v231, v25
	v_mov_b32_e32 v232, v26
	s_mov_b64 s[48:49], 0x4000
	s_mov_b64 s[46:47], 0x8000
	s_mov_b32 s9, 0x58000
	s_mov_b64 s[16:17], -1
	s_andn2_b64 vcc, exec, s[44:45]
	s_cbranch_vccnz .LBB0_855
	s_andn2_b64 vcc, exec, s[0:1]
	s_cbranch_vccnz .LBB0_854
	s_barrier
	s_branch .LBB0_854

.LBB0_882:
	s_ashr_i32 s13, s12, 31
	s_lshl_b64 s[14:15], s[12:13], 19
	s_add_u32 s14, s24, s14
	s_addc_u32 s15, s25, s15
	s_and_b64 s[16:17], s[42:43], exec
	s_cselect_b32 s13, s15, s21
	s_cselect_b32 s39, s14, s20
	s_ashr_i32 s11, s10, 31
	s_lshl_b64 s[16:17], s[10:11], 19
	s_add_u32 s16, s26, s16
	s_addc_u32 s17, s27, s17
	s_and_b64 s[22:23], s[42:43], exec
	s_cselect_b32 s11, s17, s19
	s_cselect_b32 s41, s16, s18
	s_add_u32 s44, s18, 0x100
	s_addc_u32 s45, s19, 0
	s_add_u32 s18, s20, 0x40080
	s_addc_u32 s19, s21, 0
	s_mov_b32 s46, -2
	v_mov_b32_e32 v8, v214
	v_mov_b32_e32 v9, v215
	v_mov_b32_e32 v10, v216
	v_mov_b32_e32 v11, v217
	v_mov_b32_e32 v12, v218
	v_mov_b32_e32 v13, v219
	v_mov_b32_e32 v14, v220
	v_mov_b32_e32 v15, v221
	v_mov_b32_e32 v16, v222
	v_mov_b32_e32 v17, v223
	v_mov_b32_e32 v18, v224
	v_mov_b32_e32 v19, v225
	v_mov_b32_e32 v20, v226
	v_mov_b32_e32 v21, v227
	v_mov_b32_e32 v22, v228
	v_mov_b32_e32 v23, v229
	v_mov_b32_e32 v24, v230
	v_mov_b32_e32 v25, v231
	v_mov_b32_e32 v26, v232

.LBB0_886:
	v_and_b32_e32 v160, 63, v206
	v_lshrrev_b32_e32 v161, 6, v206
	v_and_b32_e32 v162, 15, v160
	v_readfirstlane_b32 s18, v161
	v_lshrrev_b32_e32 v163, 4, v160
	s_nop 3
	s_and_b32 s19, s18, 3
	s_lshl_b32 s19, s19, 5
	s_lshl_b32 s11, s33, 8
	s_add_i32 s19, s19, s11
	v_lshl_add_u32 v164, v163, 3, s19
	s_lshr_b32 s19, s18, 2
	s_lshl_b32 s19, s19, 6
	s_lshl_b32 s11, s38, 8
	s_add_i32 s11, s11, s19
	v_add_u32_e32 v165, s11, v162
	v_lshlrev_b32_e32 v146, 11, v165
	v_lshl_add_u32 v146, v164, 1, v146
	s_add_u32 s46, s70, 0x17800000
	s_addc_u32 s47, s71, 0
	s_add_u32 s48, s70, 0x15800000
	s_addc_u32 s49, s71, 0
	v_mov_b32_e32 v147, 0x21800000
	v_mov_b32_e32 v172, v146
	v_add_u32_e32 v173, 0x8000, v146
	v_add_u32_e32 v174, 0x10000, v146
	v_add_u32_e32 v175, 0x18000, v146
	v_add_u32_e32 v176, 0x40000, v146
	v_add_u32_e32 v177, 0x48000, v146
	v_add_u32_e32 v178, 0x50000, v146
	v_add_u32_e32 v179, 0x58000, v146
	global_load_dwordx4 v[192:195], v172, s[46:47]
	global_load_dwordx4 v[196:199], v172, s[46:47] offset:256
	global_load_dwordx4 v[200:203], v173, s[46:47]
	global_load_dwordx4 v[216:219], v173, s[46:47] offset:256
	global_load_dwordx4 v[220:223], v174, s[46:47]
	global_load_dwordx4 v[224:227], v174, s[46:47] offset:256
	global_load_dwordx4 v[228:231], v175, s[46:47]
	global_load_dwordx4 v[232:235], v175, s[46:47] offset:256
	global_load_dwordx4 v[236:239], v176, s[46:47]
	global_load_dwordx4 v[240:243], v176, s[46:47] offset:256
	global_load_dwordx4 v[244:247], v177, s[46:47]
	s_waitcnt vmcnt(10)
	v_lshlrev_b32_e32 v160, 16, v192
	v_and_b32_e32 v161, 0xffff0000, v192
	v_lshlrev_b32_e32 v162, 16, v193
	v_and_b32_e32 v163, 0xffff0000, v193
	v_lshlrev_b32_e32 v164, 16, v194
	v_and_b32_e32 v165, 0xffff0000, v194
	v_lshlrev_b32_e32 v180, 16, v195
	v_and_b32_e32 v181, 0xffff0000, v195
	global_load_dwordx4 v[192:195], v177, s[46:47] offset:256
	v_max_f32_e32 v160, v160, v147
	v_max_f32_e32 v161, v161, v147
	v_max_f32_e32 v162, v162, v147
	v_max_f32_e32 v163, v163, v147
	v_max_f32_e32 v164, v164, v147
	v_max_f32_e32 v165, v165, v147
	v_max_f32_e32 v180, v180, v147
	v_max_f32_e32 v181, v181, v147
	v_mul_f32_e32 v132, v132, v160
	v_mul_f32_e32 v133, v133, v161
	v_mul_f32_e32 v134, v134, v162
	v_mul_f32_e32 v135, v135, v163
	v_mul_f32_e32 v128, v128, v164
	v_mul_f32_e32 v129, v129, v165
	v_mul_f32_e32 v130, v130, v180
	v_mul_f32_e32 v131, v131, v181
	v_cvt_pk_bf16_f32 v184, v132, v133
	v_cvt_pk_bf16_f32 v185, v134, v135
	v_cvt_pk_bf16_f32 v186, v128, v129
	v_cvt_pk_bf16_f32 v187, v130, v131
	global_store_dwordx4 v172, v[184:187], s[48:49]
	s_waitcnt vmcnt(11)
	v_lshlrev_b32_e32 v160, 16, v196
	v_and_b32_e32 v161, 0xffff0000, v196
	v_lshlrev_b32_e32 v162, 16, v197
	v_and_b32_e32 v163, 0xffff0000, v197
	v_lshlrev_b32_e32 v164, 16, v198
	v_and_b32_e32 v165, 0xffff0000, v198
	v_lshlrev_b32_e32 v180, 16, v199
	v_and_b32_e32 v181, 0xffff0000, v199
	global_load_dwordx4 v[196:199], v178, s[46:47]
	v_max_f32_e32 v160, v160, v147
	v_max_f32_e32 v161, v161, v147
	v_max_f32_e32 v162, v162, v147
	v_max_f32_e32 v163, v163, v147
	v_max_f32_e32 v164, v164, v147
	v_max_f32_e32 v165, v165, v147
	v_max_f32_e32 v180, v180, v147
	v_max_f32_e32 v181, v181, v147
	v_mul_f32_e32 v124, v124, v160
	v_mul_f32_e32 v125, v125, v161
	v_mul_f32_e32 v126, v126, v162
	v_mul_f32_e32 v127, v127, v163
	v_mul_f32_e32 v120, v120, v164
	v_mul_f32_e32 v121, v121, v165
	v_mul_f32_e32 v122, v122, v180
	v_mul_f32_e32 v123, v123, v181
	v_cvt_pk_bf16_f32 v188, v124, v125
	v_cvt_pk_bf16_f32 v189, v126, v127
	v_cvt_pk_bf16_f32 v190, v120, v121
	v_cvt_pk_bf16_f32 v191, v122, v123
	global_store_dwordx4 v172, v[188:191], s[48:49] offset:256
	s_waitcnt vmcnt(12)
	v_lshlrev_b32_e32 v160, 16, v200
	v_and_b32_e32 v161, 0xffff0000, v200
	v_lshlrev_b32_e32 v162, 16, v201
	v_and_b32_e32 v163, 0xffff0000, v201
	v_lshlrev_b32_e32 v164, 16, v202
	v_and_b32_e32 v165, 0xffff0000, v202
	v_lshlrev_b32_e32 v180, 16, v203
	v_and_b32_e32 v181, 0xffff0000, v203
	global_load_dwordx4 v[200:203], v178, s[46:47] offset:256
	v_max_f32_e32 v160, v160, v147
	v_max_f32_e32 v161, v161, v147
	v_max_f32_e32 v162, v162, v147
	v_max_f32_e32 v163, v163, v147
	v_max_f32_e32 v164, v164, v147
	v_max_f32_e32 v165, v165, v147
	v_max_f32_e32 v180, v180, v147
	v_max_f32_e32 v181, v181, v147
	v_mul_f32_e32 v116, v116, v160
	v_mul_f32_e32 v117, v117, v161
	v_mul_f32_e32 v118, v118, v162
	v_mul_f32_e32 v119, v119, v163
	v_mul_f32_e32 v112, v112, v164
	v_mul_f32_e32 v113, v113, v165
	v_mul_f32_e32 v114, v114, v180
	v_mul_f32_e32 v115, v115, v181
	v_cvt_pk_bf16_f32 v184, v116, v117
	v_cvt_pk_bf16_f32 v185, v118, v119
	v_cvt_pk_bf16_f32 v186, v112, v113
	v_cvt_pk_bf16_f32 v187, v114, v115
	global_store_dwordx4 v173, v[184:187], s[48:49]
	s_waitcnt vmcnt(13)
	v_lshlrev_b32_e32 v160, 16, v216
	v_and_b32_e32 v161, 0xffff0000, v216
	v_lshlrev_b32_e32 v162, 16, v217
	v_and_b32_e32 v163, 0xffff0000, v217
	v_lshlrev_b32_e32 v164, 16, v218
	v_and_b32_e32 v165, 0xffff0000, v218
	v_lshlrev_b32_e32 v180, 16, v219
	v_and_b32_e32 v181, 0xffff0000, v219
	global_load_dwordx4 v[216:219], v179, s[46:47]
	v_max_f32_e32 v160, v160, v147
	v_max_f32_e32 v161, v161, v147
	v_max_f32_e32 v162, v162, v147
	v_max_f32_e32 v163, v163, v147
	v_max_f32_e32 v164, v164, v147
	v_max_f32_e32 v165, v165, v147
	v_max_f32_e32 v180, v180, v147
	v_max_f32_e32 v181, v181, v147
	v_mul_f32_e32 v108, v108, v160
	v_mul_f32_e32 v109, v109, v161
	v_mul_f32_e32 v110, v110, v162
	v_mul_f32_e32 v111, v111, v163
	v_mul_f32_e32 v104, v104, v164
	v_mul_f32_e32 v105, v105, v165
	v_mul_f32_e32 v106, v106, v180
	v_mul_f32_e32 v107, v107, v181
	v_cvt_pk_bf16_f32 v188, v108, v109
	v_cvt_pk_bf16_f32 v189, v110, v111
	v_cvt_pk_bf16_f32 v190, v104, v105
	v_cvt_pk_bf16_f32 v191, v106, v107
	global_store_dwordx4 v173, v[188:191], s[48:49] offset:256
	s_waitcnt vmcnt(14)
	v_lshlrev_b32_e32 v160, 16, v220
	v_and_b32_e32 v161, 0xffff0000, v220
	v_lshlrev_b32_e32 v162, 16, v221
	v_and_b32_e32 v163, 0xffff0000, v221
	v_lshlrev_b32_e32 v164, 16, v222
	v_and_b32_e32 v165, 0xffff0000, v222
	v_lshlrev_b32_e32 v180, 16, v223
	v_and_b32_e32 v181, 0xffff0000, v223
	global_load_dwordx4 v[220:223], v179, s[46:47] offset:256
	v_max_f32_e32 v160, v160, v147
	v_max_f32_e32 v161, v161, v147
	v_max_f32_e32 v162, v162, v147
	v_max_f32_e32 v163, v163, v147
	v_max_f32_e32 v164, v164, v147
	v_max_f32_e32 v165, v165, v147
	v_max_f32_e32 v180, v180, v147
	v_max_f32_e32 v181, v181, v147
	v_mul_f32_e32 v100, v100, v160
	v_mul_f32_e32 v101, v101, v161
	v_mul_f32_e32 v102, v102, v162
	v_mul_f32_e32 v103, v103, v163
	v_mul_f32_e32 v96, v96, v164
	v_mul_f32_e32 v97, v97, v165
	v_mul_f32_e32 v98, v98, v180
	v_mul_f32_e32 v99, v99, v181
	v_cvt_pk_bf16_f32 v184, v100, v101
	v_cvt_pk_bf16_f32 v185, v102, v103
	v_cvt_pk_bf16_f32 v186, v96, v97
	v_cvt_pk_bf16_f32 v187, v98, v99
	global_store_dwordx4 v174, v[184:187], s[48:49]
	s_waitcnt vmcnt(15)
	v_lshlrev_b32_e32 v160, 16, v224
	v_and_b32_e32 v161, 0xffff0000, v224
	v_lshlrev_b32_e32 v162, 16, v225
	v_and_b32_e32 v163, 0xffff0000, v225
	v_lshlrev_b32_e32 v164, 16, v226
	v_and_b32_e32 v165, 0xffff0000, v226
	v_lshlrev_b32_e32 v180, 16, v227
	v_and_b32_e32 v181, 0xffff0000, v227
	v_max_f32_e32 v160, v160, v147
	v_max_f32_e32 v161, v161, v147
	v_max_f32_e32 v162, v162, v147
	v_max_f32_e32 v163, v163, v147
	v_max_f32_e32 v164, v164, v147
	v_max_f32_e32 v165, v165, v147
	v_max_f32_e32 v180, v180, v147
	v_max_f32_e32 v181, v181, v147
	v_mul_f32_e32 v92, v92, v160
	v_mul_f32_e32 v93, v93, v161
	v_mul_f32_e32 v94, v94, v162
	v_mul_f32_e32 v95, v95, v163
	v_mul_f32_e32 v88, v88, v164
	v_mul_f32_e32 v89, v89, v165
	v_mul_f32_e32 v90, v90, v180
	v_mul_f32_e32 v91, v91, v181
	v_cvt_pk_bf16_f32 v188, v92, v93
	v_cvt_pk_bf16_f32 v189, v94, v95
	v_cvt_pk_bf16_f32 v190, v88, v89
	v_cvt_pk_bf16_f32 v191, v90, v91
	global_store_dwordx4 v174, v[188:191], s[48:49] offset:256
	s_waitcnt vmcnt(15)
	v_lshlrev_b32_e32 v160, 16, v228
	v_and_b32_e32 v161, 0xffff0000, v228
	v_lshlrev_b32_e32 v162, 16, v229
	v_and_b32_e32 v163, 0xffff0000, v229
	v_lshlrev_b32_e32 v164, 16, v230
	v_and_b32_e32 v165, 0xffff0000, v230
	v_lshlrev_b32_e32 v180, 16, v231
	v_and_b32_e32 v181, 0xffff0000, v231
	v_max_f32_e32 v160, v160, v147
	v_max_f32_e32 v161, v161, v147
	v_max_f32_e32 v162, v162, v147
	v_max_f32_e32 v163, v163, v147
	v_max_f32_e32 v164, v164, v147
	v_max_f32_e32 v165, v165, v147
	v_max_f32_e32 v180, v180, v147
	v_max_f32_e32 v181, v181, v147
	v_mul_f32_e32 v84, v84, v160
	v_mul_f32_e32 v85, v85, v161
	v_mul_f32_e32 v86, v86, v162
	v_mul_f32_e32 v87, v87, v163
	v_mul_f32_e32 v80, v80, v164
	v_mul_f32_e32 v81, v81, v165
	v_mul_f32_e32 v82, v82, v180
	v_mul_f32_e32 v83, v83, v181
	v_cvt_pk_bf16_f32 v184, v84, v85
	v_cvt_pk_bf16_f32 v185, v86, v87
	v_cvt_pk_bf16_f32 v186, v80, v81
	v_cvt_pk_bf16_f32 v187, v82, v83
	global_store_dwordx4 v175, v[184:187], s[48:49]
	s_waitcnt vmcnt(15)
	v_lshlrev_b32_e32 v160, 16, v232
	v_and_b32_e32 v161, 0xffff0000, v232
	v_lshlrev_b32_e32 v162, 16, v233
	v_and_b32_e32 v163, 0xffff0000, v233
	v_lshlrev_b32_e32 v164, 16, v234
	v_and_b32_e32 v165, 0xffff0000, v234
	v_lshlrev_b32_e32 v180, 16, v235
	v_and_b32_e32 v181, 0xffff0000, v235
	v_max_f32_e32 v160, v160, v147
	v_max_f32_e32 v161, v161, v147
	v_max_f32_e32 v162, v162, v147
	v_max_f32_e32 v163, v163, v147
	v_max_f32_e32 v164, v164, v147
	v_max_f32_e32 v165, v165, v147
	v_max_f32_e32 v180, v180, v147
	v_max_f32_e32 v181, v181, v147
	v_mul_f32_e32 v76, v76, v160
	v_mul_f32_e32 v77, v77, v161
	v_mul_f32_e32 v78, v78, v162
	v_mul_f32_e32 v79, v79, v163
	v_mul_f32_e32 v72, v72, v164
	v_mul_f32_e32 v73, v73, v165
	v_mul_f32_e32 v74, v74, v180
	v_mul_f32_e32 v75, v75, v181
	v_cvt_pk_bf16_f32 v188, v76, v77
	v_cvt_pk_bf16_f32 v189, v78, v79
	v_cvt_pk_bf16_f32 v190, v72, v73
	v_cvt_pk_bf16_f32 v191, v74, v75
	global_store_dwordx4 v175, v[188:191], s[48:49] offset:256
	s_waitcnt vmcnt(15)
	v_lshlrev_b32_e32 v160, 16, v236
	v_and_b32_e32 v161, 0xffff0000, v236
	v_lshlrev_b32_e32 v162, 16, v237
	v_and_b32_e32 v163, 0xffff0000, v237
	v_lshlrev_b32_e32 v164, 16, v238
	v_and_b32_e32 v165, 0xffff0000, v238
	v_lshlrev_b32_e32 v180, 16, v239
	v_and_b32_e32 v181, 0xffff0000, v239
	v_max_f32_e32 v160, v160, v147
	v_max_f32_e32 v161, v161, v147
	v_max_f32_e32 v162, v162, v147
	v_max_f32_e32 v163, v163, v147
	v_max_f32_e32 v164, v164, v147
	v_max_f32_e32 v165, v165, v147
	v_max_f32_e32 v180, v180, v147
	v_max_f32_e32 v181, v181, v147
	v_mul_f32_e32 v68, v68, v160
	v_mul_f32_e32 v69, v69, v161
	v_mul_f32_e32 v70, v70, v162
	v_mul_f32_e32 v71, v71, v163
	v_mul_f32_e32 v64, v64, v164
	v_mul_f32_e32 v65, v65, v165
	v_mul_f32_e32 v66, v66, v180
	v_mul_f32_e32 v67, v67, v181
	v_cvt_pk_bf16_f32 v184, v68, v69
	v_cvt_pk_bf16_f32 v185, v70, v71
	v_cvt_pk_bf16_f32 v186, v64, v65
	v_cvt_pk_bf16_f32 v187, v66, v67
	global_store_dwordx4 v176, v[184:187], s[48:49]
	s_waitcnt vmcnt(15)
	v_lshlrev_b32_e32 v160, 16, v240
	v_and_b32_e32 v161, 0xffff0000, v240
	v_lshlrev_b32_e32 v162, 16, v241
	v_and_b32_e32 v163, 0xffff0000, v241
	v_lshlrev_b32_e32 v164, 16, v242
	v_and_b32_e32 v165, 0xffff0000, v242
	v_lshlrev_b32_e32 v180, 16, v243
	v_and_b32_e32 v181, 0xffff0000, v243
	v_max_f32_e32 v160, v160, v147
	v_max_f32_e32 v161, v161, v147
	v_max_f32_e32 v162, v162, v147
	v_max_f32_e32 v163, v163, v147
	v_max_f32_e32 v164, v164, v147
	v_max_f32_e32 v165, v165, v147
	v_max_f32_e32 v180, v180, v147
	v_max_f32_e32 v181, v181, v147
	v_mul_f32_e32 v60, v60, v160
	v_mul_f32_e32 v61, v61, v161
	v_mul_f32_e32 v62, v62, v162
	v_mul_f32_e32 v63, v63, v163
	v_mul_f32_e32 v56, v56, v164
	v_mul_f32_e32 v57, v57, v165
	v_mul_f32_e32 v58, v58, v180
	v_mul_f32_e32 v59, v59, v181
	v_cvt_pk_bf16_f32 v188, v60, v61
	v_cvt_pk_bf16_f32 v189, v62, v63
	v_cvt_pk_bf16_f32 v190, v56, v57
	v_cvt_pk_bf16_f32 v191, v58, v59
	global_store_dwordx4 v176, v[188:191], s[48:49] offset:256
	s_waitcnt vmcnt(15)
	v_lshlrev_b32_e32 v160, 16, v244
	v_and_b32_e32 v161, 0xffff0000, v244
	v_lshlrev_b32_e32 v162, 16, v245
	v_and_b32_e32 v163, 0xffff0000, v245
	v_lshlrev_b32_e32 v164, 16, v246
	v_and_b32_e32 v165, 0xffff0000, v246
	v_lshlrev_b32_e32 v180, 16, v247
	v_and_b32_e32 v181, 0xffff0000, v247
	v_max_f32_e32 v160, v160, v147
	v_max_f32_e32 v161, v161, v147
	v_max_f32_e32 v162, v162, v147
	v_max_f32_e32 v163, v163, v147
	v_max_f32_e32 v164, v164, v147
	v_max_f32_e32 v165, v165, v147
	v_max_f32_e32 v180, v180, v147
	v_max_f32_e32 v181, v181, v147
	v_mul_f32_e32 v52, v52, v160
	v_mul_f32_e32 v53, v53, v161
	v_mul_f32_e32 v54, v54, v162
	v_mul_f32_e32 v55, v55, v163
	v_mul_f32_e32 v48, v48, v164
	v_mul_f32_e32 v49, v49, v165
	v_mul_f32_e32 v50, v50, v180
	v_mul_f32_e32 v51, v51, v181
	v_cvt_pk_bf16_f32 v184, v52, v53
	v_cvt_pk_bf16_f32 v185, v54, v55
	v_cvt_pk_bf16_f32 v186, v48, v49
	v_cvt_pk_bf16_f32 v187, v50, v51
	global_store_dwordx4 v177, v[184:187], s[48:49]
	s_waitcnt vmcnt(15)
	v_lshlrev_b32_e32 v160, 16, v192
	v_and_b32_e32 v161, 0xffff0000, v192
	v_lshlrev_b32_e32 v162, 16, v193
	v_and_b32_e32 v163, 0xffff0000, v193
	v_lshlrev_b32_e32 v164, 16, v194
	v_and_b32_e32 v165, 0xffff0000, v194
	v_lshlrev_b32_e32 v180, 16, v195
	v_and_b32_e32 v181, 0xffff0000, v195
	v_max_f32_e32 v160, v160, v147
	v_max_f32_e32 v161, v161, v147
	v_max_f32_e32 v162, v162, v147
	v_max_f32_e32 v163, v163, v147
	v_max_f32_e32 v164, v164, v147
	v_max_f32_e32 v165, v165, v147
	v_max_f32_e32 v180, v180, v147
	v_max_f32_e32 v181, v181, v147
	v_mul_f32_e32 v44, v44, v160
	v_mul_f32_e32 v45, v45, v161
	v_mul_f32_e32 v46, v46, v162
	v_mul_f32_e32 v47, v47, v163
	v_mul_f32_e32 v40, v40, v164
	v_mul_f32_e32 v41, v41, v165
	v_mul_f32_e32 v42, v42, v180
	v_mul_f32_e32 v43, v43, v181
	v_cvt_pk_bf16_f32 v188, v44, v45
	v_cvt_pk_bf16_f32 v189, v46, v47
	v_cvt_pk_bf16_f32 v190, v40, v41
	v_cvt_pk_bf16_f32 v191, v42, v43
	global_store_dwordx4 v177, v[188:191], s[48:49] offset:256
	s_waitcnt vmcnt(14)
	v_lshlrev_b32_e32 v160, 16, v196
	v_and_b32_e32 v161, 0xffff0000, v196
	v_lshlrev_b32_e32 v162, 16, v197
	v_and_b32_e32 v163, 0xffff0000, v197
	v_lshlrev_b32_e32 v164, 16, v198
	v_and_b32_e32 v165, 0xffff0000, v198
	v_lshlrev_b32_e32 v180, 16, v199
	v_and_b32_e32 v181, 0xffff0000, v199
	v_max_f32_e32 v160, v160, v147
	v_max_f32_e32 v161, v161, v147
	v_max_f32_e32 v162, v162, v147
	v_max_f32_e32 v163, v163, v147
	v_max_f32_e32 v164, v164, v147
	v_max_f32_e32 v165, v165, v147
	v_max_f32_e32 v180, v180, v147
	v_max_f32_e32 v181, v181, v147
	v_mul_f32_e32 v36, v36, v160
	v_mul_f32_e32 v37, v37, v161
	v_mul_f32_e32 v38, v38, v162
	v_mul_f32_e32 v39, v39, v163
	v_mul_f32_e32 v32, v32, v164
	v_mul_f32_e32 v33, v33, v165
	v_mul_f32_e32 v34, v34, v180
	v_mul_f32_e32 v35, v35, v181
	v_cvt_pk_bf16_f32 v184, v36, v37
	v_cvt_pk_bf16_f32 v185, v38, v39
	v_cvt_pk_bf16_f32 v186, v32, v33
	v_cvt_pk_bf16_f32 v187, v34, v35
	global_store_dwordx4 v178, v[184:187], s[48:49]
	s_waitcnt vmcnt(13)
	v_lshlrev_b32_e32 v160, 16, v200
	v_and_b32_e32 v161, 0xffff0000, v200
	v_lshlrev_b32_e32 v162, 16, v201
	v_and_b32_e32 v163, 0xffff0000, v201
	v_lshlrev_b32_e32 v164, 16, v202
	v_and_b32_e32 v165, 0xffff0000, v202
	v_lshlrev_b32_e32 v180, 16, v203
	v_and_b32_e32 v181, 0xffff0000, v203
	v_max_f32_e32 v160, v160, v147
	v_max_f32_e32 v161, v161, v147
	v_max_f32_e32 v162, v162, v147
	v_max_f32_e32 v163, v163, v147
	v_max_f32_e32 v164, v164, v147
	v_max_f32_e32 v165, v165, v147
	v_max_f32_e32 v180, v180, v147
	v_max_f32_e32 v181, v181, v147
	v_mul_f32_e32 v28, v28, v160
	v_mul_f32_e32 v29, v29, v161
	v_mul_f32_e32 v30, v30, v162
	v_mul_f32_e32 v31, v31, v163
	v_mul_f32_e32 v24, v24, v164
	v_mul_f32_e32 v25, v25, v165
	v_mul_f32_e32 v26, v26, v180
	v_mul_f32_e32 v27, v27, v181
	v_cvt_pk_bf16_f32 v188, v28, v29
	v_cvt_pk_bf16_f32 v189, v30, v31
	v_cvt_pk_bf16_f32 v190, v24, v25
	v_cvt_pk_bf16_f32 v191, v26, v27
	global_store_dwordx4 v178, v[188:191], s[48:49] offset:256
	s_waitcnt vmcnt(12)
	v_lshlrev_b32_e32 v160, 16, v216
	v_and_b32_e32 v161, 0xffff0000, v216
	v_lshlrev_b32_e32 v162, 16, v217
	v_and_b32_e32 v163, 0xffff0000, v217
	v_lshlrev_b32_e32 v164, 16, v218
	v_and_b32_e32 v165, 0xffff0000, v218
	v_lshlrev_b32_e32 v180, 16, v219
	v_and_b32_e32 v181, 0xffff0000, v219
	v_max_f32_e32 v160, v160, v147
	v_max_f32_e32 v161, v161, v147
	v_max_f32_e32 v162, v162, v147
	v_max_f32_e32 v163, v163, v147
	v_max_f32_e32 v164, v164, v147
	v_max_f32_e32 v165, v165, v147
	v_max_f32_e32 v180, v180, v147
	v_max_f32_e32 v181, v181, v147
	v_mul_f32_e32 v20, v20, v160
	v_mul_f32_e32 v21, v21, v161
	v_mul_f32_e32 v22, v22, v162
	v_mul_f32_e32 v23, v23, v163
	v_mul_f32_e32 v16, v16, v164
	v_mul_f32_e32 v17, v17, v165
	v_mul_f32_e32 v18, v18, v180
	v_mul_f32_e32 v19, v19, v181
	v_cvt_pk_bf16_f32 v184, v20, v21
	v_cvt_pk_bf16_f32 v185, v22, v23
	v_cvt_pk_bf16_f32 v186, v16, v17
	v_cvt_pk_bf16_f32 v187, v18, v19
	global_store_dwordx4 v179, v[184:187], s[48:49]
	s_waitcnt vmcnt(11)
	v_lshlrev_b32_e32 v160, 16, v220
	v_and_b32_e32 v161, 0xffff0000, v220
	v_lshlrev_b32_e32 v162, 16, v221
	v_and_b32_e32 v163, 0xffff0000, v221
	v_lshlrev_b32_e32 v164, 16, v222
	v_and_b32_e32 v165, 0xffff0000, v222
	v_lshlrev_b32_e32 v180, 16, v223
	v_and_b32_e32 v181, 0xffff0000, v223
	v_max_f32_e32 v160, v160, v147
	v_max_f32_e32 v161, v161, v147
	v_max_f32_e32 v162, v162, v147
	v_max_f32_e32 v163, v163, v147
	v_max_f32_e32 v164, v164, v147
	v_max_f32_e32 v165, v165, v147
	v_max_f32_e32 v180, v180, v147
	v_max_f32_e32 v181, v181, v147
	v_mul_f32_e32 v12, v12, v160
	v_mul_f32_e32 v13, v13, v161
	v_mul_f32_e32 v14, v14, v162
	v_mul_f32_e32 v15, v15, v163
	v_mul_f32_e32 v8, v8, v164
	v_mul_f32_e32 v9, v9, v165
	v_mul_f32_e32 v10, v10, v180
	v_mul_f32_e32 v11, v11, v181
	v_cvt_pk_bf16_f32 v188, v12, v13
	v_cvt_pk_bf16_f32 v189, v14, v15
	v_cvt_pk_bf16_f32 v190, v8, v9
	v_cvt_pk_bf16_f32 v191, v10, v11
	global_store_dwordx4 v179, v[188:191], s[48:49] offset:256
	s_mov_b64 s[48:49], 0x4000
	s_mov_b64 s[46:47], 0x8000
	s_mov_b64 s[18:19], -1
	s_andn2_b64 vcc, exec, s[42:43]
	s_cbranch_vccnz .LBB0_875
	s_andn2_b64 vcc, exec, s[0:1]
	s_cbranch_vccnz .LBB0_874
	s_barrier
	s_branch .LBB0_874

.LBB0_1045:
	v_and_b32_e32 v146, 63, v206
	v_lshrrev_b32_e32 v147, 6, v206
	v_and_b32_e32 v148, 15, v146
	v_readfirstlane_b32 s16, v147
	v_lshrrev_b32_e32 v149, 4, v146
	v_xor_b32_e32 v150, 16, v146
	v_xor_b32_e32 v160, 32, v146
	v_lshlrev_b32_e32 v150, 2, v150
	v_lshlrev_b32_e32 v160, 2, v160
	s_lshr_b32 s17, s16, 2
	s_lshl_b32 s17, s17, 6
	s_lshl_b32 s9, s37, 8
	s_add_i32 s9, s9, s17
	s_and_b32 s17, s16, 3
	s_lshl_b32 s17, s17, 5
	s_lshl_b32 s46, s33, 8
	s_add_i32 s17, s17, s46
	v_lshl_add_u32 v161, v149, 3, s17
	v_add_u32_e32 v162, s9, v148
	v_lshlrev_b32_e32 v163, 6, v162
	v_lshl_add_u32 v163, v149, 4, v163
	v_add_u32_e32 v164, 0x2000, v163
	global_load_dwordx4 v[214:217], v163, s[4:5]
	global_load_dwordx4 v[218:221], v163, s[4:5] offset:1024
	global_load_dwordx4 v[222:225], v163, s[4:5] offset:2048
	global_load_dwordx4 v[226:229], v163, s[4:5] offset:3072
	global_load_dwordx4 v[230:233], v164, s[4:5]
	global_load_dwordx4 v[234:237], v164, s[4:5] offset:1024
	global_load_dwordx4 v[238:241], v164, s[4:5] offset:2048
	global_load_dwordx4 v[242:245], v164, s[4:5] offset:3072
	s_waitcnt vmcnt(7)
	v_add_f32_e32 v214, v214, v215
	v_add_f32_e32 v216, v216, v217
	v_add_f32_e32 v214, v214, v216
	s_waitcnt vmcnt(6)
	v_add_f32_e32 v218, v218, v219
	v_add_f32_e32 v220, v220, v221
	v_add_f32_e32 v218, v218, v220
	s_waitcnt vmcnt(5)
	v_add_f32_e32 v222, v222, v223
	v_add_f32_e32 v224, v224, v225
	v_add_f32_e32 v222, v222, v224
	s_waitcnt vmcnt(4)
	v_add_f32_e32 v226, v226, v227
	v_add_f32_e32 v228, v228, v229
	v_add_f32_e32 v226, v226, v228
	s_waitcnt vmcnt(3)
	v_add_f32_e32 v230, v230, v231
	v_add_f32_e32 v232, v232, v233
	v_add_f32_e32 v230, v230, v232
	s_waitcnt vmcnt(2)
	v_add_f32_e32 v234, v234, v235
	v_add_f32_e32 v236, v236, v237
	v_add_f32_e32 v234, v234, v236
	s_waitcnt vmcnt(1)
	v_add_f32_e32 v238, v238, v239
	v_add_f32_e32 v240, v240, v241
	v_add_f32_e32 v238, v238, v240
	s_waitcnt vmcnt(0)
	v_add_f32_e32 v242, v242, v243
	v_add_f32_e32 v244, v244, v245
	v_add_f32_e32 v242, v242, v244
	ds_bpermute_b32 v215, v150, v214
	ds_bpermute_b32 v219, v150, v218
	ds_bpermute_b32 v223, v150, v222
	ds_bpermute_b32 v227, v150, v226
	ds_bpermute_b32 v231, v150, v230
	ds_bpermute_b32 v235, v150, v234
	ds_bpermute_b32 v239, v150, v238
	ds_bpermute_b32 v243, v150, v242
	s_waitcnt lgkmcnt(7)
	v_add_f32_e32 v214, v214, v215
	s_waitcnt lgkmcnt(6)
	v_add_f32_e32 v218, v218, v219
	s_waitcnt lgkmcnt(5)
	v_add_f32_e32 v222, v222, v223
	s_waitcnt lgkmcnt(4)
	v_add_f32_e32 v226, v226, v227
	s_waitcnt lgkmcnt(3)
	v_add_f32_e32 v230, v230, v231
	s_waitcnt lgkmcnt(2)
	v_add_f32_e32 v234, v234, v235
	s_waitcnt lgkmcnt(1)
	v_add_f32_e32 v238, v238, v239
	s_waitcnt lgkmcnt(0)
	v_add_f32_e32 v242, v242, v243
	ds_bpermute_b32 v215, v160, v214
	ds_bpermute_b32 v219, v160, v218
	ds_bpermute_b32 v223, v160, v222
	ds_bpermute_b32 v227, v160, v226
	ds_bpermute_b32 v231, v160, v230
	ds_bpermute_b32 v235, v160, v234
	ds_bpermute_b32 v239, v160, v238
	ds_bpermute_b32 v243, v160, v242
	s_waitcnt lgkmcnt(7)
	v_add_f32_e32 v214, v214, v215
	v_fmamk_f32 v214, v214, 0x3a800000, v208
	s_waitcnt lgkmcnt(6)
	v_add_f32_e32 v218, v218, v219
	v_fmamk_f32 v218, v218, 0x3a800000, v208
	s_waitcnt lgkmcnt(5)
	v_add_f32_e32 v222, v222, v223
	v_fmamk_f32 v222, v222, 0x3a800000, v208
	s_waitcnt lgkmcnt(4)
	v_add_f32_e32 v226, v226, v227
	v_fmamk_f32 v226, v226, 0x3a800000, v208
	s_waitcnt lgkmcnt(3)
	v_add_f32_e32 v230, v230, v231
	v_fmamk_f32 v230, v230, 0x3a800000, v208
	s_waitcnt lgkmcnt(2)
	v_add_f32_e32 v234, v234, v235
	v_fmamk_f32 v234, v234, 0x3a800000, v208
	s_waitcnt lgkmcnt(1)
	v_add_f32_e32 v238, v238, v239
	v_fmamk_f32 v238, v238, 0x3a800000, v208
	s_waitcnt lgkmcnt(0)
	v_add_f32_e32 v242, v242, v243
	v_fmamk_f32 v242, v242, 0x3a800000, v208
	v_rsq_f32_e32 v186, v214
	v_rsq_f32_e32 v188, v218
	v_rsq_f32_e32 v190, v222
	v_rsq_f32_e32 v192, v226
	v_rsq_f32_e32 v194, v230
	v_rsq_f32_e32 v196, v234
	v_rsq_f32_e32 v198, v238
	v_rsq_f32_e32 v200, v242
	s_nop 0
	v_lshlrev_b32_e32 v165, 13, v162
	v_lshl_add_u32 v165, v161, 1, v165
	v_mov_b32_e32 v172, v165
	v_pk_mul_f32 v[132:133], v[132:133], v[186:187] op_sel_hi:[1,0]
	v_pk_mul_f32 v[134:135], v[134:135], v[186:187] op_sel_hi:[1,0]
	v_pk_mul_f32 v[128:129], v[128:129], v[186:187] op_sel_hi:[1,0]
	v_pk_mul_f32 v[130:131], v[130:131], v[186:187] op_sel_hi:[1,0]
	v_max_f32_e32 v132, 0, v132
	v_max_f32_e32 v133, 0, v133
	v_max_f32_e32 v134, 0, v134
	v_max_f32_e32 v135, 0, v135
	v_max_f32_e32 v128, 0, v128
	v_max_f32_e32 v129, 0, v129
	v_max_f32_e32 v130, 0, v130
	v_max_f32_e32 v131, 0, v131
	v_pk_mul_f32 v[132:133], v[132:133], v[132:133]
	v_pk_mul_f32 v[134:135], v[134:135], v[134:135]
	v_pk_mul_f32 v[128:129], v[128:129], v[128:129]
	v_pk_mul_f32 v[130:131], v[130:131], v[130:131]
	v_cvt_pk_bf16_f32 v214, v132, v133
	v_cvt_pk_bf16_f32 v215, v134, v135
	v_cvt_pk_bf16_f32 v216, v128, v129
	v_cvt_pk_bf16_f32 v217, v130, v131
	global_store_dwordx4 v172, v[214:217], s[2:3]
	v_pk_mul_f32 v[124:125], v[124:125], v[186:187] op_sel_hi:[1,0]
	v_pk_mul_f32 v[126:127], v[126:127], v[186:187] op_sel_hi:[1,0]
	v_pk_mul_f32 v[120:121], v[120:121], v[186:187] op_sel_hi:[1,0]
	v_pk_mul_f32 v[122:123], v[122:123], v[186:187] op_sel_hi:[1,0]
	v_max_f32_e32 v124, 0, v124
	v_max_f32_e32 v125, 0, v125
	v_max_f32_e32 v126, 0, v126
	v_max_f32_e32 v127, 0, v127
	v_max_f32_e32 v120, 0, v120
	v_max_f32_e32 v121, 0, v121
	v_max_f32_e32 v122, 0, v122
	v_max_f32_e32 v123, 0, v123
	v_pk_mul_f32 v[124:125], v[124:125], v[124:125]
	v_pk_mul_f32 v[126:127], v[126:127], v[126:127]
	v_pk_mul_f32 v[120:121], v[120:121], v[120:121]
	v_pk_mul_f32 v[122:123], v[122:123], v[122:123]
	v_cvt_pk_bf16_f32 v218, v124, v125
	v_cvt_pk_bf16_f32 v219, v126, v127
	v_cvt_pk_bf16_f32 v220, v120, v121
	v_cvt_pk_bf16_f32 v221, v122, v123
	global_store_dwordx4 v172, v[218:221], s[2:3] offset:256
	v_add_u32_e32 v173, 0x20000, v165
	v_pk_mul_f32 v[116:117], v[116:117], v[188:189] op_sel_hi:[1,0]
	v_pk_mul_f32 v[118:119], v[118:119], v[188:189] op_sel_hi:[1,0]
	v_pk_mul_f32 v[112:113], v[112:113], v[188:189] op_sel_hi:[1,0]
	v_pk_mul_f32 v[114:115], v[114:115], v[188:189] op_sel_hi:[1,0]
	v_max_f32_e32 v116, 0, v116
	v_max_f32_e32 v117, 0, v117
	v_max_f32_e32 v118, 0, v118
	v_max_f32_e32 v119, 0, v119
	v_max_f32_e32 v112, 0, v112
	v_max_f32_e32 v113, 0, v113
	v_max_f32_e32 v114, 0, v114
	v_max_f32_e32 v115, 0, v115
	v_pk_mul_f32 v[116:117], v[116:117], v[116:117]
	v_pk_mul_f32 v[118:119], v[118:119], v[118:119]
	v_pk_mul_f32 v[112:113], v[112:113], v[112:113]
	v_pk_mul_f32 v[114:115], v[114:115], v[114:115]
	v_cvt_pk_bf16_f32 v222, v116, v117
	v_cvt_pk_bf16_f32 v223, v118, v119
	v_cvt_pk_bf16_f32 v224, v112, v113
	v_cvt_pk_bf16_f32 v225, v114, v115
	global_store_dwordx4 v173, v[222:225], s[2:3]
	v_pk_mul_f32 v[108:109], v[108:109], v[188:189] op_sel_hi:[1,0]
	v_pk_mul_f32 v[110:111], v[110:111], v[188:189] op_sel_hi:[1,0]
	v_pk_mul_f32 v[104:105], v[104:105], v[188:189] op_sel_hi:[1,0]
	v_pk_mul_f32 v[106:107], v[106:107], v[188:189] op_sel_hi:[1,0]
	v_max_f32_e32 v108, 0, v108
	v_max_f32_e32 v109, 0, v109
	v_max_f32_e32 v110, 0, v110
	v_max_f32_e32 v111, 0, v111
	v_max_f32_e32 v104, 0, v104
	v_max_f32_e32 v105, 0, v105
	v_max_f32_e32 v106, 0, v106
	v_max_f32_e32 v107, 0, v107
	v_pk_mul_f32 v[108:109], v[108:109], v[108:109]
	v_pk_mul_f32 v[110:111], v[110:111], v[110:111]
	v_pk_mul_f32 v[104:105], v[104:105], v[104:105]
	v_pk_mul_f32 v[106:107], v[106:107], v[106:107]
	v_cvt_pk_bf16_f32 v226, v108, v109
	v_cvt_pk_bf16_f32 v227, v110, v111
	v_cvt_pk_bf16_f32 v228, v104, v105
	v_cvt_pk_bf16_f32 v229, v106, v107
	global_store_dwordx4 v173, v[226:229], s[2:3] offset:256
	v_add_u32_e32 v174, 0x40000, v165
	v_pk_mul_f32 v[100:101], v[100:101], v[190:191] op_sel_hi:[1,0]
	v_pk_mul_f32 v[102:103], v[102:103], v[190:191] op_sel_hi:[1,0]
	v_pk_mul_f32 v[96:97], v[96:97], v[190:191] op_sel_hi:[1,0]
	v_pk_mul_f32 v[98:99], v[98:99], v[190:191] op_sel_hi:[1,0]
	v_max_f32_e32 v100, 0, v100
	v_max_f32_e32 v101, 0, v101
	v_max_f32_e32 v102, 0, v102
	v_max_f32_e32 v103, 0, v103
	v_max_f32_e32 v96, 0, v96
	v_max_f32_e32 v97, 0, v97
	v_max_f32_e32 v98, 0, v98
	v_max_f32_e32 v99, 0, v99
	v_pk_mul_f32 v[100:101], v[100:101], v[100:101]
	v_pk_mul_f32 v[102:103], v[102:103], v[102:103]
	v_pk_mul_f32 v[96:97], v[96:97], v[96:97]
	v_pk_mul_f32 v[98:99], v[98:99], v[98:99]
	v_cvt_pk_bf16_f32 v230, v100, v101
	v_cvt_pk_bf16_f32 v231, v102, v103
	v_cvt_pk_bf16_f32 v232, v96, v97
	v_cvt_pk_bf16_f32 v233, v98, v99
	global_store_dwordx4 v174, v[230:233], s[2:3]
	v_pk_mul_f32 v[92:93], v[92:93], v[190:191] op_sel_hi:[1,0]
	v_pk_mul_f32 v[94:95], v[94:95], v[190:191] op_sel_hi:[1,0]
	v_pk_mul_f32 v[88:89], v[88:89], v[190:191] op_sel_hi:[1,0]
	v_pk_mul_f32 v[90:91], v[90:91], v[190:191] op_sel_hi:[1,0]
	v_max_f32_e32 v92, 0, v92
	v_max_f32_e32 v93, 0, v93
	v_max_f32_e32 v94, 0, v94
	v_max_f32_e32 v95, 0, v95
	v_max_f32_e32 v88, 0, v88
	v_max_f32_e32 v89, 0, v89
	v_max_f32_e32 v90, 0, v90
	v_max_f32_e32 v91, 0, v91
	v_pk_mul_f32 v[92:93], v[92:93], v[92:93]
	v_pk_mul_f32 v[94:95], v[94:95], v[94:95]
	v_pk_mul_f32 v[88:89], v[88:89], v[88:89]
	v_pk_mul_f32 v[90:91], v[90:91], v[90:91]
	v_cvt_pk_bf16_f32 v234, v92, v93
	v_cvt_pk_bf16_f32 v235, v94, v95
	v_cvt_pk_bf16_f32 v236, v88, v89
	v_cvt_pk_bf16_f32 v237, v90, v91
	global_store_dwordx4 v174, v[234:237], s[2:3] offset:256
	v_add_u32_e32 v175, 0x60000, v165
	v_pk_mul_f32 v[84:85], v[84:85], v[192:193] op_sel_hi:[1,0]
	v_pk_mul_f32 v[86:87], v[86:87], v[192:193] op_sel_hi:[1,0]
	v_pk_mul_f32 v[80:81], v[80:81], v[192:193] op_sel_hi:[1,0]
	v_pk_mul_f32 v[82:83], v[82:83], v[192:193] op_sel_hi:[1,0]
	v_max_f32_e32 v84, 0, v84
	v_max_f32_e32 v85, 0, v85
	v_max_f32_e32 v86, 0, v86
	v_max_f32_e32 v87, 0, v87
	v_max_f32_e32 v80, 0, v80
	v_max_f32_e32 v81, 0, v81
	v_max_f32_e32 v82, 0, v82
	v_max_f32_e32 v83, 0, v83
	v_pk_mul_f32 v[84:85], v[84:85], v[84:85]
	v_pk_mul_f32 v[86:87], v[86:87], v[86:87]
	v_pk_mul_f32 v[80:81], v[80:81], v[80:81]
	v_pk_mul_f32 v[82:83], v[82:83], v[82:83]
	v_cvt_pk_bf16_f32 v238, v84, v85
	v_cvt_pk_bf16_f32 v239, v86, v87
	v_cvt_pk_bf16_f32 v240, v80, v81
	v_cvt_pk_bf16_f32 v241, v82, v83
	global_store_dwordx4 v175, v[238:241], s[2:3]
	v_pk_mul_f32 v[76:77], v[76:77], v[192:193] op_sel_hi:[1,0]
	v_pk_mul_f32 v[78:79], v[78:79], v[192:193] op_sel_hi:[1,0]
	v_pk_mul_f32 v[72:73], v[72:73], v[192:193] op_sel_hi:[1,0]
	v_pk_mul_f32 v[74:75], v[74:75], v[192:193] op_sel_hi:[1,0]
	v_max_f32_e32 v76, 0, v76
	v_max_f32_e32 v77, 0, v77
	v_max_f32_e32 v78, 0, v78
	v_max_f32_e32 v79, 0, v79
	v_max_f32_e32 v72, 0, v72
	v_max_f32_e32 v73, 0, v73
	v_max_f32_e32 v74, 0, v74
	v_max_f32_e32 v75, 0, v75
	v_pk_mul_f32 v[76:77], v[76:77], v[76:77]
	v_pk_mul_f32 v[78:79], v[78:79], v[78:79]
	v_pk_mul_f32 v[72:73], v[72:73], v[72:73]
	v_pk_mul_f32 v[74:75], v[74:75], v[74:75]
	v_cvt_pk_bf16_f32 v242, v76, v77
	v_cvt_pk_bf16_f32 v243, v78, v79
	v_cvt_pk_bf16_f32 v244, v72, v73
	v_cvt_pk_bf16_f32 v245, v74, v75
	global_store_dwordx4 v175, v[242:245], s[2:3] offset:256
	v_add_u32_e32 v172, 0x100000, v165
	v_pk_mul_f32 v[68:69], v[68:69], v[194:195] op_sel_hi:[1,0]
	v_pk_mul_f32 v[70:71], v[70:71], v[194:195] op_sel_hi:[1,0]
	v_pk_mul_f32 v[64:65], v[64:65], v[194:195] op_sel_hi:[1,0]
	v_pk_mul_f32 v[66:67], v[66:67], v[194:195] op_sel_hi:[1,0]
	v_max_f32_e32 v68, 0, v68
	v_max_f32_e32 v69, 0, v69
	v_max_f32_e32 v70, 0, v70
	v_max_f32_e32 v71, 0, v71
	v_max_f32_e32 v64, 0, v64
	v_max_f32_e32 v65, 0, v65
	v_max_f32_e32 v66, 0, v66
	v_max_f32_e32 v67, 0, v67
	v_pk_mul_f32 v[68:69], v[68:69], v[68:69]
	v_pk_mul_f32 v[70:71], v[70:71], v[70:71]
	v_pk_mul_f32 v[64:65], v[64:65], v[64:65]
	v_pk_mul_f32 v[66:67], v[66:67], v[66:67]
	v_cvt_pk_bf16_f32 v214, v68, v69
	v_cvt_pk_bf16_f32 v215, v70, v71
	v_cvt_pk_bf16_f32 v216, v64, v65
	v_cvt_pk_bf16_f32 v217, v66, v67
	global_store_dwordx4 v172, v[214:217], s[2:3]
	v_pk_mul_f32 v[60:61], v[60:61], v[194:195] op_sel_hi:[1,0]
	v_pk_mul_f32 v[62:63], v[62:63], v[194:195] op_sel_hi:[1,0]
	v_pk_mul_f32 v[56:57], v[56:57], v[194:195] op_sel_hi:[1,0]
	v_pk_mul_f32 v[58:59], v[58:59], v[194:195] op_sel_hi:[1,0]
	v_max_f32_e32 v60, 0, v60
	v_max_f32_e32 v61, 0, v61
	v_max_f32_e32 v62, 0, v62
	v_max_f32_e32 v63, 0, v63
	v_max_f32_e32 v56, 0, v56
	v_max_f32_e32 v57, 0, v57
	v_max_f32_e32 v58, 0, v58
	v_max_f32_e32 v59, 0, v59
	v_pk_mul_f32 v[60:61], v[60:61], v[60:61]
	v_pk_mul_f32 v[62:63], v[62:63], v[62:63]
	v_pk_mul_f32 v[56:57], v[56:57], v[56:57]
	v_pk_mul_f32 v[58:59], v[58:59], v[58:59]
	v_cvt_pk_bf16_f32 v218, v60, v61
	v_cvt_pk_bf16_f32 v219, v62, v63
	v_cvt_pk_bf16_f32 v220, v56, v57
	v_cvt_pk_bf16_f32 v221, v58, v59
	global_store_dwordx4 v172, v[218:221], s[2:3] offset:256
	v_add_u32_e32 v173, 0x120000, v165
	v_pk_mul_f32 v[52:53], v[52:53], v[196:197] op_sel_hi:[1,0]
	v_pk_mul_f32 v[54:55], v[54:55], v[196:197] op_sel_hi:[1,0]
	v_pk_mul_f32 v[48:49], v[48:49], v[196:197] op_sel_hi:[1,0]
	v_pk_mul_f32 v[50:51], v[50:51], v[196:197] op_sel_hi:[1,0]
	v_max_f32_e32 v52, 0, v52
	v_max_f32_e32 v53, 0, v53
	v_max_f32_e32 v54, 0, v54
	v_max_f32_e32 v55, 0, v55
	v_max_f32_e32 v48, 0, v48
	v_max_f32_e32 v49, 0, v49
	v_max_f32_e32 v50, 0, v50
	v_max_f32_e32 v51, 0, v51
	v_pk_mul_f32 v[52:53], v[52:53], v[52:53]
	v_pk_mul_f32 v[54:55], v[54:55], v[54:55]
	v_pk_mul_f32 v[48:49], v[48:49], v[48:49]
	v_pk_mul_f32 v[50:51], v[50:51], v[50:51]
	v_cvt_pk_bf16_f32 v222, v52, v53
	v_cvt_pk_bf16_f32 v223, v54, v55
	v_cvt_pk_bf16_f32 v224, v48, v49
	v_cvt_pk_bf16_f32 v225, v50, v51
	global_store_dwordx4 v173, v[222:225], s[2:3]
	v_pk_mul_f32 v[44:45], v[44:45], v[196:197] op_sel_hi:[1,0]
	v_pk_mul_f32 v[46:47], v[46:47], v[196:197] op_sel_hi:[1,0]
	v_pk_mul_f32 v[40:41], v[40:41], v[196:197] op_sel_hi:[1,0]
	v_pk_mul_f32 v[42:43], v[42:43], v[196:197] op_sel_hi:[1,0]
	v_max_f32_e32 v44, 0, v44
	v_max_f32_e32 v45, 0, v45
	v_max_f32_e32 v46, 0, v46
	v_max_f32_e32 v47, 0, v47
	v_max_f32_e32 v40, 0, v40
	v_max_f32_e32 v41, 0, v41
	v_max_f32_e32 v42, 0, v42
	v_max_f32_e32 v43, 0, v43
	v_pk_mul_f32 v[44:45], v[44:45], v[44:45]
	v_pk_mul_f32 v[46:47], v[46:47], v[46:47]
	v_pk_mul_f32 v[40:41], v[40:41], v[40:41]
	v_pk_mul_f32 v[42:43], v[42:43], v[42:43]
	v_cvt_pk_bf16_f32 v226, v44, v45
	v_cvt_pk_bf16_f32 v227, v46, v47
	v_cvt_pk_bf16_f32 v228, v40, v41
	v_cvt_pk_bf16_f32 v229, v42, v43
	global_store_dwordx4 v173, v[226:229], s[2:3] offset:256
	v_add_u32_e32 v174, 0x140000, v165
	v_pk_mul_f32 v[36:37], v[36:37], v[198:199] op_sel_hi:[1,0]
	v_pk_mul_f32 v[38:39], v[38:39], v[198:199] op_sel_hi:[1,0]
	v_pk_mul_f32 v[32:33], v[32:33], v[198:199] op_sel_hi:[1,0]
	v_pk_mul_f32 v[34:35], v[34:35], v[198:199] op_sel_hi:[1,0]
	v_max_f32_e32 v36, 0, v36
	v_max_f32_e32 v37, 0, v37
	v_max_f32_e32 v38, 0, v38
	v_max_f32_e32 v39, 0, v39
	v_max_f32_e32 v32, 0, v32
	v_max_f32_e32 v33, 0, v33
	v_max_f32_e32 v34, 0, v34
	v_max_f32_e32 v35, 0, v35
	v_pk_mul_f32 v[36:37], v[36:37], v[36:37]
	v_pk_mul_f32 v[38:39], v[38:39], v[38:39]
	v_pk_mul_f32 v[32:33], v[32:33], v[32:33]
	v_pk_mul_f32 v[34:35], v[34:35], v[34:35]
	v_cvt_pk_bf16_f32 v230, v36, v37
	v_cvt_pk_bf16_f32 v231, v38, v39
	v_cvt_pk_bf16_f32 v232, v32, v33
	v_cvt_pk_bf16_f32 v233, v34, v35
	global_store_dwordx4 v174, v[230:233], s[2:3]
	v_pk_mul_f32 v[28:29], v[28:29], v[198:199] op_sel_hi:[1,0]
	v_pk_mul_f32 v[30:31], v[30:31], v[198:199] op_sel_hi:[1,0]
	v_pk_mul_f32 v[24:25], v[24:25], v[198:199] op_sel_hi:[1,0]
	v_pk_mul_f32 v[26:27], v[26:27], v[198:199] op_sel_hi:[1,0]
	v_max_f32_e32 v28, 0, v28
	v_max_f32_e32 v29, 0, v29
	v_max_f32_e32 v30, 0, v30
	v_max_f32_e32 v31, 0, v31
	v_max_f32_e32 v24, 0, v24
	v_max_f32_e32 v25, 0, v25
	v_max_f32_e32 v26, 0, v26
	v_max_f32_e32 v27, 0, v27
	v_pk_mul_f32 v[28:29], v[28:29], v[28:29]
	v_pk_mul_f32 v[30:31], v[30:31], v[30:31]
	v_pk_mul_f32 v[24:25], v[24:25], v[24:25]
	v_pk_mul_f32 v[26:27], v[26:27], v[26:27]
	v_cvt_pk_bf16_f32 v234, v28, v29
	v_cvt_pk_bf16_f32 v235, v30, v31
	v_cvt_pk_bf16_f32 v236, v24, v25
	v_cvt_pk_bf16_f32 v237, v26, v27
	global_store_dwordx4 v174, v[234:237], s[2:3] offset:256
	v_add_u32_e32 v175, 0x160000, v165
	v_pk_mul_f32 v[20:21], v[20:21], v[200:201] op_sel_hi:[1,0]
	v_pk_mul_f32 v[22:23], v[22:23], v[200:201] op_sel_hi:[1,0]
	v_pk_mul_f32 v[16:17], v[16:17], v[200:201] op_sel_hi:[1,0]
	v_pk_mul_f32 v[18:19], v[18:19], v[200:201] op_sel_hi:[1,0]
	v_max_f32_e32 v20, 0, v20
	v_max_f32_e32 v21, 0, v21
	v_max_f32_e32 v22, 0, v22
	v_max_f32_e32 v23, 0, v23
	v_max_f32_e32 v16, 0, v16
	v_max_f32_e32 v17, 0, v17
	v_max_f32_e32 v18, 0, v18
	v_max_f32_e32 v19, 0, v19
	v_pk_mul_f32 v[20:21], v[20:21], v[20:21]
	v_pk_mul_f32 v[22:23], v[22:23], v[22:23]
	v_pk_mul_f32 v[16:17], v[16:17], v[16:17]
	v_pk_mul_f32 v[18:19], v[18:19], v[18:19]
	v_cvt_pk_bf16_f32 v238, v20, v21
	v_cvt_pk_bf16_f32 v239, v22, v23
	v_cvt_pk_bf16_f32 v240, v16, v17
	v_cvt_pk_bf16_f32 v241, v18, v19
	global_store_dwordx4 v175, v[238:241], s[2:3]
	v_pk_mul_f32 v[12:13], v[12:13], v[200:201] op_sel_hi:[1,0]
	v_pk_mul_f32 v[14:15], v[14:15], v[200:201] op_sel_hi:[1,0]
	v_pk_mul_f32 v[8:9], v[8:9], v[200:201] op_sel_hi:[1,0]
	v_pk_mul_f32 v[10:11], v[10:11], v[200:201] op_sel_hi:[1,0]
	v_max_f32_e32 v12, 0, v12
	v_max_f32_e32 v13, 0, v13
	v_max_f32_e32 v14, 0, v14
	v_max_f32_e32 v15, 0, v15
	v_max_f32_e32 v8, 0, v8
	v_max_f32_e32 v9, 0, v9
	v_max_f32_e32 v10, 0, v10
	v_max_f32_e32 v11, 0, v11
	v_pk_mul_f32 v[12:13], v[12:13], v[12:13]
	v_pk_mul_f32 v[14:15], v[14:15], v[14:15]
	v_pk_mul_f32 v[8:9], v[8:9], v[8:9]
	v_pk_mul_f32 v[10:11], v[10:11], v[10:11]
	v_cvt_pk_bf16_f32 v242, v12, v13
	v_cvt_pk_bf16_f32 v243, v14, v15
	v_cvt_pk_bf16_f32 v244, v8, v9
	v_cvt_pk_bf16_f32 v245, v10, v11
	global_store_dwordx4 v175, v[242:245], s[2:3] offset:256
	s_mov_b64 s[16:17], -1
	s_mov_b64 s[48:49], 0x4000
	s_mov_b64 s[46:47], 0x8000
	s_andn2_b64 vcc, exec, s[40:41]
	s_cbranch_vccnz .LBB0_1034
	s_andn2_b64 vcc, exec, s[0:1]
	s_cbranch_vccnz .LBB0_1033
	s_barrier
	s_branch .LBB0_1033
